# sc1 write-through on all GEMM epilogue dwordx4 stores (theory: cheaper L2 writeback at grid barriers)
# baseline (speedup 1.0000x reference)
; __device__ __forceinline__ unsigned cvt_pk_bf16(float lo, float hi) { unsigned r; asm volatile("v_cvt_pk_bf16_f32 %0, %1, %2" : "=v"(r) : "v"(lo), "v"(hi)); return r; }
;     __device__ __forceinline__ void operator()(const f32x4 (&acc)[2][2][4][2], const Unit& u, int wr, int wc, int fr, int fq) const {
;     ...
;         for (int ai = 0; ai < 2; ++ai)
; #pragma unroll
;             for (int m = 0; m < 4; ++m) { const int row = row0 + ai * HALF + m * 16; const float r = rr[ai][m]; bf16_t* rowp = O + (size_t)row * IN_W + col0;
;                 if (sig) {
;                     const float c1 = r * -1.4426950408889634f; f32x4 ra[2], gb[2];
; #pragma unroll
;                     for (int n = 0; n < 2; ++n)
; #pragma unroll
;                         for (int j = 0; j < 4; ++j) { const float da = 1.0f + __builtin_amdgcn_exp2f(acc[ai][0][m][n][j] * c1), db = fminf(1.0f + __builtin_amdgcn_exp2f(acc[ai][1][m][n][j] * c1), 1e30f);
;                             ra[n][j] = db * __builtin_amdgcn_rcpf(da); gb[n][j] = __builtin_amdgcn_rcpf(db); }
;                     u32x4 w; w.x = cvt_pk_bf16(ra[0][0], ra[0][1]); w.y = cvt_pk_bf16(ra[0][2], ra[0][3]); w.z = cvt_pk_bf16(ra[1][0], ra[1][1]); w.w = cvt_pk_bf16(ra[1][2], ra[1][3]);
;                     *(u32x4*)rowp = w;
;                     w.x = cvt_pk_bf16(gb[0][0], gb[0][1]); w.y = cvt_pk_bf16(gb[0][2], gb[0][3]); w.z = cvt_pk_bf16(gb[1][0], gb[1][1]); w.w = cvt_pk_bf16(gb[1][2], gb[1][3]);
;                     *(u32x4*)(rowp + HALF) = w;
;                 } else {
; #pragma unroll
;                 for (int bj = 0; bj < 2; ++bj) { const f32x4 v0 = acc[ai][bj][m][0] * r, v1 = acc[ai][bj][m][1] * r;
;                     u32x4 w; w.x = cvt_pk_bf16(v0[0], v0[1]); w.y = cvt_pk_bf16(v0[2], v0[3]); w.z = cvt_pk_bf16(v1[0], v1[1]); w.w = cvt_pk_bf16(v1[2], v1[3]);
;                     *(u32x4*)(rowp + bj * HALF) = w; } } }
.LBB0_172:
	v_mov_b64_e32 v[130:131], s[10:11]
	v_mad_u64_u32 v[130:131], s[26:27], v146, s83, v[130:131]
	v_mov_b32_e32 v132, v131
	v_lshl_or_b32 v152, s44, 8, v163
	v_mad_u64_u32 v[132:133], s[26:27], v147, s83, v[132:133]
	s_cmp_lt_i32 s44, 14
	v_ashrrev_i32_e32 v153, 31, v152
	v_mov_b32_e32 v131, v132
	s_cselect_b64 s[16:17], -1, 0
	s_cmp_gt_i32 s44, 13
	v_lshl_add_u64 v[158:159], v[152:153], 1, v[130:131]
	s_mov_b64 s[26:27], -1
	s_cbranch_scc1 .LBB0_174
	s_waitcnt lgkmcnt(0)
	v_pk_mul_f32 v[132:133], v[128:129], v[156:157] op_sel_hi:[1,0]
	v_pk_mul_f32 v[130:131], v[126:127], v[156:157] op_sel_hi:[1,0]
	v_pk_mul_f32 v[166:167], v[120:121], v[156:157] op_sel_hi:[1,0]
	v_pk_mul_f32 v[180:181], v[118:119], v[156:157] op_sel_hi:[1,0]
	v_cvt_pk_bf16_f32 v130, v130, v131
	v_cvt_pk_bf16_f32 v131, v132, v133
	s_mov_b64 s[26:27], 0
	v_cvt_pk_bf16_f32 v132, v180, v181
	v_cvt_pk_bf16_f32 v133, v166, v167
	global_store_dwordx4 v[158:159], v[130:133], off sc1
	v_pk_mul_f32 v[166:167], v[116:117], v[156:157] op_sel_hi:[1,0]
	v_pk_mul_f32 v[180:181], v[114:115], v[156:157] op_sel_hi:[1,0]
	v_pk_mul_f32 v[132:133], v[124:125], v[156:157] op_sel_hi:[1,0]
	v_pk_mul_f32 v[130:131], v[122:123], v[156:157] op_sel_hi:[1,0]
	s_nop 0
	v_cvt_pk_bf16_f32 v130, v130, v131
	v_cvt_pk_bf16_f32 v131, v132, v133
	v_cvt_pk_bf16_f32 v132, v180, v181
	v_cvt_pk_bf16_f32 v133, v166, v167
.LBB0_174:
	s_andn2_b64 vcc, exec, s[26:27]
	s_cbranch_vccnz .LBB0_176
	s_waitcnt lgkmcnt(0)
	v_mul_f32_e32 v130, 0xbfb8aa3b, v156
	v_mul_f32_e32 v118, v118, v130
	v_exp_f32_e32 v118, v118
	v_mul_f32_e32 v114, v114, v130
	v_exp_f32_e32 v114, v114
	v_mul_f32_e32 v119, v119, v130
	v_add_f32_e32 v118, 1.0, v118
	v_rcp_f32_e32 v118, v118
	v_exp_f32_e32 v119, v119
	v_add_f32_e32 v114, 1.0, v114
	v_mul_f32_e32 v115, v115, v130
	v_min_f32_e32 v114, 0x7149f2ca, v114
	v_exp_f32_e32 v115, v115
	v_mul_f32_e32 v118, v118, v114
	v_rcp_f32_e32 v132, v114
	v_add_f32_e32 v114, 1.0, v119
	v_mul_f32_e32 v119, v120, v130
	v_rcp_f32_e32 v114, v114
	v_exp_f32_e32 v119, v119
	v_mul_f32_e32 v116, v116, v130
	v_add_f32_e32 v115, 1.0, v115
	v_exp_f32_e32 v116, v116
	v_min_f32_e32 v115, 0x7149f2ca, v115
	v_mul_f32_e32 v120, v114, v115
	v_add_f32_e32 v114, 1.0, v119
	v_rcp_f32_e32 v114, v114
	v_rcp_f32_e32 v133, v115
	v_add_f32_e32 v115, 1.0, v116
	v_mul_f32_e32 v116, v121, v130
	v_mul_f32_e32 v126, v126, v130
	v_mul_f32_e32 v127, v127, v130
	v_mul_f32_e32 v128, v128, v130
	v_mul_f32_e32 v129, v129, v130
	v_exp_f32_e32 v116, v116
	v_exp_f32_e32 v126, v126
	v_exp_f32_e32 v127, v127
	v_exp_f32_e32 v128, v128
	v_exp_f32_e32 v129, v129
	v_min_f32_e32 v115, 0x7149f2ca, v115
	v_mul_f32_e32 v119, v114, v115
	v_mul_f32_e32 v114, v117, v130
	v_mul_f32_e32 v122, v122, v130
	v_mul_f32_e32 v123, v123, v130
	v_mul_f32_e32 v124, v124, v130
	v_mul_f32_e32 v125, v125, v130
	v_exp_f32_e32 v114, v114
	v_exp_f32_e32 v122, v122
	v_exp_f32_e32 v123, v123
	v_exp_f32_e32 v124, v124
	v_exp_f32_e32 v125, v125
	v_add_f32_e32 v116, 1.0, v116
	v_add_f32_e32 v126, 1.0, v126
	v_add_f32_e32 v127, 1.0, v127
	v_add_f32_e32 v128, 1.0, v128
	v_add_f32_e32 v129, 1.0, v129
	v_rcp_f32_e32 v116, v116
	v_rcp_f32_e32 v126, v126
	v_rcp_f32_e32 v127, v127
	v_rcp_f32_e32 v128, v128
	v_rcp_f32_e32 v129, v129
	v_add_f32_e32 v114, 1.0, v114
	v_add_f32_e32 v122, 1.0, v122
	v_add_f32_e32 v123, 1.0, v123
	v_add_f32_e32 v124, 1.0, v124
	v_add_f32_e32 v125, 1.0, v125
	v_min_f32_e32 v114, 0x7149f2ca, v114
	v_min_f32_e32 v122, 0x7149f2ca, v122
	v_min_f32_e32 v123, 0x7149f2ca, v123
	v_min_f32_e32 v124, 0x7149f2ca, v124
	v_min_f32_e32 v125, 0x7149f2ca, v125
	v_mul_f32_e32 v117, v116, v114
	v_mul_f32_e32 v126, v126, v122
	v_rcp_f32_e32 v122, v122
	v_mul_f32_e32 v127, v127, v123
	v_rcp_f32_e32 v123, v123
	v_mul_f32_e32 v128, v128, v124
	v_rcp_f32_e32 v124, v124
	v_mul_f32_e32 v129, v129, v125
	v_rcp_f32_e32 v125, v125
	v_rcp_f32_e32 v121, v115
	v_rcp_f32_e32 v147, v114
	v_cvt_pk_bf16_f32 v114, v126, v127
	v_cvt_pk_bf16_f32 v115, v128, v129
	v_cvt_pk_bf16_f32 v116, v118, v120
	v_cvt_pk_bf16_f32 v117, v119, v117
	global_store_dwordx4 v[158:159], v[114:117], off sc1
	v_cvt_pk_bf16_f32 v130, v122, v123
	v_cvt_pk_bf16_f32 v131, v124, v125
	v_cvt_pk_bf16_f32 v132, v132, v133
	v_cvt_pk_bf16_f32 v133, v121, v147
.LBB0_176:
	s_nop 1
	v_or_b32_e32 v116, 16, v146
	v_mov_b64_e32 v[114:115], s[10:11]
	v_mad_i64_i32 v[114:115], s[26:27], v116, s83, v[114:115]
	v_lshl_add_u64 v[118:119], v[152:153], 1, v[114:115]
	v_cndmask_b32_e64 v114, 0, 1, s[16:17]
	v_cmp_ne_u32_e64 s[40:41], 1, v114
	s_andn2_b64 vcc, exec, s[16:17]
	s_mov_b64 s[16:17], -1
	global_store_dwordx4 v[158:159], v[130:133], off offset:256 sc1
	s_cbranch_vccnz .LBB0_178
	s_waitcnt lgkmcnt(0)
	v_pk_mul_f32 v[116:117], v[112:113], v[156:157] op_sel:[0,1]
	v_pk_mul_f32 v[114:115], v[110:111], v[156:157] op_sel:[0,1]
	v_pk_mul_f32 v[120:121], v[104:105], v[156:157] op_sel:[0,1]
	v_pk_mul_f32 v[122:123], v[102:103], v[156:157] op_sel:[0,1]
	v_cvt_pk_bf16_f32 v114, v114, v115
	v_cvt_pk_bf16_f32 v115, v116, v117
	s_mov_b64 s[16:17], 0
	v_cvt_pk_bf16_f32 v116, v122, v123
	v_cvt_pk_bf16_f32 v117, v120, v121
	global_store_dwordx4 v[118:119], v[114:117], off sc1
	v_pk_mul_f32 v[120:121], v[100:101], v[156:157] op_sel:[0,1]
	v_pk_mul_f32 v[122:123], v[98:99], v[156:157] op_sel:[0,1]
	v_pk_mul_f32 v[116:117], v[108:109], v[156:157] op_sel:[0,1]
	v_pk_mul_f32 v[114:115], v[106:107], v[156:157] op_sel:[0,1]
	s_nop 0
	v_cvt_pk_bf16_f32 v114, v114, v115
	v_cvt_pk_bf16_f32 v115, v116, v117
	v_cvt_pk_bf16_f32 v116, v122, v123
	v_cvt_pk_bf16_f32 v117, v120, v121
; __device__ __forceinline__ unsigned cvt_pk_bf16(float lo, float hi) { unsigned r; asm volatile("v_cvt_pk_bf16_f32 %0, %1, %2" : "=v"(r) : "v"(lo), "v"(hi)); return r; }
;     __device__ __forceinline__ void operator()(const f32x4 (&acc)[2][2][4][2], const Unit& u, int wr, int wc, int fr, int fq) const {
;     ...
;         for (int ai = 0; ai < 2; ++ai)
; #pragma unroll
;             for (int m = 0; m < 4; ++m) { const int row = row0 + ai * HALF + m * 16; const float r = rr[ai][m]; bf16_t* rowp = O + (size_t)row * IN_W + col0;
;                 if (sig) {
;                     const float c1 = r * -1.4426950408889634f; f32x4 ra[2], gb[2];
; #pragma unroll
;                     for (int n = 0; n < 2; ++n)
; #pragma unroll
;                         for (int j = 0; j < 4; ++j) { const float da = 1.0f + __builtin_amdgcn_exp2f(acc[ai][0][m][n][j] * c1), db = fminf(1.0f + __builtin_amdgcn_exp2f(acc[ai][1][m][n][j] * c1), 1e30f);
;                             ra[n][j] = db * __builtin_amdgcn_rcpf(da); gb[n][j] = __builtin_amdgcn_rcpf(db); }
;                     u32x4 w; w.x = cvt_pk_bf16(ra[0][0], ra[0][1]); w.y = cvt_pk_bf16(ra[0][2], ra[0][3]); w.z = cvt_pk_bf16(ra[1][0], ra[1][1]); w.w = cvt_pk_bf16(ra[1][2], ra[1][3]);
;                     *(u32x4*)rowp = w;
;                     w.x = cvt_pk_bf16(gb[0][0], gb[0][1]); w.y = cvt_pk_bf16(gb[0][2], gb[0][3]); w.z = cvt_pk_bf16(gb[1][0], gb[1][1]); w.w = cvt_pk_bf16(gb[1][2], gb[1][3]);
;                     *(u32x4*)(rowp + HALF) = w;
;                 } else {
; #pragma unroll
;                 for (int bj = 0; bj < 2; ++bj) { const f32x4 v0 = acc[ai][bj][m][0] * r, v1 = acc[ai][bj][m][1] * r;
;                     u32x4 w; w.x = cvt_pk_bf16(v0[0], v0[1]); w.y = cvt_pk_bf16(v0[2], v0[3]); w.z = cvt_pk_bf16(v1[0], v1[1]); w.w = cvt_pk_bf16(v1[2], v1[3]);
;                     *(u32x4*)(rowp + bj * HALF) = w; } } }
.LBB0_178:
	s_andn2_b64 vcc, exec, s[16:17]
	s_cbranch_vccnz .LBB0_180
	s_waitcnt lgkmcnt(0)
	v_mul_f32_e32 v114, 0xbfb8aa3b, v157
	v_mul_f32_e32 v102, v102, v114
	v_exp_f32_e32 v102, v102
	v_mul_f32_e32 v98, v98, v114
	v_exp_f32_e32 v98, v98
	v_mul_f32_e32 v103, v103, v114
	v_add_f32_e32 v102, 1.0, v102
	v_rcp_f32_e32 v102, v102
	v_exp_f32_e32 v103, v103
	v_add_f32_e32 v98, 1.0, v98
	v_mul_f32_e32 v99, v99, v114
	v_min_f32_e32 v98, 0x7149f2ca, v98
	v_exp_f32_e32 v99, v99
	v_mul_f32_e32 v102, v102, v98
	v_rcp_f32_e32 v116, v98
	v_add_f32_e32 v98, 1.0, v103
	v_mul_f32_e32 v103, v104, v114
	v_rcp_f32_e32 v98, v98
	v_exp_f32_e32 v103, v103
	v_mul_f32_e32 v100, v100, v114
	v_add_f32_e32 v99, 1.0, v99
	v_exp_f32_e32 v100, v100
	v_min_f32_e32 v99, 0x7149f2ca, v99
	v_mul_f32_e32 v104, v98, v99
	v_add_f32_e32 v98, 1.0, v103
	v_rcp_f32_e32 v98, v98
	v_rcp_f32_e32 v117, v99
	v_add_f32_e32 v99, 1.0, v100
	v_mul_f32_e32 v100, v105, v114
	v_mul_f32_e32 v110, v110, v114
	v_mul_f32_e32 v111, v111, v114
	v_mul_f32_e32 v112, v112, v114
	v_mul_f32_e32 v113, v113, v114
	v_exp_f32_e32 v100, v100
	v_exp_f32_e32 v110, v110
	v_exp_f32_e32 v111, v111
	v_exp_f32_e32 v112, v112
	v_exp_f32_e32 v113, v113
	v_min_f32_e32 v99, 0x7149f2ca, v99
	v_mul_f32_e32 v103, v98, v99
	v_mul_f32_e32 v98, v101, v114
	v_mul_f32_e32 v106, v106, v114
	v_mul_f32_e32 v107, v107, v114
	v_mul_f32_e32 v108, v108, v114
	v_mul_f32_e32 v109, v109, v114
	v_exp_f32_e32 v98, v98
	v_exp_f32_e32 v106, v106
	v_exp_f32_e32 v107, v107
	v_exp_f32_e32 v108, v108
	v_exp_f32_e32 v109, v109
	v_add_f32_e32 v100, 1.0, v100
	v_add_f32_e32 v110, 1.0, v110
	v_add_f32_e32 v111, 1.0, v111
	v_add_f32_e32 v112, 1.0, v112
	v_add_f32_e32 v113, 1.0, v113
	v_rcp_f32_e32 v100, v100
	v_rcp_f32_e32 v110, v110
	v_rcp_f32_e32 v111, v111
	v_rcp_f32_e32 v112, v112
	v_rcp_f32_e32 v113, v113
	v_add_f32_e32 v98, 1.0, v98
	v_add_f32_e32 v106, 1.0, v106
	v_add_f32_e32 v107, 1.0, v107
	v_add_f32_e32 v108, 1.0, v108
	v_add_f32_e32 v109, 1.0, v109
	v_min_f32_e32 v98, 0x7149f2ca, v98
	v_min_f32_e32 v106, 0x7149f2ca, v106
	v_min_f32_e32 v107, 0x7149f2ca, v107
	v_min_f32_e32 v108, 0x7149f2ca, v108
	v_min_f32_e32 v109, 0x7149f2ca, v109
	v_mul_f32_e32 v101, v100, v98
	v_mul_f32_e32 v110, v110, v106
	v_rcp_f32_e32 v106, v106
	v_mul_f32_e32 v111, v111, v107
	v_rcp_f32_e32 v107, v107
	v_mul_f32_e32 v112, v112, v108
	v_rcp_f32_e32 v108, v108
	v_mul_f32_e32 v113, v113, v109
	v_rcp_f32_e32 v109, v109
	v_rcp_f32_e32 v105, v99
	v_rcp_f32_e32 v120, v98
	v_cvt_pk_bf16_f32 v98, v110, v111
	v_cvt_pk_bf16_f32 v99, v112, v113
	v_cvt_pk_bf16_f32 v100, v102, v104
	v_cvt_pk_bf16_f32 v101, v103, v101
	global_store_dwordx4 v[118:119], v[98:101], off sc1
	v_cvt_pk_bf16_f32 v114, v106, v107
	v_cvt_pk_bf16_f32 v115, v108, v109
	v_cvt_pk_bf16_f32 v116, v116, v117
	v_cvt_pk_bf16_f32 v117, v105, v120
.LBB0_180:
	s_nop 1
	v_or_b32_e32 v100, 32, v146
	v_mov_b64_e32 v[98:99], s[10:11]
	v_mad_i64_i32 v[98:99], s[16:17], v100, s83, v[98:99]
	v_lshl_add_u64 v[102:103], v[152:153], 1, v[98:99]
	s_and_b64 vcc, exec, s[40:41]
	s_mov_b64 s[16:17], -1
	global_store_dwordx4 v[118:119], v[114:117], off offset:256 sc1
	s_cbranch_vccnz .LBB0_182
	s_waitcnt lgkmcnt(0)
	v_pk_mul_f32 v[100:101], v[96:97], v[154:155] op_sel_hi:[1,0]
	v_pk_mul_f32 v[98:99], v[94:95], v[154:155] op_sel_hi:[1,0]
	v_pk_mul_f32 v[104:105], v[88:89], v[154:155] op_sel_hi:[1,0]
	v_pk_mul_f32 v[106:107], v[86:87], v[154:155] op_sel_hi:[1,0]
	v_cvt_pk_bf16_f32 v98, v98, v99
	v_cvt_pk_bf16_f32 v99, v100, v101
	s_mov_b64 s[16:17], 0
	v_cvt_pk_bf16_f32 v100, v106, v107
	v_cvt_pk_bf16_f32 v101, v104, v105
	global_store_dwordx4 v[102:103], v[98:101], off sc1
	v_pk_mul_f32 v[104:105], v[84:85], v[154:155] op_sel_hi:[1,0]
	v_pk_mul_f32 v[106:107], v[82:83], v[154:155] op_sel_hi:[1,0]
	v_pk_mul_f32 v[100:101], v[92:93], v[154:155] op_sel_hi:[1,0]
	v_pk_mul_f32 v[98:99], v[90:91], v[154:155] op_sel_hi:[1,0]
	s_nop 0
	v_cvt_pk_bf16_f32 v98, v98, v99
	v_cvt_pk_bf16_f32 v99, v100, v101
	v_cvt_pk_bf16_f32 v100, v106, v107
	v_cvt_pk_bf16_f32 v101, v104, v105
.LBB0_182:
	s_andn2_b64 vcc, exec, s[16:17]
	s_cbranch_vccnz .LBB0_184
	s_waitcnt lgkmcnt(0)
	v_mul_f32_e32 v98, 0xbfb8aa3b, v154
	v_mul_f32_e32 v86, v86, v98
	v_exp_f32_e32 v86, v86
	v_mul_f32_e32 v82, v82, v98
	v_exp_f32_e32 v82, v82
	v_mul_f32_e32 v87, v87, v98
	v_add_f32_e32 v86, 1.0, v86
	v_rcp_f32_e32 v86, v86
	v_exp_f32_e32 v87, v87
	v_add_f32_e32 v82, 1.0, v82
	v_mul_f32_e32 v83, v83, v98
	v_min_f32_e32 v82, 0x7149f2ca, v82
	v_exp_f32_e32 v83, v83
	v_mul_f32_e32 v86, v86, v82
	v_rcp_f32_e32 v100, v82
	v_add_f32_e32 v82, 1.0, v87
	v_mul_f32_e32 v87, v88, v98
	v_rcp_f32_e32 v82, v82
	v_exp_f32_e32 v87, v87
	v_mul_f32_e32 v84, v84, v98
	v_add_f32_e32 v83, 1.0, v83
	v_exp_f32_e32 v84, v84
	v_min_f32_e32 v83, 0x7149f2ca, v83
	v_mul_f32_e32 v88, v82, v83
	v_add_f32_e32 v82, 1.0, v87
	v_rcp_f32_e32 v82, v82
	v_rcp_f32_e32 v101, v83
	v_add_f32_e32 v83, 1.0, v84
	v_mul_f32_e32 v84, v89, v98
	v_mul_f32_e32 v94, v94, v98
	v_mul_f32_e32 v95, v95, v98
	v_mul_f32_e32 v96, v96, v98
	v_mul_f32_e32 v97, v97, v98
	v_exp_f32_e32 v84, v84
	v_exp_f32_e32 v94, v94
	v_exp_f32_e32 v95, v95
	v_exp_f32_e32 v96, v96
	v_exp_f32_e32 v97, v97
	v_min_f32_e32 v83, 0x7149f2ca, v83
	v_mul_f32_e32 v87, v82, v83
	v_mul_f32_e32 v82, v85, v98
	v_mul_f32_e32 v90, v90, v98
	v_mul_f32_e32 v91, v91, v98
	v_mul_f32_e32 v92, v92, v98
	v_mul_f32_e32 v93, v93, v98
	v_exp_f32_e32 v82, v82
	v_exp_f32_e32 v90, v90
	v_exp_f32_e32 v91, v91
	v_exp_f32_e32 v92, v92
	v_exp_f32_e32 v93, v93
	v_add_f32_e32 v84, 1.0, v84
	v_add_f32_e32 v94, 1.0, v94
	v_add_f32_e32 v95, 1.0, v95
	v_add_f32_e32 v96, 1.0, v96
	v_add_f32_e32 v97, 1.0, v97
	v_rcp_f32_e32 v84, v84
	v_rcp_f32_e32 v94, v94
	v_rcp_f32_e32 v95, v95
	v_rcp_f32_e32 v96, v96
	v_rcp_f32_e32 v97, v97
	v_add_f32_e32 v82, 1.0, v82
	v_add_f32_e32 v90, 1.0, v90
	v_add_f32_e32 v91, 1.0, v91
	v_add_f32_e32 v92, 1.0, v92
	v_add_f32_e32 v93, 1.0, v93
	v_min_f32_e32 v82, 0x7149f2ca, v82
	v_min_f32_e32 v90, 0x7149f2ca, v90
	v_min_f32_e32 v91, 0x7149f2ca, v91
	v_min_f32_e32 v92, 0x7149f2ca, v92
	v_min_f32_e32 v93, 0x7149f2ca, v93
	v_mul_f32_e32 v85, v84, v82
	v_mul_f32_e32 v94, v94, v90
	v_rcp_f32_e32 v90, v90
	v_mul_f32_e32 v95, v95, v91
	v_rcp_f32_e32 v91, v91
	v_mul_f32_e32 v96, v96, v92
	v_rcp_f32_e32 v92, v92
	v_mul_f32_e32 v97, v97, v93
	v_rcp_f32_e32 v93, v93
	v_rcp_f32_e32 v89, v83
	v_rcp_f32_e32 v104, v82
	v_cvt_pk_bf16_f32 v82, v94, v95
	v_cvt_pk_bf16_f32 v83, v96, v97
	v_cvt_pk_bf16_f32 v84, v86, v88
	v_cvt_pk_bf16_f32 v85, v87, v85
	global_store_dwordx4 v[102:103], v[82:85], off sc1
	v_cvt_pk_bf16_f32 v98, v90, v91
	v_cvt_pk_bf16_f32 v99, v92, v93
	v_cvt_pk_bf16_f32 v100, v100, v101
	v_cvt_pk_bf16_f32 v101, v89, v104
; __device__ __forceinline__ unsigned cvt_pk_bf16(float lo, float hi) { unsigned r; asm volatile("v_cvt_pk_bf16_f32 %0, %1, %2" : "=v"(r) : "v"(lo), "v"(hi)); return r; }
;     __device__ __forceinline__ void operator()(const f32x4 (&acc)[2][2][4][2], const Unit& u, int wr, int wc, int fr, int fq) const {
;     ...
;         for (int ai = 0; ai < 2; ++ai)
; #pragma unroll
;             for (int m = 0; m < 4; ++m) { const int row = row0 + ai * HALF + m * 16; const float r = rr[ai][m]; bf16_t* rowp = O + (size_t)row * IN_W + col0;
;                 if (sig) {
;                     const float c1 = r * -1.4426950408889634f; f32x4 ra[2], gb[2];
; #pragma unroll
;                     for (int n = 0; n < 2; ++n)
; #pragma unroll
;                         for (int j = 0; j < 4; ++j) { const float da = 1.0f + __builtin_amdgcn_exp2f(acc[ai][0][m][n][j] * c1), db = fminf(1.0f + __builtin_amdgcn_exp2f(acc[ai][1][m][n][j] * c1), 1e30f);
;                             ra[n][j] = db * __builtin_amdgcn_rcpf(da); gb[n][j] = __builtin_amdgcn_rcpf(db); }
;                     u32x4 w; w.x = cvt_pk_bf16(ra[0][0], ra[0][1]); w.y = cvt_pk_bf16(ra[0][2], ra[0][3]); w.z = cvt_pk_bf16(ra[1][0], ra[1][1]); w.w = cvt_pk_bf16(ra[1][2], ra[1][3]);
;                     *(u32x4*)rowp = w;
;                     w.x = cvt_pk_bf16(gb[0][0], gb[0][1]); w.y = cvt_pk_bf16(gb[0][2], gb[0][3]); w.z = cvt_pk_bf16(gb[1][0], gb[1][1]); w.w = cvt_pk_bf16(gb[1][2], gb[1][3]);
;                     *(u32x4*)(rowp + HALF) = w;
;                 } else {
; #pragma unroll
;                 for (int bj = 0; bj < 2; ++bj) { const f32x4 v0 = acc[ai][bj][m][0] * r, v1 = acc[ai][bj][m][1] * r;
;                     u32x4 w; w.x = cvt_pk_bf16(v0[0], v0[1]); w.y = cvt_pk_bf16(v0[2], v0[3]); w.z = cvt_pk_bf16(v1[0], v1[1]); w.w = cvt_pk_bf16(v1[2], v1[3]);
;                     *(u32x4*)(rowp + bj * HALF) = w; } } }
.LBB0_184:
	s_nop 1
	v_or_b32_e32 v84, 48, v146
	v_mov_b64_e32 v[82:83], s[10:11]
	v_mad_i64_i32 v[82:83], s[16:17], v84, s83, v[82:83]
	v_lshl_add_u64 v[86:87], v[152:153], 1, v[82:83]
	s_and_b64 vcc, exec, s[40:41]
	s_mov_b64 s[16:17], -1
	global_store_dwordx4 v[102:103], v[98:101], off offset:256 sc1
	s_cbranch_vccnz .LBB0_186
	s_waitcnt lgkmcnt(0)
	v_pk_mul_f32 v[84:85], v[80:81], v[154:155] op_sel:[0,1]
	v_pk_mul_f32 v[82:83], v[78:79], v[154:155] op_sel:[0,1]
	v_pk_mul_f32 v[88:89], v[72:73], v[154:155] op_sel:[0,1]
	v_pk_mul_f32 v[90:91], v[70:71], v[154:155] op_sel:[0,1]
	v_cvt_pk_bf16_f32 v82, v82, v83
	v_cvt_pk_bf16_f32 v83, v84, v85
	s_mov_b64 s[16:17], 0
	v_cvt_pk_bf16_f32 v84, v90, v91
	v_cvt_pk_bf16_f32 v85, v88, v89
	global_store_dwordx4 v[86:87], v[82:85], off sc1
	v_pk_mul_f32 v[88:89], v[68:69], v[154:155] op_sel:[0,1]
	v_pk_mul_f32 v[90:91], v[66:67], v[154:155] op_sel:[0,1]
	v_pk_mul_f32 v[84:85], v[76:77], v[154:155] op_sel:[0,1]
	v_pk_mul_f32 v[82:83], v[74:75], v[154:155] op_sel:[0,1]
	s_nop 0
	v_cvt_pk_bf16_f32 v82, v82, v83
	v_cvt_pk_bf16_f32 v83, v84, v85
	v_cvt_pk_bf16_f32 v84, v90, v91
	v_cvt_pk_bf16_f32 v85, v88, v89
.LBB0_186:
	s_andn2_b64 vcc, exec, s[16:17]
	s_cbranch_vccnz .LBB0_188
	s_waitcnt lgkmcnt(0)
	v_mul_f32_e32 v82, 0xbfb8aa3b, v155
	v_mul_f32_e32 v70, v70, v82
	v_exp_f32_e32 v70, v70
	v_mul_f32_e32 v66, v66, v82
	v_exp_f32_e32 v66, v66
	v_mul_f32_e32 v71, v71, v82
	v_add_f32_e32 v70, 1.0, v70
	v_rcp_f32_e32 v70, v70
	v_exp_f32_e32 v71, v71
	v_add_f32_e32 v66, 1.0, v66
	v_mul_f32_e32 v67, v67, v82
	v_min_f32_e32 v66, 0x7149f2ca, v66
	v_exp_f32_e32 v67, v67
	v_mul_f32_e32 v70, v70, v66
	v_rcp_f32_e32 v84, v66
	v_add_f32_e32 v66, 1.0, v71
	v_mul_f32_e32 v71, v72, v82
	v_rcp_f32_e32 v66, v66
	v_exp_f32_e32 v71, v71
	v_mul_f32_e32 v68, v68, v82
	v_add_f32_e32 v67, 1.0, v67
	v_exp_f32_e32 v68, v68
	v_min_f32_e32 v67, 0x7149f2ca, v67
	v_mul_f32_e32 v72, v66, v67
	v_add_f32_e32 v66, 1.0, v71
	v_rcp_f32_e32 v66, v66
	v_rcp_f32_e32 v85, v67
	v_add_f32_e32 v67, 1.0, v68
	v_mul_f32_e32 v68, v73, v82
	v_mul_f32_e32 v78, v78, v82
	v_mul_f32_e32 v79, v79, v82
	v_mul_f32_e32 v80, v80, v82
	v_mul_f32_e32 v81, v81, v82
	v_exp_f32_e32 v68, v68
	v_exp_f32_e32 v78, v78
	v_exp_f32_e32 v79, v79
	v_exp_f32_e32 v80, v80
	v_exp_f32_e32 v81, v81
	v_min_f32_e32 v67, 0x7149f2ca, v67
	v_mul_f32_e32 v71, v66, v67
	v_mul_f32_e32 v66, v69, v82
	v_mul_f32_e32 v74, v74, v82
	v_mul_f32_e32 v75, v75, v82
	v_mul_f32_e32 v76, v76, v82
	v_mul_f32_e32 v77, v77, v82
	v_exp_f32_e32 v66, v66
	v_exp_f32_e32 v74, v74
	v_exp_f32_e32 v75, v75
	v_exp_f32_e32 v76, v76
	v_exp_f32_e32 v77, v77
	v_add_f32_e32 v68, 1.0, v68
	v_add_f32_e32 v78, 1.0, v78
	v_add_f32_e32 v79, 1.0, v79
	v_add_f32_e32 v80, 1.0, v80
	v_add_f32_e32 v81, 1.0, v81
	v_rcp_f32_e32 v68, v68
	v_rcp_f32_e32 v78, v78
	v_rcp_f32_e32 v79, v79
	v_rcp_f32_e32 v80, v80
	v_rcp_f32_e32 v81, v81
	v_add_f32_e32 v66, 1.0, v66
	v_add_f32_e32 v74, 1.0, v74
	v_add_f32_e32 v75, 1.0, v75
	v_add_f32_e32 v76, 1.0, v76
	v_add_f32_e32 v77, 1.0, v77
	v_min_f32_e32 v66, 0x7149f2ca, v66
	v_min_f32_e32 v74, 0x7149f2ca, v74
	v_min_f32_e32 v75, 0x7149f2ca, v75
	v_min_f32_e32 v76, 0x7149f2ca, v76
	v_min_f32_e32 v77, 0x7149f2ca, v77
	v_mul_f32_e32 v69, v68, v66
	v_mul_f32_e32 v78, v78, v74
	v_rcp_f32_e32 v74, v74
	v_mul_f32_e32 v79, v79, v75
	v_rcp_f32_e32 v75, v75
	v_mul_f32_e32 v80, v80, v76
	v_rcp_f32_e32 v76, v76
	v_mul_f32_e32 v81, v81, v77
	v_rcp_f32_e32 v77, v77
	v_rcp_f32_e32 v73, v67
	v_rcp_f32_e32 v88, v66
	v_cvt_pk_bf16_f32 v66, v78, v79
	v_cvt_pk_bf16_f32 v67, v80, v81
	v_cvt_pk_bf16_f32 v68, v70, v72
	v_cvt_pk_bf16_f32 v69, v71, v69
	global_store_dwordx4 v[86:87], v[66:69], off sc1
	v_cvt_pk_bf16_f32 v82, v74, v75
	v_cvt_pk_bf16_f32 v83, v76, v77
	v_cvt_pk_bf16_f32 v84, v84, v85
	v_cvt_pk_bf16_f32 v85, v73, v88
.LBB0_188:
	s_nop 1
	v_add_u32_e32 v68, 0x80, v146
	v_mov_b64_e32 v[66:67], s[10:11]
	v_mad_i64_i32 v[66:67], s[16:17], v68, s83, v[66:67]
	v_lshl_add_u64 v[70:71], v[152:153], 1, v[66:67]
	s_and_b64 vcc, exec, s[40:41]
	s_mov_b64 s[16:17], -1
	global_store_dwordx4 v[86:87], v[82:85], off offset:256 sc1
	s_cbranch_vccnz .LBB0_190
	s_waitcnt lgkmcnt(0)
	v_pk_mul_f32 v[68:69], v[64:65], v[150:151] op_sel_hi:[1,0]
	v_pk_mul_f32 v[66:67], v[62:63], v[150:151] op_sel_hi:[1,0]
	v_pk_mul_f32 v[72:73], v[56:57], v[150:151] op_sel_hi:[1,0]
	v_pk_mul_f32 v[74:75], v[54:55], v[150:151] op_sel_hi:[1,0]
	v_cvt_pk_bf16_f32 v66, v66, v67
	v_cvt_pk_bf16_f32 v67, v68, v69
	s_mov_b64 s[16:17], 0
	v_cvt_pk_bf16_f32 v68, v74, v75
	v_cvt_pk_bf16_f32 v69, v72, v73
	global_store_dwordx4 v[70:71], v[66:69], off sc1
	v_pk_mul_f32 v[72:73], v[52:53], v[150:151] op_sel_hi:[1,0]
	v_pk_mul_f32 v[74:75], v[50:51], v[150:151] op_sel_hi:[1,0]
	v_pk_mul_f32 v[68:69], v[60:61], v[150:151] op_sel_hi:[1,0]
	v_pk_mul_f32 v[66:67], v[58:59], v[150:151] op_sel_hi:[1,0]
	s_nop 0
	v_cvt_pk_bf16_f32 v66, v66, v67
	v_cvt_pk_bf16_f32 v67, v68, v69
	v_cvt_pk_bf16_f32 v68, v74, v75
	v_cvt_pk_bf16_f32 v69, v72, v73
; __device__ __forceinline__ unsigned cvt_pk_bf16(float lo, float hi) { unsigned r; asm volatile("v_cvt_pk_bf16_f32 %0, %1, %2" : "=v"(r) : "v"(lo), "v"(hi)); return r; }
;     __device__ __forceinline__ void operator()(const f32x4 (&acc)[2][2][4][2], const Unit& u, int wr, int wc, int fr, int fq) const {
;     ...
;         for (int ai = 0; ai < 2; ++ai)
; #pragma unroll
;             for (int m = 0; m < 4; ++m) { const int row = row0 + ai * HALF + m * 16; const float r = rr[ai][m]; bf16_t* rowp = O + (size_t)row * IN_W + col0;
;                 if (sig) {
;                     const float c1 = r * -1.4426950408889634f; f32x4 ra[2], gb[2];
; #pragma unroll
;                     for (int n = 0; n < 2; ++n)
; #pragma unroll
;                         for (int j = 0; j < 4; ++j) { const float da = 1.0f + __builtin_amdgcn_exp2f(acc[ai][0][m][n][j] * c1), db = fminf(1.0f + __builtin_amdgcn_exp2f(acc[ai][1][m][n][j] * c1), 1e30f);
;                             ra[n][j] = db * __builtin_amdgcn_rcpf(da); gb[n][j] = __builtin_amdgcn_rcpf(db); }
;                     u32x4 w; w.x = cvt_pk_bf16(ra[0][0], ra[0][1]); w.y = cvt_pk_bf16(ra[0][2], ra[0][3]); w.z = cvt_pk_bf16(ra[1][0], ra[1][1]); w.w = cvt_pk_bf16(ra[1][2], ra[1][3]);
;                     *(u32x4*)rowp = w;
;                     w.x = cvt_pk_bf16(gb[0][0], gb[0][1]); w.y = cvt_pk_bf16(gb[0][2], gb[0][3]); w.z = cvt_pk_bf16(gb[1][0], gb[1][1]); w.w = cvt_pk_bf16(gb[1][2], gb[1][3]);
;                     *(u32x4*)(rowp + HALF) = w;
;                 } else {
; #pragma unroll
;                 for (int bj = 0; bj < 2; ++bj) { const f32x4 v0 = acc[ai][bj][m][0] * r, v1 = acc[ai][bj][m][1] * r;
;                     u32x4 w; w.x = cvt_pk_bf16(v0[0], v0[1]); w.y = cvt_pk_bf16(v0[2], v0[3]); w.z = cvt_pk_bf16(v1[0], v1[1]); w.w = cvt_pk_bf16(v1[2], v1[3]);
;                     *(u32x4*)(rowp + bj * HALF) = w; } } }
.LBB0_190:
	s_andn2_b64 vcc, exec, s[16:17]
	s_cbranch_vccnz .LBB0_192
	s_waitcnt lgkmcnt(0)
	v_mul_f32_e32 v66, 0xbfb8aa3b, v150
	v_mul_f32_e32 v54, v54, v66
	v_exp_f32_e32 v54, v54
	v_mul_f32_e32 v50, v50, v66
	v_exp_f32_e32 v50, v50
	v_mul_f32_e32 v55, v55, v66
	v_add_f32_e32 v54, 1.0, v54
	v_rcp_f32_e32 v54, v54
	v_exp_f32_e32 v55, v55
	v_add_f32_e32 v50, 1.0, v50
	v_mul_f32_e32 v51, v51, v66
	v_min_f32_e32 v50, 0x7149f2ca, v50
	v_exp_f32_e32 v51, v51
	v_mul_f32_e32 v54, v54, v50
	v_rcp_f32_e32 v68, v50
	v_add_f32_e32 v50, 1.0, v55
	v_mul_f32_e32 v55, v56, v66
	v_rcp_f32_e32 v50, v50
	v_exp_f32_e32 v55, v55
	v_mul_f32_e32 v52, v52, v66
	v_add_f32_e32 v51, 1.0, v51
	v_exp_f32_e32 v52, v52
	v_min_f32_e32 v51, 0x7149f2ca, v51
	v_mul_f32_e32 v56, v50, v51
	v_add_f32_e32 v50, 1.0, v55
	v_rcp_f32_e32 v50, v50
	v_rcp_f32_e32 v69, v51
	v_add_f32_e32 v51, 1.0, v52
	v_mul_f32_e32 v52, v57, v66
	v_mul_f32_e32 v62, v62, v66
	v_mul_f32_e32 v63, v63, v66
	v_mul_f32_e32 v64, v64, v66
	v_mul_f32_e32 v65, v65, v66
	v_exp_f32_e32 v52, v52
	v_exp_f32_e32 v62, v62
	v_exp_f32_e32 v63, v63
	v_exp_f32_e32 v64, v64
	v_exp_f32_e32 v65, v65
	v_min_f32_e32 v51, 0x7149f2ca, v51
	v_mul_f32_e32 v55, v50, v51
	v_mul_f32_e32 v50, v53, v66
	v_mul_f32_e32 v58, v58, v66
	v_mul_f32_e32 v59, v59, v66
	v_mul_f32_e32 v60, v60, v66
	v_mul_f32_e32 v61, v61, v66
	v_exp_f32_e32 v50, v50
	v_exp_f32_e32 v58, v58
	v_exp_f32_e32 v59, v59
	v_exp_f32_e32 v60, v60
	v_exp_f32_e32 v61, v61
	v_add_f32_e32 v52, 1.0, v52
	v_add_f32_e32 v62, 1.0, v62
	v_add_f32_e32 v63, 1.0, v63
	v_add_f32_e32 v64, 1.0, v64
	v_add_f32_e32 v65, 1.0, v65
	v_rcp_f32_e32 v52, v52
	v_rcp_f32_e32 v62, v62
	v_rcp_f32_e32 v63, v63
	v_rcp_f32_e32 v64, v64
	v_rcp_f32_e32 v65, v65
	v_add_f32_e32 v50, 1.0, v50
	v_add_f32_e32 v58, 1.0, v58
	v_add_f32_e32 v59, 1.0, v59
	v_add_f32_e32 v60, 1.0, v60
	v_add_f32_e32 v61, 1.0, v61
	v_min_f32_e32 v50, 0x7149f2ca, v50
	v_min_f32_e32 v58, 0x7149f2ca, v58
	v_min_f32_e32 v59, 0x7149f2ca, v59
	v_min_f32_e32 v60, 0x7149f2ca, v60
	v_min_f32_e32 v61, 0x7149f2ca, v61
	v_mul_f32_e32 v53, v52, v50
	v_mul_f32_e32 v62, v62, v58
	v_rcp_f32_e32 v58, v58
	v_mul_f32_e32 v63, v63, v59
	v_rcp_f32_e32 v59, v59
	v_mul_f32_e32 v64, v64, v60
	v_rcp_f32_e32 v60, v60
	v_mul_f32_e32 v65, v65, v61
	v_rcp_f32_e32 v61, v61
	v_rcp_f32_e32 v57, v51
	v_rcp_f32_e32 v72, v50
	v_cvt_pk_bf16_f32 v50, v62, v63
	v_cvt_pk_bf16_f32 v51, v64, v65
	v_cvt_pk_bf16_f32 v52, v54, v56
	v_cvt_pk_bf16_f32 v53, v55, v53
	global_store_dwordx4 v[70:71], v[50:53], off sc1
	v_cvt_pk_bf16_f32 v66, v58, v59
	v_cvt_pk_bf16_f32 v67, v60, v61
	v_cvt_pk_bf16_f32 v68, v68, v69
	v_cvt_pk_bf16_f32 v69, v57, v72
.LBB0_192:
	s_nop 1
	v_add_u32_e32 v52, 0x90, v146
	v_mov_b64_e32 v[50:51], s[10:11]
	v_mad_i64_i32 v[50:51], s[16:17], v52, s83, v[50:51]
	v_lshl_add_u64 v[54:55], v[152:153], 1, v[50:51]
	s_and_b64 vcc, exec, s[40:41]
	s_mov_b64 s[16:17], -1
	global_store_dwordx4 v[70:71], v[66:69], off offset:256 sc1
	s_cbranch_vccnz .LBB0_194
	s_waitcnt lgkmcnt(0)
	v_pk_mul_f32 v[52:53], v[48:49], v[150:151] op_sel:[0,1]
	v_pk_mul_f32 v[50:51], v[46:47], v[150:151] op_sel:[0,1]
	v_pk_mul_f32 v[56:57], v[40:41], v[150:151] op_sel:[0,1]
	v_pk_mul_f32 v[58:59], v[38:39], v[150:151] op_sel:[0,1]
	v_cvt_pk_bf16_f32 v50, v50, v51
	v_cvt_pk_bf16_f32 v51, v52, v53
	s_mov_b64 s[16:17], 0
	v_cvt_pk_bf16_f32 v52, v58, v59
	v_cvt_pk_bf16_f32 v53, v56, v57
	global_store_dwordx4 v[54:55], v[50:53], off sc1
	v_pk_mul_f32 v[56:57], v[36:37], v[150:151] op_sel:[0,1]
	v_pk_mul_f32 v[58:59], v[34:35], v[150:151] op_sel:[0,1]
	v_pk_mul_f32 v[52:53], v[44:45], v[150:151] op_sel:[0,1]
	v_pk_mul_f32 v[50:51], v[42:43], v[150:151] op_sel:[0,1]
	s_nop 0
	v_cvt_pk_bf16_f32 v50, v50, v51
	v_cvt_pk_bf16_f32 v51, v52, v53
	v_cvt_pk_bf16_f32 v52, v58, v59
	v_cvt_pk_bf16_f32 v53, v56, v57
.LBB0_194:
	s_andn2_b64 vcc, exec, s[16:17]
	s_cbranch_vccnz .LBB0_196
	s_waitcnt lgkmcnt(0)
	v_mul_f32_e32 v50, 0xbfb8aa3b, v151
	v_mul_f32_e32 v38, v38, v50
	v_exp_f32_e32 v38, v38
	v_mul_f32_e32 v34, v34, v50
	v_exp_f32_e32 v34, v34
	v_mul_f32_e32 v39, v39, v50
	v_add_f32_e32 v38, 1.0, v38
	v_rcp_f32_e32 v38, v38
	v_exp_f32_e32 v39, v39
	v_add_f32_e32 v34, 1.0, v34
	v_mul_f32_e32 v35, v35, v50
	v_min_f32_e32 v34, 0x7149f2ca, v34
	v_exp_f32_e32 v35, v35
	v_mul_f32_e32 v38, v38, v34
	v_rcp_f32_e32 v52, v34
	v_add_f32_e32 v34, 1.0, v39
	v_mul_f32_e32 v39, v40, v50
	v_rcp_f32_e32 v34, v34
	v_exp_f32_e32 v39, v39
	v_mul_f32_e32 v36, v36, v50
	v_add_f32_e32 v35, 1.0, v35
	v_exp_f32_e32 v36, v36
	v_min_f32_e32 v35, 0x7149f2ca, v35
	v_mul_f32_e32 v40, v34, v35
	v_add_f32_e32 v34, 1.0, v39
	v_rcp_f32_e32 v34, v34
	v_rcp_f32_e32 v53, v35
	v_add_f32_e32 v35, 1.0, v36
	v_mul_f32_e32 v36, v41, v50
	v_mul_f32_e32 v46, v46, v50
	v_mul_f32_e32 v47, v47, v50
	v_mul_f32_e32 v48, v48, v50
	v_mul_f32_e32 v49, v49, v50
	v_exp_f32_e32 v36, v36
	v_exp_f32_e32 v46, v46
	v_exp_f32_e32 v47, v47
	v_exp_f32_e32 v48, v48
	v_exp_f32_e32 v49, v49
	v_min_f32_e32 v35, 0x7149f2ca, v35
	v_mul_f32_e32 v39, v34, v35
	v_mul_f32_e32 v34, v37, v50
	v_mul_f32_e32 v42, v42, v50
	v_mul_f32_e32 v43, v43, v50
	v_mul_f32_e32 v44, v44, v50
	v_mul_f32_e32 v45, v45, v50
	v_exp_f32_e32 v34, v34
	v_exp_f32_e32 v42, v42
	v_exp_f32_e32 v43, v43
	v_exp_f32_e32 v44, v44
	v_exp_f32_e32 v45, v45
	v_add_f32_e32 v36, 1.0, v36
	v_add_f32_e32 v46, 1.0, v46
	v_add_f32_e32 v47, 1.0, v47
	v_add_f32_e32 v48, 1.0, v48
	v_add_f32_e32 v49, 1.0, v49
	v_rcp_f32_e32 v36, v36
	v_rcp_f32_e32 v46, v46
	v_rcp_f32_e32 v47, v47
	v_rcp_f32_e32 v48, v48
	v_rcp_f32_e32 v49, v49
	v_add_f32_e32 v34, 1.0, v34
	v_add_f32_e32 v42, 1.0, v42
	v_add_f32_e32 v43, 1.0, v43
	v_add_f32_e32 v44, 1.0, v44
	v_add_f32_e32 v45, 1.0, v45
	v_min_f32_e32 v34, 0x7149f2ca, v34
	v_min_f32_e32 v42, 0x7149f2ca, v42
	v_min_f32_e32 v43, 0x7149f2ca, v43
	v_min_f32_e32 v44, 0x7149f2ca, v44
	v_min_f32_e32 v45, 0x7149f2ca, v45
	v_mul_f32_e32 v37, v36, v34
	v_mul_f32_e32 v46, v46, v42
	v_rcp_f32_e32 v42, v42
	v_mul_f32_e32 v47, v47, v43
	v_rcp_f32_e32 v43, v43
	v_mul_f32_e32 v48, v48, v44
	v_rcp_f32_e32 v44, v44
	v_mul_f32_e32 v49, v49, v45
	v_rcp_f32_e32 v45, v45
	v_rcp_f32_e32 v41, v35
	v_rcp_f32_e32 v56, v34
	v_cvt_pk_bf16_f32 v34, v46, v47
	v_cvt_pk_bf16_f32 v35, v48, v49
	v_cvt_pk_bf16_f32 v36, v38, v40
	v_cvt_pk_bf16_f32 v37, v39, v37
	global_store_dwordx4 v[54:55], v[34:37], off sc1
	v_cvt_pk_bf16_f32 v50, v42, v43
	v_cvt_pk_bf16_f32 v51, v44, v45
	v_cvt_pk_bf16_f32 v52, v52, v53
	v_cvt_pk_bf16_f32 v53, v41, v56
; __device__ __forceinline__ unsigned cvt_pk_bf16(float lo, float hi) { unsigned r; asm volatile("v_cvt_pk_bf16_f32 %0, %1, %2" : "=v"(r) : "v"(lo), "v"(hi)); return r; }
;     __device__ __forceinline__ void operator()(const f32x4 (&acc)[2][2][4][2], const Unit& u, int wr, int wc, int fr, int fq) const {
;     ...
;         for (int ai = 0; ai < 2; ++ai)
; #pragma unroll
;             for (int m = 0; m < 4; ++m) { const int row = row0 + ai * HALF + m * 16; const float r = rr[ai][m]; bf16_t* rowp = O + (size_t)row * IN_W + col0;
;                 if (sig) {
;                     const float c1 = r * -1.4426950408889634f; f32x4 ra[2], gb[2];
; #pragma unroll
;                     for (int n = 0; n < 2; ++n)
; #pragma unroll
;                         for (int j = 0; j < 4; ++j) { const float da = 1.0f + __builtin_amdgcn_exp2f(acc[ai][0][m][n][j] * c1), db = fminf(1.0f + __builtin_amdgcn_exp2f(acc[ai][1][m][n][j] * c1), 1e30f);
;                             ra[n][j] = db * __builtin_amdgcn_rcpf(da); gb[n][j] = __builtin_amdgcn_rcpf(db); }
;                     u32x4 w; w.x = cvt_pk_bf16(ra[0][0], ra[0][1]); w.y = cvt_pk_bf16(ra[0][2], ra[0][3]); w.z = cvt_pk_bf16(ra[1][0], ra[1][1]); w.w = cvt_pk_bf16(ra[1][2], ra[1][3]);
;                     *(u32x4*)rowp = w;
;                     w.x = cvt_pk_bf16(gb[0][0], gb[0][1]); w.y = cvt_pk_bf16(gb[0][2], gb[0][3]); w.z = cvt_pk_bf16(gb[1][0], gb[1][1]); w.w = cvt_pk_bf16(gb[1][2], gb[1][3]);
;                     *(u32x4*)(rowp + HALF) = w;
;                 } else {
; #pragma unroll
;                 for (int bj = 0; bj < 2; ++bj) { const f32x4 v0 = acc[ai][bj][m][0] * r, v1 = acc[ai][bj][m][1] * r;
;                     u32x4 w; w.x = cvt_pk_bf16(v0[0], v0[1]); w.y = cvt_pk_bf16(v0[2], v0[3]); w.z = cvt_pk_bf16(v1[0], v1[1]); w.w = cvt_pk_bf16(v1[2], v1[3]);
;                     *(u32x4*)(rowp + bj * HALF) = w; } } }
.LBB0_196:
	s_nop 1
	v_add_u32_e32 v36, 0xa0, v146
	v_mov_b64_e32 v[34:35], s[10:11]
	v_mad_i64_i32 v[34:35], s[16:17], v36, s83, v[34:35]
	v_lshl_add_u64 v[38:39], v[152:153], 1, v[34:35]
	s_and_b64 vcc, exec, s[40:41]
	s_mov_b64 s[16:17], -1
	global_store_dwordx4 v[54:55], v[50:53], off offset:256 sc1
	s_cbranch_vccnz .LBB0_198
	s_waitcnt lgkmcnt(0)
	v_pk_mul_f32 v[36:37], v[32:33], v[148:149] op_sel_hi:[1,0]
	v_pk_mul_f32 v[34:35], v[30:31], v[148:149] op_sel_hi:[1,0]
	v_pk_mul_f32 v[40:41], v[24:25], v[148:149] op_sel_hi:[1,0]
	v_pk_mul_f32 v[42:43], v[22:23], v[148:149] op_sel_hi:[1,0]
	v_cvt_pk_bf16_f32 v34, v34, v35
	v_cvt_pk_bf16_f32 v35, v36, v37
	s_mov_b64 s[16:17], 0
	v_cvt_pk_bf16_f32 v36, v42, v43
	v_cvt_pk_bf16_f32 v37, v40, v41
	global_store_dwordx4 v[38:39], v[34:37], off sc1
	v_pk_mul_f32 v[40:41], v[20:21], v[148:149] op_sel_hi:[1,0]
	v_pk_mul_f32 v[42:43], v[18:19], v[148:149] op_sel_hi:[1,0]
	v_pk_mul_f32 v[36:37], v[28:29], v[148:149] op_sel_hi:[1,0]
	v_pk_mul_f32 v[34:35], v[26:27], v[148:149] op_sel_hi:[1,0]
	s_nop 0
	v_cvt_pk_bf16_f32 v34, v34, v35
	v_cvt_pk_bf16_f32 v35, v36, v37
	v_cvt_pk_bf16_f32 v36, v42, v43
	v_cvt_pk_bf16_f32 v37, v40, v41
.LBB0_198:
	s_andn2_b64 vcc, exec, s[16:17]
	s_cbranch_vccnz .LBB0_200
	s_waitcnt lgkmcnt(0)
	v_mul_f32_e32 v34, 0xbfb8aa3b, v148
	v_mul_f32_e32 v22, v22, v34
	v_exp_f32_e32 v22, v22
	v_mul_f32_e32 v18, v18, v34
	v_exp_f32_e32 v18, v18
	v_mul_f32_e32 v23, v23, v34
	v_add_f32_e32 v22, 1.0, v22
	v_rcp_f32_e32 v22, v22
	v_exp_f32_e32 v23, v23
	v_add_f32_e32 v18, 1.0, v18
	v_mul_f32_e32 v19, v19, v34
	v_min_f32_e32 v18, 0x7149f2ca, v18
	v_exp_f32_e32 v19, v19
	v_mul_f32_e32 v22, v22, v18
	v_rcp_f32_e32 v36, v18
	v_add_f32_e32 v18, 1.0, v23
	v_mul_f32_e32 v23, v24, v34
	v_rcp_f32_e32 v18, v18
	v_exp_f32_e32 v23, v23
	v_mul_f32_e32 v20, v20, v34
	v_add_f32_e32 v19, 1.0, v19
	v_exp_f32_e32 v20, v20
	v_min_f32_e32 v19, 0x7149f2ca, v19
	v_mul_f32_e32 v24, v18, v19
	v_add_f32_e32 v18, 1.0, v23
	v_rcp_f32_e32 v18, v18
	v_rcp_f32_e32 v37, v19
	v_add_f32_e32 v19, 1.0, v20
	v_mul_f32_e32 v20, v25, v34
	v_mul_f32_e32 v30, v30, v34
	v_mul_f32_e32 v31, v31, v34
	v_mul_f32_e32 v32, v32, v34
	v_mul_f32_e32 v33, v33, v34
	v_exp_f32_e32 v20, v20
	v_exp_f32_e32 v30, v30
	v_exp_f32_e32 v31, v31
	v_exp_f32_e32 v32, v32
	v_exp_f32_e32 v33, v33
	v_min_f32_e32 v19, 0x7149f2ca, v19
	v_mul_f32_e32 v23, v18, v19
	v_mul_f32_e32 v18, v21, v34
	v_mul_f32_e32 v26, v26, v34
	v_mul_f32_e32 v27, v27, v34
	v_mul_f32_e32 v28, v28, v34
	v_mul_f32_e32 v29, v29, v34
	v_exp_f32_e32 v18, v18
	v_exp_f32_e32 v26, v26
	v_exp_f32_e32 v27, v27
	v_exp_f32_e32 v28, v28
	v_exp_f32_e32 v29, v29
	v_add_f32_e32 v20, 1.0, v20
	v_add_f32_e32 v30, 1.0, v30
	v_add_f32_e32 v31, 1.0, v31
	v_add_f32_e32 v32, 1.0, v32
	v_add_f32_e32 v33, 1.0, v33
	v_rcp_f32_e32 v20, v20
	v_rcp_f32_e32 v30, v30
	v_rcp_f32_e32 v31, v31
	v_rcp_f32_e32 v32, v32
	v_rcp_f32_e32 v33, v33
	v_add_f32_e32 v18, 1.0, v18
	v_add_f32_e32 v26, 1.0, v26
	v_add_f32_e32 v27, 1.0, v27
	v_add_f32_e32 v28, 1.0, v28
	v_add_f32_e32 v29, 1.0, v29
	v_min_f32_e32 v18, 0x7149f2ca, v18
	v_min_f32_e32 v26, 0x7149f2ca, v26
	v_min_f32_e32 v27, 0x7149f2ca, v27
	v_min_f32_e32 v28, 0x7149f2ca, v28
	v_min_f32_e32 v29, 0x7149f2ca, v29
	v_mul_f32_e32 v21, v20, v18
	v_mul_f32_e32 v30, v30, v26
	v_rcp_f32_e32 v26, v26
	v_mul_f32_e32 v31, v31, v27
	v_rcp_f32_e32 v27, v27
	v_mul_f32_e32 v32, v32, v28
	v_rcp_f32_e32 v28, v28
	v_mul_f32_e32 v33, v33, v29
	v_rcp_f32_e32 v29, v29
	v_rcp_f32_e32 v25, v19
	v_rcp_f32_e32 v40, v18
	v_cvt_pk_bf16_f32 v18, v30, v31
	v_cvt_pk_bf16_f32 v19, v32, v33
	v_cvt_pk_bf16_f32 v20, v22, v24
	v_cvt_pk_bf16_f32 v21, v23, v21
	global_store_dwordx4 v[38:39], v[18:21], off sc1
	v_cvt_pk_bf16_f32 v34, v26, v27
	v_cvt_pk_bf16_f32 v35, v28, v29
	v_cvt_pk_bf16_f32 v36, v36, v37
	v_cvt_pk_bf16_f32 v37, v25, v40
; __device__ __forceinline__ unsigned cvt_pk_bf16(float lo, float hi) { unsigned r; asm volatile("v_cvt_pk_bf16_f32 %0, %1, %2" : "=v"(r) : "v"(lo), "v"(hi)); return r; }
;     __device__ __forceinline__ void operator()(const f32x4 (&acc)[2][2][4][2], const Unit& u, int wr, int wc, int fr, int fq) const {
;     ...
;         for (int ai = 0; ai < 2; ++ai)
; #pragma unroll
;             for (int m = 0; m < 4; ++m) { const int row = row0 + ai * HALF + m * 16; const float r = rr[ai][m]; bf16_t* rowp = O + (size_t)row * IN_W + col0;
;                 if (sig) {
;                     const float c1 = r * -1.4426950408889634f; f32x4 ra[2], gb[2];
; #pragma unroll
;                     for (int n = 0; n < 2; ++n)
; #pragma unroll
;                         for (int j = 0; j < 4; ++j) { const float da = 1.0f + __builtin_amdgcn_exp2f(acc[ai][0][m][n][j] * c1), db = fminf(1.0f + __builtin_amdgcn_exp2f(acc[ai][1][m][n][j] * c1), 1e30f);
;                             ra[n][j] = db * __builtin_amdgcn_rcpf(da); gb[n][j] = __builtin_amdgcn_rcpf(db); }
;                     u32x4 w; w.x = cvt_pk_bf16(ra[0][0], ra[0][1]); w.y = cvt_pk_bf16(ra[0][2], ra[0][3]); w.z = cvt_pk_bf16(ra[1][0], ra[1][1]); w.w = cvt_pk_bf16(ra[1][2], ra[1][3]);
;                     *(u32x4*)rowp = w;
;                     w.x = cvt_pk_bf16(gb[0][0], gb[0][1]); w.y = cvt_pk_bf16(gb[0][2], gb[0][3]); w.z = cvt_pk_bf16(gb[1][0], gb[1][1]); w.w = cvt_pk_bf16(gb[1][2], gb[1][3]);
;                     *(u32x4*)(rowp + HALF) = w;
;                 } else {
; #pragma unroll
;                 for (int bj = 0; bj < 2; ++bj) { const f32x4 v0 = acc[ai][bj][m][0] * r, v1 = acc[ai][bj][m][1] * r;
;                     u32x4 w; w.x = cvt_pk_bf16(v0[0], v0[1]); w.y = cvt_pk_bf16(v0[2], v0[3]); w.z = cvt_pk_bf16(v1[0], v1[1]); w.w = cvt_pk_bf16(v1[2], v1[3]);
;                     *(u32x4*)(rowp + bj * HALF) = w; } } }
.LBB0_200:
	s_nop 1
	v_add_u32_e32 v20, 0xb0, v146
	v_mov_b64_e32 v[18:19], s[10:11]
	v_mad_i64_i32 v[18:19], s[16:17], v20, s83, v[18:19]
	v_lshl_add_u64 v[22:23], v[152:153], 1, v[18:19]
	s_and_b64 vcc, exec, s[40:41]
	s_mov_b64 s[16:17], -1
	global_store_dwordx4 v[38:39], v[34:37], off offset:256 sc1
	s_cbranch_vccz .LBB0_203
	s_andn2_b64 vcc, exec, s[16:17]
	s_cbranch_vccz .LBB0_204
.LBB0_202:
	s_andn2_b64 vcc, exec, s[38:39]
	s_mov_b64 s[16:17], -1
	global_store_dwordx4 v[22:23], v[18:21], off offset:256 sc1
	s_cbranch_vccnz .LBB0_161
	s_branch .LBB0_205
.LBB0_203:
	s_waitcnt lgkmcnt(0)
	v_pk_mul_f32 v[20:21], v[16:17], v[148:149] op_sel:[0,1]
	v_pk_mul_f32 v[18:19], v[14:15], v[148:149] op_sel:[0,1]
	v_pk_mul_f32 v[24:25], v[8:9], v[148:149] op_sel:[0,1]
	v_pk_mul_f32 v[26:27], v[6:7], v[148:149] op_sel:[0,1]
	v_cvt_pk_bf16_f32 v18, v18, v19
	v_cvt_pk_bf16_f32 v19, v20, v21
	s_nop 0
	v_cvt_pk_bf16_f32 v20, v26, v27
	v_cvt_pk_bf16_f32 v21, v24, v25
	global_store_dwordx4 v[22:23], v[18:21], off sc1
	v_pk_mul_f32 v[24:25], v[4:5], v[148:149] op_sel:[0,1]
	v_pk_mul_f32 v[26:27], v[2:3], v[148:149] op_sel:[0,1]
	v_pk_mul_f32 v[20:21], v[12:13], v[148:149] op_sel:[0,1]
	v_pk_mul_f32 v[18:19], v[10:11], v[148:149] op_sel:[0,1]
	s_nop 0
	v_cvt_pk_bf16_f32 v18, v18, v19
	v_cvt_pk_bf16_f32 v19, v20, v21
	v_cvt_pk_bf16_f32 v20, v26, v27
	v_cvt_pk_bf16_f32 v21, v24, v25
	s_cbranch_execnz .LBB0_202
.LBB0_204:
	s_waitcnt lgkmcnt(0)
	v_mul_f32_e32 v18, 0xbfb8aa3b, v149
	v_mul_f32_e32 v6, v6, v18
	v_exp_f32_e32 v6, v6
	v_mul_f32_e32 v2, v2, v18
	v_exp_f32_e32 v2, v2
	v_mul_f32_e32 v7, v7, v18
	v_add_f32_e32 v6, 1.0, v6
	v_rcp_f32_e32 v6, v6
	v_exp_f32_e32 v7, v7
	v_add_f32_e32 v2, 1.0, v2
	v_mul_f32_e32 v3, v3, v18
	v_min_f32_e32 v2, 0x7149f2ca, v2
	v_exp_f32_e32 v3, v3
	v_mul_f32_e32 v6, v6, v2
	v_rcp_f32_e32 v20, v2
	v_add_f32_e32 v2, 1.0, v7
	v_mul_f32_e32 v7, v8, v18
	v_rcp_f32_e32 v2, v2
	v_exp_f32_e32 v7, v7
	v_mul_f32_e32 v4, v4, v18
	v_add_f32_e32 v3, 1.0, v3
	v_exp_f32_e32 v4, v4
	v_min_f32_e32 v3, 0x7149f2ca, v3
	v_mul_f32_e32 v8, v2, v3
	v_add_f32_e32 v2, 1.0, v7
	v_rcp_f32_e32 v2, v2
	v_rcp_f32_e32 v21, v3
	v_add_f32_e32 v3, 1.0, v4
	v_mul_f32_e32 v4, v9, v18
	v_mul_f32_e32 v14, v14, v18
	v_mul_f32_e32 v15, v15, v18
	v_mul_f32_e32 v16, v16, v18
	v_mul_f32_e32 v17, v17, v18
	v_exp_f32_e32 v4, v4
	v_exp_f32_e32 v14, v14
	v_exp_f32_e32 v15, v15
	v_exp_f32_e32 v16, v16
	v_exp_f32_e32 v17, v17
	v_min_f32_e32 v3, 0x7149f2ca, v3
	v_mul_f32_e32 v7, v2, v3
	v_mul_f32_e32 v2, v5, v18
	v_mul_f32_e32 v10, v10, v18
	v_mul_f32_e32 v11, v11, v18
	v_mul_f32_e32 v12, v12, v18
	v_mul_f32_e32 v13, v13, v18
	v_exp_f32_e32 v2, v2
	v_exp_f32_e32 v10, v10
	v_exp_f32_e32 v11, v11
	v_exp_f32_e32 v12, v12
	v_exp_f32_e32 v13, v13
	v_add_f32_e32 v4, 1.0, v4
	v_add_f32_e32 v14, 1.0, v14
	v_add_f32_e32 v15, 1.0, v15
	v_add_f32_e32 v16, 1.0, v16
	v_add_f32_e32 v17, 1.0, v17
	v_rcp_f32_e32 v4, v4
	v_rcp_f32_e32 v14, v14
	v_rcp_f32_e32 v15, v15
	v_rcp_f32_e32 v16, v16
	v_rcp_f32_e32 v17, v17
	v_add_f32_e32 v2, 1.0, v2
	v_add_f32_e32 v10, 1.0, v10
	v_add_f32_e32 v11, 1.0, v11
	v_add_f32_e32 v12, 1.0, v12
	v_add_f32_e32 v13, 1.0, v13
	v_min_f32_e32 v2, 0x7149f2ca, v2
	v_min_f32_e32 v10, 0x7149f2ca, v10
	v_min_f32_e32 v11, 0x7149f2ca, v11
	v_min_f32_e32 v12, 0x7149f2ca, v12
	v_min_f32_e32 v13, 0x7149f2ca, v13
	v_mul_f32_e32 v5, v4, v2
	v_mul_f32_e32 v14, v14, v10
	v_rcp_f32_e32 v10, v10
	v_mul_f32_e32 v15, v15, v11
	v_rcp_f32_e32 v11, v11
	v_mul_f32_e32 v16, v16, v12
	v_rcp_f32_e32 v12, v12
	v_mul_f32_e32 v17, v17, v13
	v_rcp_f32_e32 v13, v13
	v_rcp_f32_e32 v9, v3
	v_rcp_f32_e32 v24, v2
	v_cvt_pk_bf16_f32 v2, v14, v15
	v_cvt_pk_bf16_f32 v3, v16, v17
	v_cvt_pk_bf16_f32 v4, v6, v8
	v_cvt_pk_bf16_f32 v5, v7, v5
	global_store_dwordx4 v[22:23], v[2:5], off sc1
	v_cvt_pk_bf16_f32 v18, v10, v11
	v_cvt_pk_bf16_f32 v19, v12, v13
	v_cvt_pk_bf16_f32 v20, v20, v21
	v_cvt_pk_bf16_f32 v21, v9, v24
	s_andn2_b64 vcc, exec, s[38:39]
	s_mov_b64 s[16:17], -1
	global_store_dwordx4 v[22:23], v[18:21], off offset:256 sc1
	s_cbranch_vccnz .LBB0_161

; __device__ __forceinline__ unsigned cvt_pk_bf16(float lo, float hi) { unsigned r; asm volatile("v_cvt_pk_bf16_f32 %0, %1, %2" : "=v"(r) : "v"(lo), "v"(hi)); return r; }
; __device__ __forceinline__ float bf_lo(unsigned w) { return __uint_as_float(w << 16); }
; __device__ __forceinline__ float bf_hi(unsigned w) { return __uint_as_float(w & 0xffff0000u); }
;     __device__ __forceinline__ void operator()(f32x4 (&acc)[2][2][4][2], const Unit& u, int wr, int wc, int fr, int fq) const {
;     ...
; #pragma unroll
;         for (int ai = 0; ai < 2; ++ai) {
;             u32x4 gw[4][2];
; #pragma unroll
;             for (int m = 0; m < 4; ++m)
; #pragma unroll
;                 for (int bj = 0; bj < 2; ++bj) gw[m][bj] = *(const u32x4*)(P + (size_t)(row0 + ai * HALF + m * 16) * IN_W + gcol + bj * 256);
; #pragma unroll
;             for (int m = 0; m < 4; ++m)
; #pragma unroll
;                 for (int bj = 0; bj < 2; ++bj) { const int row = row0 + ai * HALF + m * 16, col = col0 + bj * HALF; const u32x4 g = gw[m][bj];
;                     f32x4 g0, g1; g0[0] = bf_lo(g.x); g0[1] = bf_hi(g.x); g0[2] = bf_lo(g.y); g0[3] = bf_hi(g.y); g1[0] = bf_lo(g.z); g1[1] = bf_hi(g.z); g1[2] = bf_lo(g.w); g1[3] = bf_hi(g.w);
;                     if (u.part == 0) { acc[ai][bj][m][0] = acc[ai][bj][m][0] * g0; acc[ai][bj][m][1] = acc[ai][bj][m][1] * g1; }
;                     else { const f32x4 v0 = acc[ai][bj][m][0] * g0, v1 = acc[ai][bj][m][1] * g1;
;                         u32x4 w; w.x = cvt_pk_bf16(v0[0], v0[1]); w.y = cvt_pk_bf16(v0[2], v0[3]); w.z = cvt_pk_bf16(v1[0], v1[1]); w.w = cvt_pk_bf16(v1[2], v1[3]);
;                         *(u32x4*)(O + (size_t)row * D_MODEL + col) = w; } } }
.LBB0_432:
	s_lshl_b32 s19, s43, 9
	s_cmp_eq_u32 s42, 0
	s_cselect_b64 s[16:17], -1, 0
	s_and_b64 vcc, s[16:17], exec
	s_cselect_b32 s16, 0, 0x80
	s_or_b32 s19, s19, s16
	s_cmp_lg_u32 s42, 0
	s_cselect_b64 s[16:17], -1, 0
	s_addk_i32 s19, 0xe00
	v_or_b32_e32 v52, s19, v219
	v_ashrrev_i32_e32 v53, 31, v52
	v_lshl_add_u32 v192, s51, 8, v217
	v_lshl_add_u64 v[194:195], v[52:53], 1, s[10:11]
	v_mad_i64_i32 v[56:57], s[26:27], v192, s83, v[194:195]
	v_or_b32_e32 v200, 16, v192
	global_load_dwordx4 v[52:55], v[56:57], off
	global_load_dwordx4 v[96:99], v[56:57], off offset:512
	v_mad_i64_i32 v[56:57], s[26:27], v200, s83, v[194:195]
	v_or_b32_e32 v198, 32, v192
	global_load_dwordx4 v[92:95], v[56:57], off
	global_load_dwordx4 v[128:131], v[56:57], off offset:512
	v_mad_i64_i32 v[56:57], s[26:27], v198, s83, v[194:195]
	v_or_b32_e32 v196, 48, v192
	global_load_dwordx4 v[124:127], v[56:57], off
	global_load_dwordx4 v[152:155], v[56:57], off offset:512
	v_mad_i64_i32 v[56:57], s[26:27], v196, s83, v[194:195]
	global_load_dwordx4 v[148:151], v[56:57], off
	global_load_dwordx4 v[164:167], v[56:57], off offset:512
	v_ashrrev_i32_e32 v193, 31, v192
	v_lshl_or_b32 v2, s43, 8, v219
	v_lshlrev_b64 v[202:203], 12, v[192:193]
	v_lshl_add_u64 v[202:203], s[14:15], 0, v[202:203]
	v_ashrrev_i32_e32 v3, 31, v2
	s_waitcnt vmcnt(0)
	v_lshlrev_b32_e32 v56, 16, v52
	v_and_b32_e32 v57, 0xffff0000, v52
	v_lshlrev_b32_e32 v52, 16, v53
	v_and_b32_e32 v53, 0xffff0000, v53
	v_lshlrev_b32_e32 v222, 16, v54
	v_and_b32_e32 v223, 0xffff0000, v54
	v_lshlrev_b32_e32 v54, 16, v55
	v_and_b32_e32 v55, 0xffff0000, v55
	v_pk_mul_f32 v[58:59], v[90:91], v[52:53]
	v_pk_mul_f32 v[56:57], v[88:89], v[56:57]
	v_pk_mul_f32 v[54:55], v[86:87], v[54:55]
	v_pk_mul_f32 v[52:53], v[84:85], v[222:223]
	s_cbranch_vccnz .LBB0_434
	v_cvt_pk_bf16_f32 v56, v56, v57
	v_cvt_pk_bf16_f32 v57, v58, v59
	v_cvt_pk_bf16_f32 v58, v52, v53
	v_cvt_pk_bf16_f32 v59, v54, v55
	v_lshl_add_u64 v[52:53], v[2:3], 1, v[202:203]
	global_store_dwordx4 v[52:53], v[56:59], off sc1
	v_mov_b64_e32 v[52:53], v[84:85]
	v_mov_b64_e32 v[54:55], v[86:87]
	v_mov_b64_e32 v[56:57], v[88:89]
	v_mov_b64_e32 v[58:59], v[90:91]
.LBB0_434:
	v_lshlrev_b32_e32 v84, 16, v96
	v_and_b32_e32 v85, 0xffff0000, v96
	v_lshlrev_b32_e32 v86, 16, v97
	v_and_b32_e32 v87, 0xffff0000, v97
	v_lshlrev_b32_e32 v88, 16, v98
	v_and_b32_e32 v89, 0xffff0000, v98
	v_lshlrev_b32_e32 v90, 16, v99
	v_and_b32_e32 v91, 0xffff0000, v99
	v_cndmask_b32_e64 v0, 0, 1, s[16:17]
	v_pk_mul_f32 v[86:87], v[162:163], v[86:87]
	v_pk_mul_f32 v[84:85], v[160:161], v[84:85]
	v_pk_mul_f32 v[90:91], v[158:159], v[90:91]
	v_cmp_ne_u32_e64 s[42:43], 1, v0
	s_andn2_b64 vcc, exec, s[16:17]
	v_pk_mul_f32 v[88:89], v[156:157], v[88:89]
	s_cbranch_vccnz .LBB0_436
	v_cvt_pk_bf16_f32 v84, v84, v85
	v_cvt_pk_bf16_f32 v85, v86, v87
	v_cvt_pk_bf16_f32 v86, v88, v89
	v_cvt_pk_bf16_f32 v87, v90, v91
	v_lshl_add_u64 v[88:89], v[2:3], 1, v[202:203]
	global_store_dwordx4 v[88:89], v[84:87], off offset:256 sc1
	v_mov_b64_e32 v[88:89], v[156:157]
	v_mov_b64_e32 v[90:91], v[158:159]
	v_mov_b64_e32 v[84:85], v[160:161]
	v_mov_b64_e32 v[86:87], v[162:163]
.LBB0_436:
	v_ashrrev_i32_e32 v201, 31, v200
	v_lshlrev_b64 v[156:157], 12, v[200:201]
	v_lshlrev_b32_e32 v96, 16, v92
	v_and_b32_e32 v97, 0xffff0000, v92
	v_lshlrev_b32_e32 v92, 16, v93
	v_and_b32_e32 v93, 0xffff0000, v93
	v_lshlrev_b32_e32 v158, 16, v94
	v_and_b32_e32 v159, 0xffff0000, v94
	v_lshlrev_b32_e32 v98, 16, v95
	v_and_b32_e32 v99, 0xffff0000, v95
	v_pk_mul_f32 v[94:95], v[122:123], v[92:93]
	v_pk_mul_f32 v[92:93], v[120:121], v[96:97]
	v_pk_mul_f32 v[98:99], v[110:111], v[98:99]
	v_pk_mul_f32 v[96:97], v[108:109], v[158:159]
	s_and_b64 vcc, exec, s[42:43]
	v_lshl_add_u64 v[156:157], s[14:15], 0, v[156:157]
	s_cbranch_vccnz .LBB0_438
	v_cvt_pk_bf16_f32 v92, v92, v93
	v_cvt_pk_bf16_f32 v93, v94, v95
	v_cvt_pk_bf16_f32 v94, v96, v97
	v_cvt_pk_bf16_f32 v95, v98, v99
	v_lshl_add_u64 v[96:97], v[2:3], 1, v[156:157]
	global_store_dwordx4 v[96:97], v[92:95], off sc1
	v_mov_b64_e32 v[96:97], v[108:109]
	v_mov_b64_e32 v[98:99], v[110:111]
	v_mov_b64_e32 v[92:93], v[120:121]
	v_mov_b64_e32 v[94:95], v[122:123]
.LBB0_438:
	v_lshlrev_b32_e32 v108, 16, v128
	v_and_b32_e32 v109, 0xffff0000, v128
	v_lshlrev_b32_e32 v110, 16, v129
	v_and_b32_e32 v111, 0xffff0000, v129
	v_lshlrev_b32_e32 v120, 16, v130
	v_and_b32_e32 v121, 0xffff0000, v130
	v_lshlrev_b32_e32 v122, 16, v131
	v_and_b32_e32 v123, 0xffff0000, v131
	v_pk_mul_f32 v[110:111], v[146:147], v[110:111]
	v_pk_mul_f32 v[108:109], v[144:145], v[108:109]
	v_pk_mul_f32 v[122:123], v[142:143], v[122:123]
	s_and_b64 vcc, exec, s[42:43]
	v_pk_mul_f32 v[120:121], v[140:141], v[120:121]
	s_cbranch_vccnz .LBB0_440
	v_cvt_pk_bf16_f32 v108, v108, v109
	v_cvt_pk_bf16_f32 v109, v110, v111
	v_cvt_pk_bf16_f32 v110, v120, v121
	v_cvt_pk_bf16_f32 v111, v122, v123
	v_lshl_add_u64 v[120:121], v[2:3], 1, v[156:157]
	global_store_dwordx4 v[120:121], v[108:111], off offset:256 sc1
	v_mov_b64_e32 v[120:121], v[140:141]
	v_mov_b64_e32 v[122:123], v[142:143]
	v_mov_b64_e32 v[108:109], v[144:145]
	v_mov_b64_e32 v[110:111], v[146:147]
; __device__ __forceinline__ unsigned cvt_pk_bf16(float lo, float hi) { unsigned r; asm volatile("v_cvt_pk_bf16_f32 %0, %1, %2" : "=v"(r) : "v"(lo), "v"(hi)); return r; }
; __device__ __forceinline__ float bf_lo(unsigned w) { return __uint_as_float(w << 16); }
; __device__ __forceinline__ float bf_hi(unsigned w) { return __uint_as_float(w & 0xffff0000u); }
;     __device__ __forceinline__ void operator()(f32x4 (&acc)[2][2][4][2], const Unit& u, int wr, int wc, int fr, int fq) const {
;     ...
; #pragma unroll
;         for (int ai = 0; ai < 2; ++ai) {
;             u32x4 gw[4][2];
; #pragma unroll
;             for (int m = 0; m < 4; ++m)
; #pragma unroll
;                 for (int bj = 0; bj < 2; ++bj) gw[m][bj] = *(const u32x4*)(P + (size_t)(row0 + ai * HALF + m * 16) * IN_W + gcol + bj * 256);
; #pragma unroll
;             for (int m = 0; m < 4; ++m)
; #pragma unroll
;                 for (int bj = 0; bj < 2; ++bj) { const int row = row0 + ai * HALF + m * 16, col = col0 + bj * HALF; const u32x4 g = gw[m][bj];
;                     f32x4 g0, g1; g0[0] = bf_lo(g.x); g0[1] = bf_hi(g.x); g0[2] = bf_lo(g.y); g0[3] = bf_hi(g.y); g1[0] = bf_lo(g.z); g1[1] = bf_hi(g.z); g1[2] = bf_lo(g.w); g1[3] = bf_hi(g.w);
;                     if (u.part == 0) { acc[ai][bj][m][0] = acc[ai][bj][m][0] * g0; acc[ai][bj][m][1] = acc[ai][bj][m][1] * g1; }
;                     else { const f32x4 v0 = acc[ai][bj][m][0] * g0, v1 = acc[ai][bj][m][1] * g1;
;                         u32x4 w; w.x = cvt_pk_bf16(v0[0], v0[1]); w.y = cvt_pk_bf16(v0[2], v0[3]); w.z = cvt_pk_bf16(v1[0], v1[1]); w.w = cvt_pk_bf16(v1[2], v1[3]);
;                         *(u32x4*)(O + (size_t)row * D_MODEL + col) = w; } } }
.LBB0_440:
	v_ashrrev_i32_e32 v199, 31, v198
	v_lshlrev_b64 v[140:141], 12, v[198:199]
	v_lshlrev_b32_e32 v128, 16, v124
	v_and_b32_e32 v129, 0xffff0000, v124
	v_lshlrev_b32_e32 v124, 16, v125
	v_and_b32_e32 v125, 0xffff0000, v125
	v_lshlrev_b32_e32 v142, 16, v126
	v_and_b32_e32 v143, 0xffff0000, v126
	v_lshlrev_b32_e32 v130, 16, v127
	v_and_b32_e32 v131, 0xffff0000, v127
	v_pk_mul_f32 v[126:127], v[138:139], v[124:125]
	v_pk_mul_f32 v[124:125], v[136:137], v[128:129]
	v_pk_mul_f32 v[130:131], v[134:135], v[130:131]
	v_pk_mul_f32 v[128:129], v[132:133], v[142:143]
	s_and_b64 vcc, exec, s[42:43]
	v_lshl_add_u64 v[140:141], s[14:15], 0, v[140:141]
	s_cbranch_vccnz .LBB0_442
	v_cvt_pk_bf16_f32 v124, v124, v125
	v_cvt_pk_bf16_f32 v125, v126, v127
	v_cvt_pk_bf16_f32 v126, v128, v129
	v_cvt_pk_bf16_f32 v127, v130, v131
	v_lshl_add_u64 v[128:129], v[2:3], 1, v[140:141]
	global_store_dwordx4 v[128:129], v[124:127], off sc1
	v_mov_b64_e32 v[128:129], v[132:133]
	v_mov_b64_e32 v[130:131], v[134:135]
	v_mov_b64_e32 v[124:125], v[136:137]
	v_mov_b64_e32 v[126:127], v[138:139]
.LBB0_442:
	v_lshlrev_b32_e32 v132, 16, v152
	v_and_b32_e32 v133, 0xffff0000, v152
	v_lshlrev_b32_e32 v134, 16, v153
	v_and_b32_e32 v135, 0xffff0000, v153
	v_lshlrev_b32_e32 v136, 16, v154
	v_and_b32_e32 v137, 0xffff0000, v154
	v_lshlrev_b32_e32 v138, 16, v155
	v_and_b32_e32 v139, 0xffff0000, v155
	v_pk_mul_f32 v[134:135], v[118:119], v[134:135]
	v_pk_mul_f32 v[132:133], v[116:117], v[132:133]
	v_pk_mul_f32 v[138:139], v[114:115], v[138:139]
	s_and_b64 vcc, exec, s[42:43]
	v_pk_mul_f32 v[136:137], v[112:113], v[136:137]
	s_cbranch_vccnz .LBB0_444
	v_cvt_pk_bf16_f32 v132, v132, v133
	v_cvt_pk_bf16_f32 v133, v134, v135
	v_cvt_pk_bf16_f32 v134, v136, v137
	v_cvt_pk_bf16_f32 v135, v138, v139
	v_lshl_add_u64 v[136:137], v[2:3], 1, v[140:141]
	global_store_dwordx4 v[136:137], v[132:135], off offset:256 sc1
	v_mov_b64_e32 v[138:139], v[114:115]
	v_mov_b64_e32 v[136:137], v[112:113]
	v_mov_b64_e32 v[134:135], v[118:119]
	v_mov_b64_e32 v[132:133], v[116:117]
.LBB0_444:
	v_ashrrev_i32_e32 v197, 31, v196
	v_lshlrev_b64 v[112:113], 12, v[196:197]
	v_lshlrev_b32_e32 v114, 16, v148
	v_and_b32_e32 v115, 0xffff0000, v148
	v_lshlrev_b32_e32 v116, 16, v149
	v_and_b32_e32 v117, 0xffff0000, v149
	v_lshlrev_b32_e32 v118, 16, v150
	v_and_b32_e32 v119, 0xffff0000, v150
	v_lshlrev_b32_e32 v140, 16, v151
	v_and_b32_e32 v141, 0xffff0000, v151
	v_pk_mul_f32 v[150:151], v[106:107], v[116:117]
	v_pk_mul_f32 v[148:149], v[104:105], v[114:115]
	v_pk_mul_f32 v[154:155], v[102:103], v[140:141]
	v_pk_mul_f32 v[152:153], v[100:101], v[118:119]
	s_and_b64 vcc, exec, s[42:43]
	v_lshl_add_u64 v[112:113], s[14:15], 0, v[112:113]
	s_cbranch_vccnz .LBB0_446
	v_cvt_pk_bf16_f32 v114, v148, v149
	v_cvt_pk_bf16_f32 v115, v150, v151
	v_cvt_pk_bf16_f32 v116, v152, v153
	v_cvt_pk_bf16_f32 v117, v154, v155
	v_mov_b64_e32 v[154:155], v[102:103]
	v_mov_b64_e32 v[150:151], v[106:107]
	v_lshl_add_u64 v[118:119], v[2:3], 1, v[112:113]
	v_mov_b64_e32 v[152:153], v[100:101]
	v_mov_b64_e32 v[148:149], v[104:105]
	global_store_dwordx4 v[118:119], v[114:117], off sc1
.LBB0_446:
	v_lshlrev_b32_e32 v100, 16, v164
	v_and_b32_e32 v101, 0xffff0000, v164
	v_lshlrev_b32_e32 v102, 16, v165
	v_and_b32_e32 v103, 0xffff0000, v165
	v_lshlrev_b32_e32 v104, 16, v166
	v_and_b32_e32 v105, 0xffff0000, v166
	v_lshlrev_b32_e32 v106, 16, v167
	v_and_b32_e32 v107, 0xffff0000, v167
	v_pk_mul_f32 v[102:103], v[82:83], v[102:103]
	v_pk_mul_f32 v[100:101], v[80:81], v[100:101]
	v_pk_mul_f32 v[106:107], v[78:79], v[106:107]
	s_and_b64 vcc, exec, s[42:43]
	v_pk_mul_f32 v[104:105], v[76:77], v[104:105]
	s_cbranch_vccnz .LBB0_448
	v_cvt_pk_bf16_f32 v100, v100, v101
	v_cvt_pk_bf16_f32 v101, v102, v103
	v_cvt_pk_bf16_f32 v102, v104, v105
	v_cvt_pk_bf16_f32 v103, v106, v107
	v_lshl_add_u64 v[104:105], v[2:3], 1, v[112:113]
	global_store_dwordx4 v[104:105], v[100:103], off offset:256 sc1
	v_mov_b64_e32 v[106:107], v[78:79]
	v_mov_b64_e32 v[104:105], v[76:77]
	v_mov_b64_e32 v[102:103], v[82:83]
	v_mov_b64_e32 v[100:101], v[80:81]
.LBB0_448:
	v_add_u32_e32 v80, 0x80, v192
	v_mad_i64_i32 v[82:83], s[16:17], v80, s83, v[194:195]
	v_add_u32_e32 v198, 0x90, v192
	global_load_dwordx4 v[76:79], v[82:83], off
	global_load_dwordx4 v[116:119], v[82:83], off offset:512
	v_mad_i64_i32 v[82:83], s[16:17], v198, s83, v[194:195]
	v_add_u32_e32 v196, 0xa0, v192
	global_load_dwordx4 v[112:115], v[82:83], off
	global_load_dwordx4 v[156:159], v[82:83], off offset:512
	v_mad_i64_i32 v[82:83], s[16:17], v196, s83, v[194:195]
	v_add_u32_e32 v192, 0xb0, v192
	global_load_dwordx4 v[144:147], v[82:83], off
	global_load_dwordx4 v[164:167], v[82:83], off offset:512
	v_mad_i64_i32 v[82:83], s[16:17], v192, s83, v[194:195]
	global_load_dwordx4 v[160:163], v[82:83], off
	global_load_dwordx4 v[140:143], v[82:83], off offset:512
	v_ashrrev_i32_e32 v81, 31, v80
	v_lshlrev_b64 v[194:195], 12, v[80:81]
	s_and_b64 vcc, exec, s[42:43]
	v_lshl_add_u64 v[194:195], s[14:15], 0, v[194:195]
	s_waitcnt vmcnt(7)
	v_lshlrev_b32_e32 v80, 16, v76
	v_and_b32_e32 v81, 0xffff0000, v76
	v_lshlrev_b32_e32 v76, 16, v77
	v_and_b32_e32 v77, 0xffff0000, v77
	v_lshlrev_b32_e32 v200, 16, v78
	v_and_b32_e32 v201, 0xffff0000, v78
	v_lshlrev_b32_e32 v78, 16, v79
	v_and_b32_e32 v79, 0xffff0000, v79
	v_pk_mul_f32 v[82:83], v[74:75], v[76:77]
	v_pk_mul_f32 v[80:81], v[72:73], v[80:81]
	v_pk_mul_f32 v[78:79], v[70:71], v[78:79]
	v_pk_mul_f32 v[76:77], v[68:69], v[200:201]
	s_cbranch_vccnz .LBB0_450
	v_cvt_pk_bf16_f32 v80, v80, v81
	v_cvt_pk_bf16_f32 v81, v82, v83
	v_cvt_pk_bf16_f32 v82, v76, v77
	v_cvt_pk_bf16_f32 v83, v78, v79
	v_lshl_add_u64 v[76:77], v[2:3], 1, v[194:195]
	global_store_dwordx4 v[76:77], v[80:83], off sc1
	v_mov_b64_e32 v[78:79], v[70:71]
	v_mov_b64_e32 v[76:77], v[68:69]
	v_mov_b64_e32 v[82:83], v[74:75]
	v_mov_b64_e32 v[80:81], v[72:73]
; __device__ __forceinline__ unsigned cvt_pk_bf16(float lo, float hi) { unsigned r; asm volatile("v_cvt_pk_bf16_f32 %0, %1, %2" : "=v"(r) : "v"(lo), "v"(hi)); return r; }
; __device__ __forceinline__ float bf_lo(unsigned w) { return __uint_as_float(w << 16); }
; __device__ __forceinline__ float bf_hi(unsigned w) { return __uint_as_float(w & 0xffff0000u); }
;     __device__ __forceinline__ void operator()(f32x4 (&acc)[2][2][4][2], const Unit& u, int wr, int wc, int fr, int fq) const {
;     ...
; #pragma unroll
;         for (int ai = 0; ai < 2; ++ai) {
;             u32x4 gw[4][2];
; #pragma unroll
;             for (int m = 0; m < 4; ++m)
; #pragma unroll
;                 for (int bj = 0; bj < 2; ++bj) gw[m][bj] = *(const u32x4*)(P + (size_t)(row0 + ai * HALF + m * 16) * IN_W + gcol + bj * 256);
; #pragma unroll
;             for (int m = 0; m < 4; ++m)
; #pragma unroll
;                 for (int bj = 0; bj < 2; ++bj) { const int row = row0 + ai * HALF + m * 16, col = col0 + bj * HALF; const u32x4 g = gw[m][bj];
;                     f32x4 g0, g1; g0[0] = bf_lo(g.x); g0[1] = bf_hi(g.x); g0[2] = bf_lo(g.y); g0[3] = bf_hi(g.y); g1[0] = bf_lo(g.z); g1[1] = bf_hi(g.z); g1[2] = bf_lo(g.w); g1[3] = bf_hi(g.w);
;                     if (u.part == 0) { acc[ai][bj][m][0] = acc[ai][bj][m][0] * g0; acc[ai][bj][m][1] = acc[ai][bj][m][1] * g1; }
;                     else { const f32x4 v0 = acc[ai][bj][m][0] * g0, v1 = acc[ai][bj][m][1] * g1;
;                         u32x4 w; w.x = cvt_pk_bf16(v0[0], v0[1]); w.y = cvt_pk_bf16(v0[2], v0[3]); w.z = cvt_pk_bf16(v1[0], v1[1]); w.w = cvt_pk_bf16(v1[2], v1[3]);
;                         *(u32x4*)(O + (size_t)row * D_MODEL + col) = w; } } }
.LBB0_450:
	s_waitcnt vmcnt(6)
	v_lshlrev_b32_e32 v68, 16, v116
	v_and_b32_e32 v69, 0xffff0000, v116
	v_lshlrev_b32_e32 v70, 16, v117
	v_and_b32_e32 v71, 0xffff0000, v117
	v_lshlrev_b32_e32 v72, 16, v118
	v_and_b32_e32 v73, 0xffff0000, v118
	v_lshlrev_b32_e32 v74, 16, v119
	v_and_b32_e32 v75, 0xffff0000, v119
	v_pk_mul_f32 v[70:71], v[66:67], v[70:71]
	v_pk_mul_f32 v[68:69], v[64:65], v[68:69]
	v_pk_mul_f32 v[74:75], v[62:63], v[74:75]
	s_and_b64 vcc, exec, s[42:43]
	v_pk_mul_f32 v[72:73], v[60:61], v[72:73]
	s_cbranch_vccnz .LBB0_452
	v_cvt_pk_bf16_f32 v68, v68, v69
	v_cvt_pk_bf16_f32 v69, v70, v71
	v_cvt_pk_bf16_f32 v70, v72, v73
	v_cvt_pk_bf16_f32 v71, v74, v75
	v_lshl_add_u64 v[72:73], v[2:3], 1, v[194:195]
	global_store_dwordx4 v[72:73], v[68:71], off offset:256 sc1
	v_mov_b64_e32 v[74:75], v[62:63]
	v_mov_b64_e32 v[72:73], v[60:61]
	v_mov_b64_e32 v[70:71], v[66:67]
	v_mov_b64_e32 v[68:69], v[64:65]
.LBB0_452:
	v_ashrrev_i32_e32 v199, 31, v198
	v_lshlrev_b64 v[60:61], 12, v[198:199]
	s_waitcnt vmcnt(5)
	v_lshlrev_b32_e32 v62, 16, v112
	v_and_b32_e32 v63, 0xffff0000, v112
	v_lshlrev_b32_e32 v64, 16, v113
	v_and_b32_e32 v65, 0xffff0000, v113
	v_lshlrev_b32_e32 v66, 16, v114
	v_and_b32_e32 v67, 0xffff0000, v114
	v_lshlrev_b32_e32 v116, 16, v115
	v_and_b32_e32 v117, 0xffff0000, v115
	v_pk_mul_f32 v[114:115], v[50:51], v[64:65]
	v_pk_mul_f32 v[112:113], v[48:49], v[62:63]
	v_pk_mul_f32 v[118:119], v[46:47], v[116:117]
	v_pk_mul_f32 v[116:117], v[44:45], v[66:67]
	s_and_b64 vcc, exec, s[42:43]
	v_lshl_add_u64 v[60:61], s[14:15], 0, v[60:61]
	s_cbranch_vccnz .LBB0_454
	v_cvt_pk_bf16_f32 v62, v112, v113
	v_cvt_pk_bf16_f32 v63, v114, v115
	v_cvt_pk_bf16_f32 v64, v116, v117
	v_cvt_pk_bf16_f32 v65, v118, v119
	v_mov_b64_e32 v[118:119], v[46:47]
	v_mov_b64_e32 v[114:115], v[50:51]
	v_lshl_add_u64 v[66:67], v[2:3], 1, v[60:61]
	v_mov_b64_e32 v[116:117], v[44:45]
	v_mov_b64_e32 v[112:113], v[48:49]
	global_store_dwordx4 v[66:67], v[62:65], off sc1
.LBB0_454:
	s_waitcnt vmcnt(4)
	v_lshlrev_b32_e32 v44, 16, v156
	v_and_b32_e32 v45, 0xffff0000, v156
	v_lshlrev_b32_e32 v46, 16, v157
	v_and_b32_e32 v47, 0xffff0000, v157
	v_lshlrev_b32_e32 v48, 16, v158
	v_and_b32_e32 v49, 0xffff0000, v158
	v_lshlrev_b32_e32 v50, 16, v159
	v_and_b32_e32 v51, 0xffff0000, v159
	v_pk_mul_f32 v[46:47], v[42:43], v[46:47]
	v_pk_mul_f32 v[44:45], v[40:41], v[44:45]
	v_pk_mul_f32 v[50:51], v[38:39], v[50:51]
	s_and_b64 vcc, exec, s[42:43]
	v_pk_mul_f32 v[48:49], v[36:37], v[48:49]
	s_cbranch_vccnz .LBB0_456
	v_cvt_pk_bf16_f32 v44, v44, v45
	v_cvt_pk_bf16_f32 v45, v46, v47
	v_cvt_pk_bf16_f32 v46, v48, v49
	v_cvt_pk_bf16_f32 v47, v50, v51
	v_lshl_add_u64 v[48:49], v[2:3], 1, v[60:61]
	global_store_dwordx4 v[48:49], v[44:47], off offset:256 sc1
	v_mov_b64_e32 v[50:51], v[38:39]
	v_mov_b64_e32 v[48:49], v[36:37]
	v_mov_b64_e32 v[46:47], v[42:43]
	v_mov_b64_e32 v[44:45], v[40:41]
.LBB0_456:
	v_ashrrev_i32_e32 v197, 31, v196
	v_lshlrev_b64 v[36:37], 12, v[196:197]
	s_waitcnt vmcnt(3)
	v_lshlrev_b32_e32 v38, 16, v144
	v_and_b32_e32 v39, 0xffff0000, v144
	v_lshlrev_b32_e32 v40, 16, v145
	v_and_b32_e32 v41, 0xffff0000, v145
	v_lshlrev_b32_e32 v42, 16, v146
	v_and_b32_e32 v43, 0xffff0000, v146
	v_lshlrev_b32_e32 v60, 16, v147
	v_and_b32_e32 v61, 0xffff0000, v147
	v_pk_mul_f32 v[146:147], v[34:35], v[40:41]
	v_pk_mul_f32 v[144:145], v[32:33], v[38:39]
	v_pk_mul_f32 v[158:159], v[30:31], v[60:61]
	v_pk_mul_f32 v[156:157], v[28:29], v[42:43]
	s_and_b64 vcc, exec, s[42:43]
	v_lshl_add_u64 v[36:37], s[14:15], 0, v[36:37]
	s_cbranch_vccnz .LBB0_458
	v_cvt_pk_bf16_f32 v38, v144, v145
	v_cvt_pk_bf16_f32 v39, v146, v147
	v_cvt_pk_bf16_f32 v40, v156, v157
	v_cvt_pk_bf16_f32 v41, v158, v159
	v_mov_b64_e32 v[158:159], v[30:31]
	v_mov_b64_e32 v[146:147], v[34:35]
	v_lshl_add_u64 v[42:43], v[2:3], 1, v[36:37]
	v_mov_b64_e32 v[156:157], v[28:29]
	v_mov_b64_e32 v[144:145], v[32:33]
	global_store_dwordx4 v[42:43], v[38:41], off sc1
.LBB0_458:
	s_waitcnt vmcnt(2)
	v_lshlrev_b32_e32 v28, 16, v164
	v_and_b32_e32 v29, 0xffff0000, v164
	v_lshlrev_b32_e32 v30, 16, v165
	v_and_b32_e32 v31, 0xffff0000, v165
	v_lshlrev_b32_e32 v32, 16, v166
	v_and_b32_e32 v33, 0xffff0000, v166
	v_lshlrev_b32_e32 v34, 16, v167
	v_and_b32_e32 v35, 0xffff0000, v167
	v_pk_mul_f32 v[30:31], v[26:27], v[30:31]
	v_pk_mul_f32 v[28:29], v[24:25], v[28:29]
	v_pk_mul_f32 v[34:35], v[22:23], v[34:35]
	s_and_b64 vcc, exec, s[42:43]
	v_pk_mul_f32 v[32:33], v[20:21], v[32:33]
	s_cbranch_vccnz .LBB0_460
	v_cvt_pk_bf16_f32 v28, v28, v29
	v_cvt_pk_bf16_f32 v29, v30, v31
	v_cvt_pk_bf16_f32 v30, v32, v33
	v_cvt_pk_bf16_f32 v31, v34, v35
	v_lshl_add_u64 v[32:33], v[2:3], 1, v[36:37]
	global_store_dwordx4 v[32:33], v[28:31], off offset:256 sc1
	v_mov_b64_e32 v[34:35], v[22:23]
	v_mov_b64_e32 v[32:33], v[20:21]
	v_mov_b64_e32 v[30:31], v[26:27]
	v_mov_b64_e32 v[28:29], v[24:25]
.LBB0_460:
	v_ashrrev_i32_e32 v193, 31, v192
	v_lshlrev_b64 v[20:21], 12, v[192:193]
	s_waitcnt vmcnt(1)
	v_lshlrev_b32_e32 v22, 16, v160
	v_and_b32_e32 v23, 0xffff0000, v160
	v_lshlrev_b32_e32 v24, 16, v161
	v_and_b32_e32 v25, 0xffff0000, v161
	v_lshlrev_b32_e32 v26, 16, v162
	v_and_b32_e32 v27, 0xffff0000, v162
	v_lshlrev_b32_e32 v36, 16, v163
	v_and_b32_e32 v37, 0xffff0000, v163
	v_pk_mul_f32 v[162:163], v[18:19], v[24:25]
	v_pk_mul_f32 v[160:161], v[16:17], v[22:23]
	v_pk_mul_f32 v[166:167], v[14:15], v[36:37]
	v_pk_mul_f32 v[164:165], v[12:13], v[26:27]
	s_and_b64 vcc, exec, s[42:43]
	v_lshl_add_u64 v[20:21], s[14:15], 0, v[20:21]
	s_cbranch_vccnz .LBB0_462
	v_cvt_pk_bf16_f32 v22, v160, v161
	v_cvt_pk_bf16_f32 v23, v162, v163
	v_cvt_pk_bf16_f32 v24, v164, v165
	v_cvt_pk_bf16_f32 v25, v166, v167
	v_mov_b64_e32 v[166:167], v[14:15]
	v_mov_b64_e32 v[162:163], v[18:19]
	v_lshl_add_u64 v[26:27], v[2:3], 1, v[20:21]
	v_mov_b64_e32 v[164:165], v[12:13]
	v_mov_b64_e32 v[160:161], v[16:17]
	global_store_dwordx4 v[26:27], v[22:25], off sc1
.LBB0_462:
	s_waitcnt vmcnt(0)
	v_lshlrev_b32_e32 v12, 16, v140
	v_and_b32_e32 v13, 0xffff0000, v140
	v_lshlrev_b32_e32 v14, 16, v141
	v_and_b32_e32 v15, 0xffff0000, v141
	v_lshlrev_b32_e32 v16, 16, v142
	v_and_b32_e32 v17, 0xffff0000, v142
	v_lshlrev_b32_e32 v18, 16, v143
	v_and_b32_e32 v19, 0xffff0000, v143
	v_pk_mul_f32 v[14:15], v[10:11], v[14:15]
	v_pk_mul_f32 v[12:13], v[8:9], v[12:13]
	v_pk_mul_f32 v[18:19], v[6:7], v[18:19]
	s_and_b64 vcc, exec, s[42:43]
	v_pk_mul_f32 v[16:17], v[4:5], v[16:17]
	s_cbranch_vccnz .LBB0_464
	v_cvt_pk_bf16_f32 v12, v12, v13
	v_cvt_pk_bf16_f32 v13, v14, v15
	v_cvt_pk_bf16_f32 v14, v16, v17
	v_cvt_pk_bf16_f32 v15, v18, v19
	v_lshl_add_u64 v[2:3], v[2:3], 1, v[20:21]
	global_store_dwordx4 v[2:3], v[12:15], off offset:256 sc1
	v_mov_b64_e32 v[18:19], v[6:7]
	v_mov_b64_e32 v[16:17], v[4:5]
	v_mov_b64_e32 v[14:15], v[10:11]
	v_mov_b64_e32 v[12:13], v[8:9]

; __device__ __forceinline__ unsigned cvt_pk_bf16(float lo, float hi) { unsigned r; asm volatile("v_cvt_pk_bf16_f32 %0, %1, %2" : "=v"(r) : "v"(lo), "v"(hi)); return r; }
; __device__ __forceinline__ float bf_lo(unsigned w) { return __uint_as_float(w << 16); }
; __device__ __forceinline__ float bf_hi(unsigned w) { return __uint_as_float(w & 0xffff0000u); }
;     __device__ __forceinline__ void operator()(const f32x4 (&acc)[2][2][4][2], const Unit& u, int wr, int wc, int fr, int fq) const {
;     ...
; #pragma unroll
;         for (int ai = 0; ai < 2; ++ai) {
;             u32x4 xw[4][2];
; #pragma unroll
;             for (int m = 0; m < 4; ++m)
; #pragma unroll
;                 for (int bj = 0; bj < 2; ++bj) xw[m][bj] = *(const u32x4*)(XB + (size_t)(row0 + ai * HALF + m * 16) * D_MODEL + col0 + bj * HALF);
; #pragma unroll
;             for (int m = 0; m < 4; ++m) { const int row = row0 + ai * HALF + m * 16; float ss = 0.f;
; #pragma unroll
;                 for (int bj = 0; bj < 2; ++bj) { const size_t o = (size_t)row * D_MODEL + col0 + bj * HALF; const u32x4 t = xw[m][bj];
;                     f32x4 v0, v1; v0[0] = bf_lo(t.x); v0[1] = bf_hi(t.x); v0[2] = bf_lo(t.y); v0[3] = bf_hi(t.y); v1[0] = bf_lo(t.z); v1[1] = bf_hi(t.z); v1[2] = bf_lo(t.w); v1[3] = bf_hi(t.w);
;                     v0 = v0 + acc[ai][bj][m][0]; v1 = v1 + acc[ai][bj][m][1];
;                     if (aux) { u32x4 w; w.x = cvt_pk_bf16(v0[0], v0[1]); w.y = cvt_pk_bf16(v0[2], v0[3]); w.z = cvt_pk_bf16(v1[0], v1[1]); w.w = cvt_pk_bf16(v1[2], v1[3]);
;                         *(u32x4*)(XB + o) = w;
;                         ss += (v0[0] * v0[0] + v0[1] * v0[1]) + (v0[2] * v0[2] + v0[3] * v0[3]) + (v1[0] * v1[0] + v1[1] * v1[1]) + (v1[2] * v1[2] + v1[3] * v1[3]); }
;                     else { *(f32x4*)(Xout + o) = v0; *(f32x4*)(Xout + o + 4) = v1; } }
;                 if (aux) { ss += __shfl_xor(ss, 16); ss += __shfl_xor(ss, 32); if (fq == 0) red[(ai * HALF + wr * 64 + m * 16 + fr) * 4 + wc] = ss; } } }
.LBB0_556:
	s_lshl_b32 s38, s19, 8
	v_lshl_or_b32 v166, s18, 8, v192
	v_add_u32_e32 v182, s38, v190
	v_ashrrev_i32_e32 v167, 31, v166
	v_lshlrev_b64 v[218:219], 1, v[166:167]
	v_ashrrev_i32_e32 v183, 31, v182
	v_lshl_add_u64 v[180:181], s[56:57], 0, v[218:219]
	v_lshlrev_b64 v[220:221], 12, v[182:183]
	v_lshl_add_u64 v[114:115], v[180:181], 0, v[220:221]
	global_load_dwordx4 v[196:199], v[114:115], off
	global_load_dwordx4 v[200:203], v[114:115], off offset:256
	v_or_b32_e32 v114, 16, v182
	v_ashrrev_i32_e32 v115, 31, v114
	v_lshlrev_b64 v[188:189], 12, v[114:115]
	v_lshl_add_u64 v[114:115], v[180:181], 0, v[188:189]
	global_load_dwordx4 v[150:153], v[114:115], off
	global_load_dwordx4 v[146:149], v[114:115], off offset:256
	v_or_b32_e32 v114, 32, v182
	v_ashrrev_i32_e32 v115, 31, v114
	v_lshlrev_b64 v[186:187], 12, v[114:115]
	v_lshl_add_u64 v[114:115], v[180:181], 0, v[186:187]
	global_load_dwordx4 v[134:137], v[114:115], off
	global_load_dwordx4 v[122:125], v[114:115], off offset:256
	v_or_b32_e32 v114, 48, v182
	v_ashrrev_i32_e32 v115, 31, v114
	v_lshlrev_b64 v[184:185], 12, v[114:115]
	v_lshl_add_u64 v[114:115], v[180:181], 0, v[184:185]
	global_load_dwordx4 v[118:121], v[114:115], off
	s_nop 0
	global_load_dwordx4 v[114:117], v[114:115], off offset:256
	v_lshl_add_u64 v[220:221], s[56:57], 0, v[220:221]
	v_lshl_add_u64 v[218:219], v[220:221], 0, v[218:219]
	s_waitcnt vmcnt(0)
	v_lshlrev_b32_e32 v222, 16, v196
	v_and_b32_e32 v223, 0xffff0000, v196
	v_lshlrev_b32_e32 v196, 16, v197
	v_and_b32_e32 v197, 0xffff0000, v197
	v_lshlrev_b32_e32 v224, 16, v198
	v_and_b32_e32 v225, 0xffff0000, v198
	v_lshlrev_b32_e32 v198, 16, v199
	v_and_b32_e32 v199, 0xffff0000, v199
	v_pk_add_f32 v[144:145], v[144:145], v[196:197]
	v_pk_add_f32 v[142:143], v[142:143], v[222:223]
	v_pk_add_f32 v[196:197], v[140:141], v[198:199]
	v_pk_add_f32 v[198:199], v[138:139], v[224:225]
	v_cvt_pk_bf16_f32 v138, v142, v143
	v_cvt_pk_bf16_f32 v139, v144, v145
	s_nop 0
	v_cvt_pk_bf16_f32 v140, v198, v199
	v_cvt_pk_bf16_f32 v141, v196, v197
	global_store_dwordx4 v[218:219], v[138:141], off sc1
	s_nop 1
	v_mul_f32_e32 v138, v143, v143
	v_mul_f32_e32 v139, v145, v145
	v_fmac_f32_e32 v138, v142, v142
	v_fmac_f32_e32 v139, v144, v144
	v_add_f32_e32 v138, v138, v139
	v_mul_f32_e32 v139, v199, v199
	v_fmac_f32_e32 v139, v198, v198
	v_add_f32_e32 v138, v139, v138
	v_mul_f32_e32 v139, v197, v197
	v_fmac_f32_e32 v139, v196, v196
	v_add_f32_e32 v196, v139, v138
	v_lshlrev_b32_e32 v138, 16, v200
	v_and_b32_e32 v139, 0xffff0000, v200
	v_lshlrev_b32_e32 v140, 16, v201
	v_and_b32_e32 v141, 0xffff0000, v201
	v_lshlrev_b32_e32 v142, 16, v202
	v_and_b32_e32 v143, 0xffff0000, v202
	v_lshlrev_b32_e32 v144, 16, v203
	v_and_b32_e32 v145, 0xffff0000, v203
	v_pk_add_f32 v[132:133], v[132:133], v[140:141]
	v_pk_add_f32 v[130:131], v[130:131], v[138:139]
	v_pk_add_f32 v[140:141], v[126:127], v[142:143]
	v_cvt_pk_bf16_f32 v126, v130, v131
	v_cvt_pk_bf16_f32 v127, v132, v133
	v_pk_add_f32 v[138:139], v[128:129], v[144:145]
	v_cvt_pk_bf16_f32 v128, v140, v141
	s_nop 0
	v_cvt_pk_bf16_f32 v129, v138, v139
	global_store_dwordx4 v[218:219], v[126:129], off offset:256 sc1
	s_nop 1
	v_mul_f32_e32 v126, v131, v131
	v_mul_f32_e32 v127, v133, v133
	v_fmac_f32_e32 v126, v130, v130
	v_fmac_f32_e32 v127, v132, v132
	v_add_f32_e32 v126, v126, v127
	v_mul_f32_e32 v127, v141, v141
	v_fmac_f32_e32 v127, v140, v140
	v_add_f32_e32 v126, v127, v126
	v_mul_f32_e32 v127, v139, v139
	v_fmac_f32_e32 v127, v138, v138
	v_add_f32_e32 v126, v127, v126
	v_and_b32_e32 v128, 64, v211
	v_add_f32_e32 v127, v196, v126
	v_xor_b32_e32 v126, 16, v211
	v_add_u32_e32 v129, 64, v128
	v_cmp_lt_i32_e32 vcc, v126, v129
	s_nop 1
	v_cndmask_b32_e32 v126, v211, v126, vcc
	v_lshlrev_b32_e32 v126, 2, v126
	ds_bpermute_b32 v128, v126, v127
	s_waitcnt lgkmcnt(0)
	v_add_f32_e32 v128, v127, v128
	v_xor_b32_e32 v127, 32, v211
	v_cmp_lt_i32_e32 vcc, v127, v129
	s_nop 1
	v_cndmask_b32_e32 v127, v211, v127, vcc
	v_lshlrev_b32_e32 v127, 2, v127
	ds_bpermute_b32 v129, v127, v128
	s_and_saveexec_b64 s[16:17], s[40:41]
	s_cbranch_execz .LBB0_558
	s_waitcnt lgkmcnt(0)
	v_add_f32_e32 v128, v128, v129
	ds_write_b32 v193, v128
.LBB0_558:
	s_or_b64 exec, exec, s[16:17]
	v_lshlrev_b32_e32 v128, 16, v150
	s_waitcnt lgkmcnt(0)
	v_and_b32_e32 v129, 0xffff0000, v150
	v_lshlrev_b32_e32 v130, 16, v151
	v_and_b32_e32 v131, 0xffff0000, v151
	v_lshlrev_b32_e32 v132, 16, v152
	v_and_b32_e32 v133, 0xffff0000, v152
	v_pk_add_f32 v[110:111], v[110:111], v[128:129]
	v_pk_add_f32 v[112:113], v[112:113], v[130:131]
	v_pk_add_f32 v[130:131], v[106:107], v[132:133]
	v_cvt_pk_bf16_f32 v106, v110, v111
	v_mul_f32_e32 v111, v111, v111
	v_fmac_f32_e32 v111, v110, v110
	v_mul_f32_e32 v110, v113, v113
	v_fmac_f32_e32 v110, v112, v112
	v_lshlrev_b32_e32 v138, 16, v153
	v_and_b32_e32 v139, 0xffff0000, v153
	v_add_f32_e32 v110, v111, v110
	v_mul_f32_e32 v111, v131, v131
	v_pk_add_f32 v[128:129], v[108:109], v[138:139]
	v_fmac_f32_e32 v111, v130, v130
	v_add_f32_e32 v110, v111, v110
	v_mul_f32_e32 v111, v129, v129
	v_fmac_f32_e32 v111, v128, v128
	v_cvt_pk_bf16_f32 v107, v112, v113
	v_add_f32_e32 v132, v111, v110
	v_lshlrev_b32_e32 v110, 16, v146
	v_and_b32_e32 v111, 0xffff0000, v146
	v_lshlrev_b32_e32 v112, 16, v147
	v_and_b32_e32 v113, 0xffff0000, v147
	v_cvt_pk_bf16_f32 v108, v130, v131
	v_cvt_pk_bf16_f32 v109, v128, v129
	v_lshlrev_b32_e32 v128, 16, v148
	v_and_b32_e32 v129, 0xffff0000, v148
	v_pk_add_f32 v[104:105], v[104:105], v[112:113]
	v_pk_add_f32 v[102:103], v[102:103], v[110:111]
	v_pk_add_f32 v[112:113], v[98:99], v[128:129]
	v_mul_f32_e32 v98, v103, v103
	v_mul_f32_e32 v99, v105, v105
	v_fmac_f32_e32 v98, v102, v102
	v_fmac_f32_e32 v99, v104, v104
	v_lshlrev_b32_e32 v130, 16, v149
	v_and_b32_e32 v131, 0xffff0000, v149
	v_add_f32_e32 v98, v98, v99
	v_mul_f32_e32 v99, v113, v113
	v_pk_add_f32 v[110:111], v[100:101], v[130:131]
	v_fmac_f32_e32 v99, v112, v112
	v_add_f32_e32 v98, v99, v98
	v_mul_f32_e32 v99, v111, v111
	v_fmac_f32_e32 v99, v110, v110
	v_add_f32_e32 v98, v99, v98
	v_add_f32_e32 v101, v132, v98
	ds_bpermute_b32 v130, v126, v101
	v_lshl_add_u64 v[98:99], s[56:57], 0, v[188:189]
	v_lshl_add_u64 v[128:129], v[166:167], 1, v[98:99]
	global_store_dwordx4 v[128:129], v[106:109], off sc1
	v_cvt_pk_bf16_f32 v100, v102, v103
	s_waitcnt lgkmcnt(0)
	v_add_f32_e32 v98, v101, v130
	ds_bpermute_b32 v99, v127, v98
	v_cvt_pk_bf16_f32 v101, v104, v105
	v_cvt_pk_bf16_f32 v102, v112, v113
	v_cvt_pk_bf16_f32 v103, v110, v111
	global_store_dwordx4 v[128:129], v[100:103], off offset:256 sc1
	s_and_saveexec_b64 s[16:17], s[40:41]
	s_cbranch_execz .LBB0_560
	s_waitcnt lgkmcnt(0)
	v_add_f32_e32 v98, v98, v99
	ds_write_b32 v193, v98 offset:256
; __device__ __forceinline__ unsigned cvt_pk_bf16(float lo, float hi) { unsigned r; asm volatile("v_cvt_pk_bf16_f32 %0, %1, %2" : "=v"(r) : "v"(lo), "v"(hi)); return r; }
; __device__ __forceinline__ float bf_lo(unsigned w) { return __uint_as_float(w << 16); }
; __device__ __forceinline__ float bf_hi(unsigned w) { return __uint_as_float(w & 0xffff0000u); }
;     __device__ __forceinline__ void operator()(const f32x4 (&acc)[2][2][4][2], const Unit& u, int wr, int wc, int fr, int fq) const {
;     ...
; #pragma unroll
;         for (int ai = 0; ai < 2; ++ai) {
;             u32x4 xw[4][2];
; #pragma unroll
;             for (int m = 0; m < 4; ++m)
; #pragma unroll
;                 for (int bj = 0; bj < 2; ++bj) xw[m][bj] = *(const u32x4*)(XB + (size_t)(row0 + ai * HALF + m * 16) * D_MODEL + col0 + bj * HALF);
; #pragma unroll
;             for (int m = 0; m < 4; ++m) { const int row = row0 + ai * HALF + m * 16; float ss = 0.f;
; #pragma unroll
;                 for (int bj = 0; bj < 2; ++bj) { const size_t o = (size_t)row * D_MODEL + col0 + bj * HALF; const u32x4 t = xw[m][bj];
;                     f32x4 v0, v1; v0[0] = bf_lo(t.x); v0[1] = bf_hi(t.x); v0[2] = bf_lo(t.y); v0[3] = bf_hi(t.y); v1[0] = bf_lo(t.z); v1[1] = bf_hi(t.z); v1[2] = bf_lo(t.w); v1[3] = bf_hi(t.w);
;                     v0 = v0 + acc[ai][bj][m][0]; v1 = v1 + acc[ai][bj][m][1];
;                     if (aux) { u32x4 w; w.x = cvt_pk_bf16(v0[0], v0[1]); w.y = cvt_pk_bf16(v0[2], v0[3]); w.z = cvt_pk_bf16(v1[0], v1[1]); w.w = cvt_pk_bf16(v1[2], v1[3]);
;                         *(u32x4*)(XB + o) = w;
;                         ss += (v0[0] * v0[0] + v0[1] * v0[1]) + (v0[2] * v0[2] + v0[3] * v0[3]) + (v1[0] * v1[0] + v1[1] * v1[1]) + (v1[2] * v1[2] + v1[3] * v1[3]); }
;                     else { *(f32x4*)(Xout + o) = v0; *(f32x4*)(Xout + o + 4) = v1; } }
;                 if (aux) { ss += __shfl_xor(ss, 16); ss += __shfl_xor(ss, 32); if (fq == 0) red[(ai * HALF + wr * 64 + m * 16 + fr) * 4 + wc] = ss; } } }
.LBB0_560:
	s_or_b64 exec, exec, s[16:17]
	v_lshlrev_b32_e32 v98, 16, v134
	s_waitcnt lgkmcnt(0)
	v_and_b32_e32 v99, 0xffff0000, v134
	v_lshlrev_b32_e32 v100, 16, v135
	v_and_b32_e32 v101, 0xffff0000, v135
	v_lshlrev_b32_e32 v102, 16, v136
	v_and_b32_e32 v103, 0xffff0000, v136
	v_pk_add_f32 v[94:95], v[94:95], v[98:99]
	v_pk_add_f32 v[96:97], v[96:97], v[100:101]
	v_pk_add_f32 v[100:101], v[90:91], v[102:103]
	v_cvt_pk_bf16_f32 v90, v94, v95
	v_mul_f32_e32 v95, v95, v95
	v_fmac_f32_e32 v95, v94, v94
	v_mul_f32_e32 v94, v97, v97
	v_fmac_f32_e32 v94, v96, v96
	v_lshlrev_b32_e32 v104, 16, v137
	v_and_b32_e32 v105, 0xffff0000, v137
	v_add_f32_e32 v94, v95, v94
	v_mul_f32_e32 v95, v101, v101
	v_pk_add_f32 v[98:99], v[92:93], v[104:105]
	v_fmac_f32_e32 v95, v100, v100
	v_add_f32_e32 v94, v95, v94
	v_mul_f32_e32 v95, v99, v99
	v_fmac_f32_e32 v95, v98, v98
	v_cvt_pk_bf16_f32 v91, v96, v97
	v_add_f32_e32 v102, v95, v94
	v_lshlrev_b32_e32 v94, 16, v122
	v_and_b32_e32 v95, 0xffff0000, v122
	v_lshlrev_b32_e32 v96, 16, v123
	v_and_b32_e32 v97, 0xffff0000, v123
	v_cvt_pk_bf16_f32 v92, v100, v101
	v_cvt_pk_bf16_f32 v93, v98, v99
	v_lshlrev_b32_e32 v98, 16, v124
	v_and_b32_e32 v99, 0xffff0000, v124
	v_pk_add_f32 v[88:89], v[88:89], v[96:97]
	v_pk_add_f32 v[86:87], v[86:87], v[94:95]
	v_pk_add_f32 v[96:97], v[82:83], v[98:99]
	v_mul_f32_e32 v82, v87, v87
	v_mul_f32_e32 v83, v89, v89
	v_fmac_f32_e32 v82, v86, v86
	v_fmac_f32_e32 v83, v88, v88
	v_lshlrev_b32_e32 v100, 16, v125
	v_and_b32_e32 v101, 0xffff0000, v125
	v_add_f32_e32 v82, v82, v83
	v_mul_f32_e32 v83, v97, v97
	v_pk_add_f32 v[94:95], v[84:85], v[100:101]
	v_fmac_f32_e32 v83, v96, v96
	v_add_f32_e32 v82, v83, v82
	v_mul_f32_e32 v83, v95, v95
	v_fmac_f32_e32 v83, v94, v94
	v_add_f32_e32 v82, v83, v82
	v_add_f32_e32 v85, v102, v82
	ds_bpermute_b32 v100, v126, v85
	v_lshl_add_u64 v[82:83], s[56:57], 0, v[186:187]
	v_lshl_add_u64 v[98:99], v[166:167], 1, v[82:83]
	global_store_dwordx4 v[98:99], v[90:93], off sc1
	v_cvt_pk_bf16_f32 v84, v86, v87
	s_waitcnt lgkmcnt(0)
	v_add_f32_e32 v82, v85, v100
	ds_bpermute_b32 v83, v127, v82
	v_cvt_pk_bf16_f32 v85, v88, v89
	v_cvt_pk_bf16_f32 v86, v96, v97
	v_cvt_pk_bf16_f32 v87, v94, v95
	global_store_dwordx4 v[98:99], v[84:87], off offset:256 sc1
	s_and_saveexec_b64 s[16:17], s[40:41]
	s_cbranch_execz .LBB0_562
	s_waitcnt lgkmcnt(0)
	v_add_f32_e32 v82, v82, v83
	ds_write_b32 v193, v82 offset:512
.LBB0_562:
	s_or_b64 exec, exec, s[16:17]
	v_lshlrev_b32_e32 v82, 16, v118
	s_waitcnt lgkmcnt(0)
	v_and_b32_e32 v83, 0xffff0000, v118
	v_lshlrev_b32_e32 v84, 16, v119
	v_and_b32_e32 v85, 0xffff0000, v119
	v_lshlrev_b32_e32 v86, 16, v120
	v_and_b32_e32 v87, 0xffff0000, v120
	v_pk_add_f32 v[78:79], v[78:79], v[82:83]
	v_pk_add_f32 v[80:81], v[80:81], v[84:85]
	v_pk_add_f32 v[84:85], v[74:75], v[86:87]
	v_cvt_pk_bf16_f32 v74, v78, v79
	v_mul_f32_e32 v79, v79, v79
	v_fmac_f32_e32 v79, v78, v78
	v_mul_f32_e32 v78, v81, v81
	v_fmac_f32_e32 v78, v80, v80
	v_lshlrev_b32_e32 v88, 16, v121
	v_and_b32_e32 v89, 0xffff0000, v121
	v_add_f32_e32 v78, v79, v78
	v_mul_f32_e32 v79, v85, v85
	v_pk_add_f32 v[82:83], v[76:77], v[88:89]
	v_fmac_f32_e32 v79, v84, v84
	v_add_f32_e32 v78, v79, v78
	v_mul_f32_e32 v79, v83, v83
	v_fmac_f32_e32 v79, v82, v82
	v_cvt_pk_bf16_f32 v75, v80, v81
	v_add_f32_e32 v86, v79, v78
	v_lshlrev_b32_e32 v78, 16, v114
	v_and_b32_e32 v79, 0xffff0000, v114
	v_lshlrev_b32_e32 v80, 16, v115
	v_and_b32_e32 v81, 0xffff0000, v115
	v_cvt_pk_bf16_f32 v76, v84, v85
	v_cvt_pk_bf16_f32 v77, v82, v83
	v_lshlrev_b32_e32 v82, 16, v116
	v_and_b32_e32 v83, 0xffff0000, v116
	v_pk_add_f32 v[72:73], v[72:73], v[80:81]
	v_pk_add_f32 v[70:71], v[70:71], v[78:79]
	v_pk_add_f32 v[80:81], v[66:67], v[82:83]
	v_mul_f32_e32 v66, v71, v71
	v_mul_f32_e32 v67, v73, v73
	v_fmac_f32_e32 v66, v70, v70
	v_fmac_f32_e32 v67, v72, v72
	v_lshlrev_b32_e32 v84, 16, v117
	v_and_b32_e32 v85, 0xffff0000, v117
	v_add_f32_e32 v66, v66, v67
	v_mul_f32_e32 v67, v81, v81
	v_pk_add_f32 v[78:79], v[68:69], v[84:85]
	v_fmac_f32_e32 v67, v80, v80
	v_add_f32_e32 v66, v67, v66
	v_mul_f32_e32 v67, v79, v79
	v_fmac_f32_e32 v67, v78, v78
	v_add_f32_e32 v66, v67, v66
	v_add_f32_e32 v69, v86, v66
	ds_bpermute_b32 v84, v126, v69
	v_lshl_add_u64 v[66:67], s[56:57], 0, v[184:185]
	v_lshl_add_u64 v[82:83], v[166:167], 1, v[66:67]
	global_store_dwordx4 v[82:83], v[74:77], off sc1
	v_cvt_pk_bf16_f32 v68, v70, v71
	s_waitcnt lgkmcnt(0)
	v_add_f32_e32 v66, v69, v84
	ds_bpermute_b32 v67, v127, v66
	v_cvt_pk_bf16_f32 v69, v72, v73
	v_cvt_pk_bf16_f32 v70, v80, v81
	v_cvt_pk_bf16_f32 v71, v78, v79
	global_store_dwordx4 v[82:83], v[68:71], off offset:256 sc1
	s_and_saveexec_b64 s[16:17], s[40:41]
	s_cbranch_execz .LBB0_564
	s_waitcnt lgkmcnt(0)
	v_add_f32_e32 v66, v66, v67
	ds_write_b32 v193, v66 offset:768
; __device__ __forceinline__ unsigned cvt_pk_bf16(float lo, float hi) { unsigned r; asm volatile("v_cvt_pk_bf16_f32 %0, %1, %2" : "=v"(r) : "v"(lo), "v"(hi)); return r; }
; __device__ __forceinline__ float bf_lo(unsigned w) { return __uint_as_float(w << 16); }
; __device__ __forceinline__ float bf_hi(unsigned w) { return __uint_as_float(w & 0xffff0000u); }
;     __device__ __forceinline__ void operator()(const f32x4 (&acc)[2][2][4][2], const Unit& u, int wr, int wc, int fr, int fq) const {
;     ...
; #pragma unroll
;         for (int ai = 0; ai < 2; ++ai) {
;             u32x4 xw[4][2];
; #pragma unroll
;             for (int m = 0; m < 4; ++m)
; #pragma unroll
;                 for (int bj = 0; bj < 2; ++bj) xw[m][bj] = *(const u32x4*)(XB + (size_t)(row0 + ai * HALF + m * 16) * D_MODEL + col0 + bj * HALF);
; #pragma unroll
;             for (int m = 0; m < 4; ++m) { const int row = row0 + ai * HALF + m * 16; float ss = 0.f;
; #pragma unroll
;                 for (int bj = 0; bj < 2; ++bj) { const size_t o = (size_t)row * D_MODEL + col0 + bj * HALF; const u32x4 t = xw[m][bj];
;                     f32x4 v0, v1; v0[0] = bf_lo(t.x); v0[1] = bf_hi(t.x); v0[2] = bf_lo(t.y); v0[3] = bf_hi(t.y); v1[0] = bf_lo(t.z); v1[1] = bf_hi(t.z); v1[2] = bf_lo(t.w); v1[3] = bf_hi(t.w);
;                     v0 = v0 + acc[ai][bj][m][0]; v1 = v1 + acc[ai][bj][m][1];
;                     if (aux) { u32x4 w; w.x = cvt_pk_bf16(v0[0], v0[1]); w.y = cvt_pk_bf16(v0[2], v0[3]); w.z = cvt_pk_bf16(v1[0], v1[1]); w.w = cvt_pk_bf16(v1[2], v1[3]);
;                         *(u32x4*)(XB + o) = w;
;                         ss += (v0[0] * v0[0] + v0[1] * v0[1]) + (v0[2] * v0[2] + v0[3] * v0[3]) + (v1[0] * v1[0] + v1[1] * v1[1]) + (v1[2] * v1[2] + v1[3] * v1[3]); }
;                     else { *(f32x4*)(Xout + o) = v0; *(f32x4*)(Xout + o + 4) = v1; } }
;                 if (aux) { ss += __shfl_xor(ss, 16); ss += __shfl_xor(ss, 32); if (fq == 0) red[(ai * HALF + wr * 64 + m * 16 + fr) * 4 + wc] = ss; } } }
.LBB0_564:
	s_or_b64 exec, exec, s[16:17]
	s_waitcnt lgkmcnt(0)
	v_lshlrev_b64 v[66:67], 12, v[182:183]
	s_mov_b64 s[16:17], 0x80000
	v_lshl_add_u64 v[104:105], v[66:67], 0, s[16:17]
	v_lshl_add_u64 v[68:69], v[180:181], 0, v[104:105]
	global_load_dwordx4 v[96:99], v[68:69], off
	global_load_dwordx4 v[100:103], v[68:69], off offset:256
	s_mov_b64 s[16:17], 0x90000
	v_lshl_add_u64 v[94:95], v[66:67], 0, s[16:17]
	s_mov_b64 s[16:17], 0xa0000
	v_lshl_add_u64 v[92:93], v[66:67], 0, s[16:17]
	s_mov_b64 s[16:17], 0xb0000
	v_lshl_add_u64 v[68:69], v[180:181], 0, v[94:95]
	v_lshl_add_u64 v[90:91], v[66:67], 0, s[16:17]
	global_load_dwordx4 v[86:89], v[68:69], off
	global_load_dwordx4 v[82:85], v[68:69], off offset:256
	v_lshl_add_u64 v[68:69], v[180:181], 0, v[92:93]
	v_lshl_add_u64 v[66:67], v[180:181], 0, v[90:91]
	global_load_dwordx4 v[78:81], v[68:69], off
	global_load_dwordx4 v[74:77], v[68:69], off offset:256
	global_load_dwordx4 v[70:73], v[66:67], off
	s_nop 0
	global_load_dwordx4 v[66:69], v[66:67], off offset:256
	v_lshl_add_u64 v[104:105], s[56:57], 0, v[104:105]
	v_lshl_add_u64 v[104:105], v[166:167], 1, v[104:105]
	s_waitcnt vmcnt(7)
	v_lshlrev_b32_e32 v106, 16, v96
	v_and_b32_e32 v107, 0xffff0000, v96
	v_lshlrev_b32_e32 v96, 16, v97
	v_and_b32_e32 v97, 0xffff0000, v97
	v_lshlrev_b32_e32 v108, 16, v98
	v_and_b32_e32 v109, 0xffff0000, v98
	v_lshlrev_b32_e32 v98, 16, v99
	v_and_b32_e32 v99, 0xffff0000, v99
	v_pk_add_f32 v[64:65], v[64:65], v[96:97]
	v_pk_add_f32 v[62:63], v[62:63], v[106:107]
	v_pk_add_f32 v[96:97], v[60:61], v[98:99]
	v_pk_add_f32 v[98:99], v[58:59], v[108:109]
	v_cvt_pk_bf16_f32 v58, v62, v63
	v_cvt_pk_bf16_f32 v59, v64, v65
	s_nop 0
	v_cvt_pk_bf16_f32 v60, v98, v99
	v_cvt_pk_bf16_f32 v61, v96, v97
	global_store_dwordx4 v[104:105], v[58:61], off sc1
	s_nop 1
	v_mul_f32_e32 v58, v63, v63
	v_mul_f32_e32 v59, v65, v65
	v_fmac_f32_e32 v58, v62, v62
	v_fmac_f32_e32 v59, v64, v64
	v_add_f32_e32 v58, v58, v59
	v_mul_f32_e32 v59, v99, v99
	v_fmac_f32_e32 v59, v98, v98
	v_add_f32_e32 v58, v59, v58
	v_mul_f32_e32 v59, v97, v97
	v_fmac_f32_e32 v59, v96, v96
	v_add_f32_e32 v96, v59, v58
	s_waitcnt vmcnt(7)
	v_lshlrev_b32_e32 v58, 16, v100
	v_and_b32_e32 v59, 0xffff0000, v100
	v_lshlrev_b32_e32 v60, 16, v101
	v_and_b32_e32 v61, 0xffff0000, v101
	v_lshlrev_b32_e32 v62, 16, v102
	v_and_b32_e32 v63, 0xffff0000, v102
	v_lshlrev_b32_e32 v64, 16, v103
	v_and_b32_e32 v65, 0xffff0000, v103
	v_pk_add_f32 v[56:57], v[56:57], v[60:61]
	v_pk_add_f32 v[54:55], v[54:55], v[58:59]
	v_pk_add_f32 v[60:61], v[50:51], v[62:63]
	v_cvt_pk_bf16_f32 v50, v54, v55
	v_cvt_pk_bf16_f32 v51, v56, v57
	v_pk_add_f32 v[58:59], v[52:53], v[64:65]
	v_cvt_pk_bf16_f32 v52, v60, v61
	s_nop 0
	v_cvt_pk_bf16_f32 v53, v58, v59
	global_store_dwordx4 v[104:105], v[50:53], off offset:256 sc1
	s_nop 1
	v_mul_f32_e32 v50, v55, v55
	v_mul_f32_e32 v51, v57, v57
	v_fmac_f32_e32 v50, v54, v54
	v_fmac_f32_e32 v51, v56, v56
	v_add_f32_e32 v50, v50, v51
	v_mul_f32_e32 v51, v61, v61
	v_fmac_f32_e32 v51, v60, v60
	v_add_f32_e32 v50, v51, v50
	v_mul_f32_e32 v51, v59, v59
	v_fmac_f32_e32 v51, v58, v58
	v_add_f32_e32 v50, v51, v50
	v_add_f32_e32 v50, v96, v50
	ds_bpermute_b32 v51, v126, v50
	s_waitcnt lgkmcnt(0)
	v_add_f32_e32 v50, v50, v51
	ds_bpermute_b32 v51, v127, v50
	s_and_saveexec_b64 s[16:17], s[40:41]
	s_cbranch_execz .LBB0_566
	s_waitcnt lgkmcnt(0)
	v_add_f32_e32 v50, v50, v51
	ds_write_b32 v193, v50 offset:2048
.LBB0_566:
	s_or_b64 exec, exec, s[16:17]
	s_waitcnt vmcnt(7)
	v_lshlrev_b32_e32 v50, 16, v86
	s_waitcnt lgkmcnt(0)
	v_and_b32_e32 v51, 0xffff0000, v86
	v_lshlrev_b32_e32 v52, 16, v87
	v_and_b32_e32 v53, 0xffff0000, v87
	v_lshlrev_b32_e32 v54, 16, v88
	v_and_b32_e32 v55, 0xffff0000, v88
	v_pk_add_f32 v[46:47], v[46:47], v[50:51]
	v_pk_add_f32 v[48:49], v[48:49], v[52:53]
	v_pk_add_f32 v[52:53], v[42:43], v[54:55]
	v_cvt_pk_bf16_f32 v42, v46, v47
	v_mul_f32_e32 v47, v47, v47
	v_fmac_f32_e32 v47, v46, v46
	v_mul_f32_e32 v46, v49, v49
	v_fmac_f32_e32 v46, v48, v48
	v_lshlrev_b32_e32 v56, 16, v89
	v_and_b32_e32 v57, 0xffff0000, v89
	v_add_f32_e32 v46, v47, v46
	v_mul_f32_e32 v47, v53, v53
	v_pk_add_f32 v[50:51], v[44:45], v[56:57]
	v_fmac_f32_e32 v47, v52, v52
	v_add_f32_e32 v46, v47, v46
	v_mul_f32_e32 v47, v51, v51
	v_fmac_f32_e32 v47, v50, v50
	v_cvt_pk_bf16_f32 v43, v48, v49
	v_add_f32_e32 v54, v47, v46
	s_waitcnt vmcnt(6)
	v_lshlrev_b32_e32 v46, 16, v82
	v_and_b32_e32 v47, 0xffff0000, v82
	v_lshlrev_b32_e32 v48, 16, v83
	v_and_b32_e32 v49, 0xffff0000, v83
	v_cvt_pk_bf16_f32 v44, v52, v53
	v_cvt_pk_bf16_f32 v45, v50, v51
	v_lshlrev_b32_e32 v50, 16, v84
	v_and_b32_e32 v51, 0xffff0000, v84
	v_pk_add_f32 v[40:41], v[40:41], v[48:49]
	v_pk_add_f32 v[38:39], v[38:39], v[46:47]
	v_pk_add_f32 v[48:49], v[34:35], v[50:51]
	v_mul_f32_e32 v34, v39, v39
	v_mul_f32_e32 v35, v41, v41
	v_fmac_f32_e32 v34, v38, v38
	v_fmac_f32_e32 v35, v40, v40
	v_lshlrev_b32_e32 v52, 16, v85
	v_and_b32_e32 v53, 0xffff0000, v85
	v_add_f32_e32 v34, v34, v35
	v_mul_f32_e32 v35, v49, v49
	v_pk_add_f32 v[46:47], v[36:37], v[52:53]
	v_fmac_f32_e32 v35, v48, v48
	v_add_f32_e32 v34, v35, v34
	v_mul_f32_e32 v35, v47, v47
	v_fmac_f32_e32 v35, v46, v46
	v_add_f32_e32 v34, v35, v34
	v_add_f32_e32 v37, v54, v34
	ds_bpermute_b32 v52, v126, v37
	v_lshl_add_u64 v[34:35], s[56:57], 0, v[94:95]
	v_lshl_add_u64 v[50:51], v[166:167], 1, v[34:35]
	global_store_dwordx4 v[50:51], v[42:45], off sc1
	v_cvt_pk_bf16_f32 v36, v38, v39
	s_waitcnt lgkmcnt(0)
	v_add_f32_e32 v34, v37, v52
	ds_bpermute_b32 v35, v127, v34
	v_cvt_pk_bf16_f32 v37, v40, v41
	v_cvt_pk_bf16_f32 v38, v48, v49
	v_cvt_pk_bf16_f32 v39, v46, v47
	global_store_dwordx4 v[50:51], v[36:39], off offset:256 sc1
	s_and_saveexec_b64 s[16:17], s[40:41]
	s_cbranch_execz .LBB0_568
	s_waitcnt lgkmcnt(0)
	v_add_f32_e32 v34, v34, v35
	ds_write_b32 v193, v34 offset:2304
; __device__ __forceinline__ unsigned cvt_pk_bf16(float lo, float hi) { unsigned r; asm volatile("v_cvt_pk_bf16_f32 %0, %1, %2" : "=v"(r) : "v"(lo), "v"(hi)); return r; }
; __device__ __forceinline__ float bf_lo(unsigned w) { return __uint_as_float(w << 16); }
; __device__ __forceinline__ float bf_hi(unsigned w) { return __uint_as_float(w & 0xffff0000u); }
;     __device__ __forceinline__ void operator()(const f32x4 (&acc)[2][2][4][2], const Unit& u, int wr, int wc, int fr, int fq) const {
;     ...
; #pragma unroll
;         for (int ai = 0; ai < 2; ++ai) {
;             u32x4 xw[4][2];
; #pragma unroll
;             for (int m = 0; m < 4; ++m)
; #pragma unroll
;                 for (int bj = 0; bj < 2; ++bj) xw[m][bj] = *(const u32x4*)(XB + (size_t)(row0 + ai * HALF + m * 16) * D_MODEL + col0 + bj * HALF);
; #pragma unroll
;             for (int m = 0; m < 4; ++m) { const int row = row0 + ai * HALF + m * 16; float ss = 0.f;
; #pragma unroll
;                 for (int bj = 0; bj < 2; ++bj) { const size_t o = (size_t)row * D_MODEL + col0 + bj * HALF; const u32x4 t = xw[m][bj];
;                     f32x4 v0, v1; v0[0] = bf_lo(t.x); v0[1] = bf_hi(t.x); v0[2] = bf_lo(t.y); v0[3] = bf_hi(t.y); v1[0] = bf_lo(t.z); v1[1] = bf_hi(t.z); v1[2] = bf_lo(t.w); v1[3] = bf_hi(t.w);
;                     v0 = v0 + acc[ai][bj][m][0]; v1 = v1 + acc[ai][bj][m][1];
;                     if (aux) { u32x4 w; w.x = cvt_pk_bf16(v0[0], v0[1]); w.y = cvt_pk_bf16(v0[2], v0[3]); w.z = cvt_pk_bf16(v1[0], v1[1]); w.w = cvt_pk_bf16(v1[2], v1[3]);
;                         *(u32x4*)(XB + o) = w;
;                         ss += (v0[0] * v0[0] + v0[1] * v0[1]) + (v0[2] * v0[2] + v0[3] * v0[3]) + (v1[0] * v1[0] + v1[1] * v1[1]) + (v1[2] * v1[2] + v1[3] * v1[3]); }
;                     else { *(f32x4*)(Xout + o) = v0; *(f32x4*)(Xout + o + 4) = v1; } }
;                 if (aux) { ss += __shfl_xor(ss, 16); ss += __shfl_xor(ss, 32); if (fq == 0) red[(ai * HALF + wr * 64 + m * 16 + fr) * 4 + wc] = ss; } } }
.LBB0_568:
	s_or_b64 exec, exec, s[16:17]
	s_waitcnt vmcnt(7)
	v_lshlrev_b32_e32 v34, 16, v78
	s_waitcnt lgkmcnt(0)
	v_and_b32_e32 v35, 0xffff0000, v78
	v_lshlrev_b32_e32 v36, 16, v79
	v_and_b32_e32 v37, 0xffff0000, v79
	v_lshlrev_b32_e32 v38, 16, v80
	v_and_b32_e32 v39, 0xffff0000, v80
	v_pk_add_f32 v[30:31], v[30:31], v[34:35]
	v_pk_add_f32 v[32:33], v[32:33], v[36:37]
	v_pk_add_f32 v[36:37], v[26:27], v[38:39]
	v_cvt_pk_bf16_f32 v26, v30, v31
	v_mul_f32_e32 v31, v31, v31
	v_fmac_f32_e32 v31, v30, v30
	v_mul_f32_e32 v30, v33, v33
	v_fmac_f32_e32 v30, v32, v32
	v_lshlrev_b32_e32 v40, 16, v81
	v_and_b32_e32 v41, 0xffff0000, v81
	v_add_f32_e32 v30, v31, v30
	v_mul_f32_e32 v31, v37, v37
	v_pk_add_f32 v[34:35], v[28:29], v[40:41]
	v_fmac_f32_e32 v31, v36, v36
	v_add_f32_e32 v30, v31, v30
	v_mul_f32_e32 v31, v35, v35
	v_fmac_f32_e32 v31, v34, v34
	v_cvt_pk_bf16_f32 v27, v32, v33
	v_add_f32_e32 v38, v31, v30
	s_waitcnt vmcnt(6)
	v_lshlrev_b32_e32 v30, 16, v74
	v_and_b32_e32 v31, 0xffff0000, v74
	v_lshlrev_b32_e32 v32, 16, v75
	v_and_b32_e32 v33, 0xffff0000, v75
	v_cvt_pk_bf16_f32 v28, v36, v37
	v_cvt_pk_bf16_f32 v29, v34, v35
	v_lshlrev_b32_e32 v34, 16, v76
	v_and_b32_e32 v35, 0xffff0000, v76
	v_pk_add_f32 v[24:25], v[24:25], v[32:33]
	v_pk_add_f32 v[22:23], v[22:23], v[30:31]
	v_pk_add_f32 v[32:33], v[18:19], v[34:35]
	v_mul_f32_e32 v18, v23, v23
	v_mul_f32_e32 v19, v25, v25
	v_fmac_f32_e32 v18, v22, v22
	v_fmac_f32_e32 v19, v24, v24
	v_lshlrev_b32_e32 v36, 16, v77
	v_and_b32_e32 v37, 0xffff0000, v77
	v_add_f32_e32 v18, v18, v19
	v_mul_f32_e32 v19, v33, v33
	v_pk_add_f32 v[30:31], v[20:21], v[36:37]
	v_fmac_f32_e32 v19, v32, v32
	v_add_f32_e32 v18, v19, v18
	v_mul_f32_e32 v19, v31, v31
	v_fmac_f32_e32 v19, v30, v30
	v_add_f32_e32 v18, v19, v18
	v_add_f32_e32 v21, v38, v18
	ds_bpermute_b32 v36, v126, v21
	v_lshl_add_u64 v[18:19], s[56:57], 0, v[92:93]
	v_lshl_add_u64 v[34:35], v[166:167], 1, v[18:19]
	global_store_dwordx4 v[34:35], v[26:29], off sc1
	v_cvt_pk_bf16_f32 v20, v22, v23
	s_waitcnt lgkmcnt(0)
	v_add_f32_e32 v18, v21, v36
	ds_bpermute_b32 v19, v127, v18
	v_cvt_pk_bf16_f32 v21, v24, v25
	v_cvt_pk_bf16_f32 v22, v32, v33
	v_cvt_pk_bf16_f32 v23, v30, v31
	global_store_dwordx4 v[34:35], v[20:23], off offset:256 sc1
	s_and_saveexec_b64 s[16:17], s[40:41]
	s_cbranch_execz .LBB0_570
	s_waitcnt lgkmcnt(0)
	v_add_f32_e32 v18, v18, v19
	ds_write_b32 v193, v18 offset:2560
.LBB0_570:
	s_or_b64 exec, exec, s[16:17]
	s_waitcnt vmcnt(7)
	v_lshlrev_b32_e32 v18, 16, v70
	s_waitcnt lgkmcnt(0)
	v_and_b32_e32 v19, 0xffff0000, v70
	v_lshlrev_b32_e32 v20, 16, v71
	v_and_b32_e32 v21, 0xffff0000, v71
	v_lshlrev_b32_e32 v22, 16, v72
	v_and_b32_e32 v23, 0xffff0000, v72
	v_pk_add_f32 v[14:15], v[14:15], v[18:19]
	v_pk_add_f32 v[16:17], v[16:17], v[20:21]
	v_pk_add_f32 v[20:21], v[10:11], v[22:23]
	v_cvt_pk_bf16_f32 v10, v14, v15
	v_mul_f32_e32 v15, v15, v15
	v_fmac_f32_e32 v15, v14, v14
	v_mul_f32_e32 v14, v17, v17
	v_fmac_f32_e32 v14, v16, v16
	v_lshlrev_b32_e32 v24, 16, v73
	v_and_b32_e32 v25, 0xffff0000, v73
	v_add_f32_e32 v14, v15, v14
	v_mul_f32_e32 v15, v21, v21
	v_pk_add_f32 v[18:19], v[12:13], v[24:25]
	v_fmac_f32_e32 v15, v20, v20
	v_add_f32_e32 v14, v15, v14
	v_mul_f32_e32 v15, v19, v19
	v_fmac_f32_e32 v15, v18, v18
	v_cvt_pk_bf16_f32 v11, v16, v17
	v_add_f32_e32 v22, v15, v14
	s_waitcnt vmcnt(6)
	v_lshlrev_b32_e32 v14, 16, v66
	v_and_b32_e32 v15, 0xffff0000, v66
	v_lshlrev_b32_e32 v16, 16, v67
	v_and_b32_e32 v17, 0xffff0000, v67
	v_cvt_pk_bf16_f32 v12, v20, v21
	v_cvt_pk_bf16_f32 v13, v18, v19
	v_lshlrev_b32_e32 v18, 16, v68
	v_and_b32_e32 v19, 0xffff0000, v68
	v_pk_add_f32 v[8:9], v[8:9], v[16:17]
	v_pk_add_f32 v[6:7], v[6:7], v[14:15]
	v_pk_add_f32 v[16:17], v[2:3], v[18:19]
	v_mul_f32_e32 v2, v7, v7
	v_mul_f32_e32 v3, v9, v9
	v_fmac_f32_e32 v2, v6, v6
	v_fmac_f32_e32 v3, v8, v8
	v_lshlrev_b32_e32 v20, 16, v69
	v_and_b32_e32 v21, 0xffff0000, v69
	v_add_f32_e32 v2, v2, v3
	v_mul_f32_e32 v3, v17, v17
	v_pk_add_f32 v[14:15], v[4:5], v[20:21]
	v_fmac_f32_e32 v3, v16, v16
	v_add_f32_e32 v2, v3, v2
	v_mul_f32_e32 v3, v15, v15
	v_fmac_f32_e32 v3, v14, v14
	v_add_f32_e32 v2, v3, v2
	v_add_f32_e32 v5, v22, v2
	ds_bpermute_b32 v20, v126, v5
	v_lshl_add_u64 v[2:3], s[56:57], 0, v[90:91]
	v_lshl_add_u64 v[18:19], v[166:167], 1, v[2:3]
	global_store_dwordx4 v[18:19], v[10:13], off sc1
	v_cvt_pk_bf16_f32 v4, v6, v7
	s_waitcnt lgkmcnt(0)
	v_add_f32_e32 v2, v5, v20
	ds_bpermute_b32 v3, v127, v2
	v_cvt_pk_bf16_f32 v5, v8, v9
	v_cvt_pk_bf16_f32 v6, v16, v17
	v_cvt_pk_bf16_f32 v7, v14, v15
	global_store_dwordx4 v[18:19], v[4:7], off offset:256 sc1
	s_and_saveexec_b64 s[16:17], s[40:41]
	s_cbranch_execz .LBB0_572
	s_waitcnt lgkmcnt(0)
	v_add_f32_e32 v2, v2, v3
	ds_write_b32 v193, v2 offset:2816

; __device__ __forceinline__ unsigned cvt_pk_bf16(float lo, float hi) { unsigned r; asm volatile("v_cvt_pk_bf16_f32 %0, %1, %2" : "=v"(r) : "v"(lo), "v"(hi)); return r; }
; __device__ __forceinline__ float sigmoid_f(float v) { return __builtin_amdgcn_rcpf(1.0f + __expf(-v)); }
;     __device__ __forceinline__ void operator()(const f32x4 (&acc)[2][2][4][2], const Unit& u, int wr, int wc, int fr, int fq) const {
;     ...
; #pragma unroll
;         for (int ai = 0; ai < 2; ++ai)
; #pragma unroll
;             for (int m = 0; m < 4; ++m) { const int row = row0 + ai * HALF + m * 16; const float r = rr[ai][m];
;                 float o[8];
; #pragma unroll
;                 for (int n = 0; n < 2; ++n)
; #pragma unroll
;                     for (int j = 0; j < 4; ++j) { const float g = acc[ai][0][m][n][j] * r, up = acc[ai][1][m][n][j] * r; o[4 * n + j] = g * sigmoid_f(g) * up; }
;                 u32x4 w; w.x = cvt_pk_bf16(o[0], o[1]); w.y = cvt_pk_bf16(o[2], o[3]); w.z = cvt_pk_bf16(o[4], o[5]); w.w = cvt_pk_bf16(o[6], o[7]);
;                 *(u32x4*)(O + (size_t)row * D_FF + col0) = w; }
.LBB0_666:
	v_mov_b32_e32 v154, v122
	v_mov_b32_e32 v155, v126
	v_pk_mul_f32 v[154:155], v[154:155], v[150:151] op_sel:[0,1]
	v_mov_b32_e32 v126, v123
	v_mul_f32_e32 v122, 0xbfb8aa3b, v155
	v_exp_f32_e32 v122, v122
	v_lshl_or_b32 v152, s51, 7, v161
	v_ashrrev_i32_e32 v153, 31, v152
	s_andn2_b64 vcc, exec, s[40:41]
	v_add_f32_e32 v122, 1.0, v122
	v_rcp_f32_e32 v122, v122
	s_nop 0
	v_mul_f32_e32 v122, v155, v122
	v_mul_f32_e32 v154, v154, v122
	v_pk_mul_f32 v[122:123], v[126:127], v[150:151] op_sel:[0,1]
	s_nop 0
	v_mul_f32_e32 v126, 0xbfb8aa3b, v123
	v_exp_f32_e32 v126, v126
	s_nop 0
	v_add_f32_e32 v126, 1.0, v126
	v_rcp_f32_e32 v126, v126
	s_nop 0
	v_mul_f32_e32 v123, v123, v126
	v_mul_f32_e32 v126, v122, v123
	v_mov_b32_e32 v122, v124
	v_mov_b32_e32 v123, v128
	v_pk_mul_f32 v[122:123], v[122:123], v[150:151] op_sel:[0,1]
	v_mov_b32_e32 v128, v125
	v_mul_f32_e32 v124, 0xbfb8aa3b, v123
	v_exp_f32_e32 v124, v124
	s_nop 0
	v_add_f32_e32 v124, 1.0, v124
	v_rcp_f32_e32 v124, v124
	s_nop 0
	v_mul_f32_e32 v123, v123, v124
	v_mul_f32_e32 v124, v122, v123
	v_pk_mul_f32 v[122:123], v[128:129], v[150:151] op_sel:[0,1]
	s_nop 0
	v_mul_f32_e32 v125, 0xbfb8aa3b, v123
	v_exp_f32_e32 v125, v125
	s_nop 0
	v_add_f32_e32 v125, 1.0, v125
	v_rcp_f32_e32 v125, v125
	s_nop 0
	v_mul_f32_e32 v123, v123, v125
	v_mul_f32_e32 v125, v122, v123
	v_mov_b32_e32 v122, v114
	v_mov_b32_e32 v123, v118
	v_pk_mul_f32 v[122:123], v[122:123], v[150:151] op_sel:[0,1]
	v_mov_b32_e32 v118, v115
	v_mul_f32_e32 v114, 0xbfb8aa3b, v123
	v_exp_f32_e32 v114, v114
	s_nop 0
	v_add_f32_e32 v114, 1.0, v114
	v_rcp_f32_e32 v114, v114
	s_nop 0
	v_mul_f32_e32 v114, v123, v114
	v_mul_f32_e32 v122, v122, v114
	v_pk_mul_f32 v[114:115], v[118:119], v[150:151] op_sel:[0,1]
	s_nop 0
	v_mul_f32_e32 v118, 0xbfb8aa3b, v115
	v_exp_f32_e32 v118, v118
	s_nop 0
	v_add_f32_e32 v118, 1.0, v118
	v_rcp_f32_e32 v118, v118
	s_nop 0
	v_mul_f32_e32 v115, v115, v118
	v_mul_f32_e32 v123, v114, v115
	v_mov_b32_e32 v114, v116
	v_mov_b32_e32 v115, v120
	v_pk_mul_f32 v[114:115], v[114:115], v[150:151] op_sel:[0,1]
	v_mov_b32_e32 v120, v117
	v_mul_f32_e32 v116, 0xbfb8aa3b, v115
	v_exp_f32_e32 v116, v116
	v_cvt_pk_bf16_f32 v118, v154, v126
	v_cvt_pk_bf16_f32 v119, v124, v125
	s_nop 0
	v_add_f32_e32 v116, 1.0, v116
	v_rcp_f32_e32 v116, v116
	s_nop 0
	v_mul_f32_e32 v115, v115, v116
	v_mul_f32_e32 v116, v114, v115
	v_pk_mul_f32 v[114:115], v[120:121], v[150:151] op_sel:[0,1]
	v_cvt_pk_bf16_f32 v120, v122, v123
	s_nop 0
	v_mul_f32_e32 v117, 0xbfb8aa3b, v115
	v_exp_f32_e32 v117, v117
	s_nop 0
	v_add_f32_e32 v117, 1.0, v117
	v_rcp_f32_e32 v117, v117
	s_nop 0
	v_mul_f32_e32 v115, v115, v117
	v_mul_f32_e32 v114, v114, v115
	v_cvt_pk_bf16_f32 v121, v116, v114
	v_mov_b64_e32 v[114:115], s[10:11]
	v_mad_u64_u32 v[122:123], s[16:17], v142, s76, v[114:115]
	v_mov_b32_e32 v116, v123
	v_mad_u64_u32 v[116:117], s[16:17], v143, s76, v[116:117]
	v_mov_b32_e32 v123, v116
	v_lshlrev_b64 v[116:117], 1, v[152:153]
	v_lshl_add_u64 v[122:123], v[122:123], 0, v[116:117]
	global_store_dwordx4 v[122:123], v[118:121], off sc1
	s_nop 1
	v_mov_b32_e32 v118, v106
	v_mov_b32_e32 v119, v110
	v_pk_mul_f32 v[118:119], v[118:119], v[150:151] op_sel_hi:[1,0]
	v_mov_b32_e32 v110, v107
	v_mul_f32_e32 v106, 0xbfb8aa3b, v119
	v_exp_f32_e32 v106, v106
	s_nop 0
	v_add_f32_e32 v106, 1.0, v106
	v_rcp_f32_e32 v106, v106
	s_nop 0
	v_mul_f32_e32 v106, v119, v106
	v_mul_f32_e32 v118, v118, v106
	v_pk_mul_f32 v[106:107], v[110:111], v[150:151] op_sel_hi:[1,0]
	s_nop 0
	v_mul_f32_e32 v110, 0xbfb8aa3b, v107
	v_exp_f32_e32 v110, v110
	s_nop 0
	v_add_f32_e32 v110, 1.0, v110
	v_rcp_f32_e32 v110, v110
	s_nop 0
	v_mul_f32_e32 v107, v107, v110
	v_mul_f32_e32 v110, v106, v107
	v_mov_b32_e32 v106, v108
	v_mov_b32_e32 v107, v112
	v_pk_mul_f32 v[106:107], v[106:107], v[150:151] op_sel_hi:[1,0]
	v_mov_b32_e32 v112, v109
	v_mul_f32_e32 v108, 0xbfb8aa3b, v107
	v_exp_f32_e32 v108, v108
	s_nop 0
	v_add_f32_e32 v108, 1.0, v108
	v_rcp_f32_e32 v108, v108
	s_nop 0
	v_mul_f32_e32 v107, v107, v108
	v_mul_f32_e32 v108, v106, v107
	v_pk_mul_f32 v[106:107], v[112:113], v[150:151] op_sel_hi:[1,0]
	s_nop 0
	v_mul_f32_e32 v109, 0xbfb8aa3b, v107
	v_exp_f32_e32 v109, v109
	s_nop 0
	v_add_f32_e32 v109, 1.0, v109
	v_rcp_f32_e32 v109, v109
	s_nop 0
	v_mul_f32_e32 v107, v107, v109
	v_mul_f32_e32 v109, v106, v107
	v_mov_b32_e32 v106, v98
	v_mov_b32_e32 v107, v102
	v_pk_mul_f32 v[106:107], v[106:107], v[150:151] op_sel_hi:[1,0]
	v_mov_b32_e32 v102, v99
	v_mul_f32_e32 v98, 0xbfb8aa3b, v107
	v_exp_f32_e32 v98, v98
	s_nop 0
	v_add_f32_e32 v98, 1.0, v98
	v_rcp_f32_e32 v98, v98
	s_nop 0
	v_mul_f32_e32 v98, v107, v98
	v_mul_f32_e32 v106, v106, v98
	v_pk_mul_f32 v[98:99], v[102:103], v[150:151] op_sel_hi:[1,0]
	s_nop 0
	v_mul_f32_e32 v102, 0xbfb8aa3b, v99
	v_exp_f32_e32 v102, v102
	s_nop 0
	v_add_f32_e32 v102, 1.0, v102
	v_rcp_f32_e32 v102, v102
	s_nop 0
	v_mul_f32_e32 v99, v99, v102
	v_mul_f32_e32 v102, v98, v99
	v_mov_b32_e32 v98, v100
	v_mov_b32_e32 v99, v104
	v_pk_mul_f32 v[98:99], v[98:99], v[150:151] op_sel_hi:[1,0]
	v_mov_b32_e32 v104, v101
	v_mul_f32_e32 v100, 0xbfb8aa3b, v99
	v_exp_f32_e32 v100, v100
	s_nop 0
	v_add_f32_e32 v100, 1.0, v100
	v_rcp_f32_e32 v100, v100
	s_nop 0
	v_mul_f32_e32 v99, v99, v100
	v_mul_f32_e32 v103, v98, v99
	v_pk_mul_f32 v[98:99], v[104:105], v[150:151] op_sel_hi:[1,0]
	v_or_b32_e32 v104, 16, v142
	v_mul_f32_e32 v100, 0xbfb8aa3b, v99
	v_exp_f32_e32 v100, v100
	s_nop 0
	v_add_f32_e32 v100, 1.0, v100
	v_rcp_f32_e32 v100, v100
	s_nop 0
	v_mul_f32_e32 v99, v99, v100
	v_mul_f32_e32 v101, v98, v99
	v_cvt_pk_bf16_f32 v98, v118, v110
	v_cvt_pk_bf16_f32 v99, v108, v109
; __device__ __forceinline__ unsigned cvt_pk_bf16(float lo, float hi) { unsigned r; asm volatile("v_cvt_pk_bf16_f32 %0, %1, %2" : "=v"(r) : "v"(lo), "v"(hi)); return r; }
; __device__ __forceinline__ float sigmoid_f(float v) { return __builtin_amdgcn_rcpf(1.0f + __expf(-v)); }
;     __device__ __forceinline__ void operator()(const f32x4 (&acc)[2][2][4][2], const Unit& u, int wr, int wc, int fr, int fq) const {
;     ...
; #pragma unroll
;         for (int ai = 0; ai < 2; ++ai)
; #pragma unroll
;             for (int m = 0; m < 4; ++m) { const int row = row0 + ai * HALF + m * 16; const float r = rr[ai][m];
;                 float o[8];
; #pragma unroll
;                 for (int n = 0; n < 2; ++n)
; #pragma unroll
;                     for (int j = 0; j < 4; ++j) { const float g = acc[ai][0][m][n][j] * r, up = acc[ai][1][m][n][j] * r; o[4 * n + j] = g * sigmoid_f(g) * up; }
;                 u32x4 w; w.x = cvt_pk_bf16(o[0], o[1]); w.y = cvt_pk_bf16(o[2], o[3]); w.z = cvt_pk_bf16(o[4], o[5]); w.w = cvt_pk_bf16(o[6], o[7]);
;                 *(u32x4*)(O + (size_t)row * D_FF + col0) = w; }
	v_cvt_pk_bf16_f32 v100, v106, v102
	v_cvt_pk_bf16_f32 v101, v103, v101
	v_mad_i64_i32 v[102:103], s[16:17], v104, s76, v[114:115]
	v_lshl_add_u64 v[102:103], v[102:103], 0, v[116:117]
	global_store_dwordx4 v[102:103], v[98:101], off sc1
	s_nop 1
	v_mov_b32_e32 v98, v90
	v_mov_b32_e32 v99, v94
	v_pk_mul_f32 v[98:99], v[98:99], v[148:149] op_sel:[0,1]
	v_mov_b32_e32 v94, v91
	v_mul_f32_e32 v90, 0xbfb8aa3b, v99
	v_exp_f32_e32 v90, v90
	s_nop 0
	v_add_f32_e32 v90, 1.0, v90
	v_rcp_f32_e32 v90, v90
	s_nop 0
	v_mul_f32_e32 v90, v99, v90
	v_mul_f32_e32 v98, v98, v90
	v_pk_mul_f32 v[90:91], v[94:95], v[148:149] op_sel:[0,1]
	s_nop 0
	v_mul_f32_e32 v94, 0xbfb8aa3b, v91
	v_exp_f32_e32 v94, v94
	s_nop 0
	v_add_f32_e32 v94, 1.0, v94
	v_rcp_f32_e32 v94, v94
	s_nop 0
	v_mul_f32_e32 v91, v91, v94
	v_mul_f32_e32 v94, v90, v91
	v_mov_b32_e32 v90, v92
	v_mov_b32_e32 v91, v96
	v_pk_mul_f32 v[90:91], v[90:91], v[148:149] op_sel:[0,1]
	v_mov_b32_e32 v96, v93
	v_mul_f32_e32 v92, 0xbfb8aa3b, v91
	v_exp_f32_e32 v92, v92
	s_nop 0
	v_add_f32_e32 v92, 1.0, v92
	v_rcp_f32_e32 v92, v92
	s_nop 0
	v_mul_f32_e32 v91, v91, v92
	v_mul_f32_e32 v92, v90, v91
	v_pk_mul_f32 v[90:91], v[96:97], v[148:149] op_sel:[0,1]
	s_nop 0
	v_mul_f32_e32 v93, 0xbfb8aa3b, v91
	v_exp_f32_e32 v93, v93
	s_nop 0
	v_add_f32_e32 v93, 1.0, v93
	v_rcp_f32_e32 v93, v93
	s_nop 0
	v_mul_f32_e32 v91, v91, v93
	v_mul_f32_e32 v93, v90, v91
	v_mov_b32_e32 v90, v82
	v_mov_b32_e32 v91, v86
	v_pk_mul_f32 v[90:91], v[90:91], v[148:149] op_sel:[0,1]
	v_mov_b32_e32 v86, v83
	v_mul_f32_e32 v82, 0xbfb8aa3b, v91
	v_exp_f32_e32 v82, v82
	s_nop 0
	v_add_f32_e32 v82, 1.0, v82
	v_rcp_f32_e32 v82, v82
	s_nop 0
	v_mul_f32_e32 v82, v91, v82
	v_mul_f32_e32 v90, v90, v82
	v_pk_mul_f32 v[82:83], v[86:87], v[148:149] op_sel:[0,1]
	s_nop 0
	v_mul_f32_e32 v86, 0xbfb8aa3b, v83
	v_exp_f32_e32 v86, v86
	s_nop 0
	v_add_f32_e32 v86, 1.0, v86
	v_rcp_f32_e32 v86, v86
	s_nop 0
	v_mul_f32_e32 v83, v83, v86
	v_mul_f32_e32 v86, v82, v83
	v_mov_b32_e32 v82, v84
	v_mov_b32_e32 v83, v88
	v_pk_mul_f32 v[82:83], v[82:83], v[148:149] op_sel:[0,1]
	v_mov_b32_e32 v88, v85
	v_mul_f32_e32 v84, 0xbfb8aa3b, v83
	v_exp_f32_e32 v84, v84
	s_nop 0
	v_add_f32_e32 v84, 1.0, v84
	v_rcp_f32_e32 v84, v84
	s_nop 0
	v_mul_f32_e32 v83, v83, v84
	v_mul_f32_e32 v87, v82, v83
	v_pk_mul_f32 v[82:83], v[88:89], v[148:149] op_sel:[0,1]
	v_or_b32_e32 v88, 32, v142
	v_mul_f32_e32 v84, 0xbfb8aa3b, v83
	v_exp_f32_e32 v84, v84
	s_nop 0
	v_add_f32_e32 v84, 1.0, v84
	v_rcp_f32_e32 v84, v84
	s_nop 0
	v_mul_f32_e32 v83, v83, v84
	v_mul_f32_e32 v85, v82, v83
	v_cvt_pk_bf16_f32 v82, v98, v94
	v_cvt_pk_bf16_f32 v83, v92, v93
	v_cvt_pk_bf16_f32 v84, v90, v86
	v_cvt_pk_bf16_f32 v85, v87, v85
	v_mad_i64_i32 v[86:87], s[16:17], v88, s76, v[114:115]
	v_lshl_add_u64 v[86:87], v[86:87], 0, v[116:117]
	global_store_dwordx4 v[86:87], v[82:85], off sc1
	s_nop 1
	v_mov_b32_e32 v82, v74
	v_mov_b32_e32 v83, v78
	v_pk_mul_f32 v[82:83], v[82:83], v[148:149] op_sel_hi:[1,0]
	v_mov_b32_e32 v78, v75
	v_mul_f32_e32 v74, 0xbfb8aa3b, v83
	v_exp_f32_e32 v74, v74
	s_nop 0
	v_add_f32_e32 v74, 1.0, v74
	v_rcp_f32_e32 v74, v74
	s_nop 0
	v_mul_f32_e32 v74, v83, v74
	v_mul_f32_e32 v82, v82, v74
	v_pk_mul_f32 v[74:75], v[78:79], v[148:149] op_sel_hi:[1,0]
	s_nop 0
	v_mul_f32_e32 v78, 0xbfb8aa3b, v75
	v_exp_f32_e32 v78, v78
	s_nop 0
	v_add_f32_e32 v78, 1.0, v78
	v_rcp_f32_e32 v78, v78
	s_nop 0
	v_mul_f32_e32 v75, v75, v78
	v_mul_f32_e32 v78, v74, v75
	v_mov_b32_e32 v74, v76
	v_mov_b32_e32 v75, v80
	v_pk_mul_f32 v[74:75], v[74:75], v[148:149] op_sel_hi:[1,0]
	v_mov_b32_e32 v80, v77
	v_mul_f32_e32 v76, 0xbfb8aa3b, v75
	v_exp_f32_e32 v76, v76
	s_nop 0
	v_add_f32_e32 v76, 1.0, v76
	v_rcp_f32_e32 v76, v76
	s_nop 0
	v_mul_f32_e32 v75, v75, v76
	v_mul_f32_e32 v76, v74, v75
	v_pk_mul_f32 v[74:75], v[80:81], v[148:149] op_sel_hi:[1,0]
	s_nop 0
	v_mul_f32_e32 v77, 0xbfb8aa3b, v75
	v_exp_f32_e32 v77, v77
	s_nop 0
	v_add_f32_e32 v77, 1.0, v77
	v_rcp_f32_e32 v77, v77
	s_nop 0
	v_mul_f32_e32 v75, v75, v77
	v_mul_f32_e32 v77, v74, v75
	v_mov_b32_e32 v74, v66
	v_mov_b32_e32 v75, v70
	v_pk_mul_f32 v[74:75], v[74:75], v[148:149] op_sel_hi:[1,0]
	v_mov_b32_e32 v70, v67
	v_mul_f32_e32 v66, 0xbfb8aa3b, v75
	v_exp_f32_e32 v66, v66
	s_nop 0
	v_add_f32_e32 v66, 1.0, v66
	v_rcp_f32_e32 v66, v66
	s_nop 0
	v_mul_f32_e32 v66, v75, v66
	v_mul_f32_e32 v74, v74, v66
	v_pk_mul_f32 v[66:67], v[70:71], v[148:149] op_sel_hi:[1,0]
	s_nop 0
	v_mul_f32_e32 v70, 0xbfb8aa3b, v67
	v_exp_f32_e32 v70, v70
	s_nop 0
	v_add_f32_e32 v70, 1.0, v70
	v_rcp_f32_e32 v70, v70
	s_nop 0
	v_mul_f32_e32 v67, v67, v70
	v_mul_f32_e32 v70, v66, v67
	v_mov_b32_e32 v66, v68
	v_mov_b32_e32 v67, v72
	v_pk_mul_f32 v[66:67], v[66:67], v[148:149] op_sel_hi:[1,0]
	v_mov_b32_e32 v72, v69
	v_mul_f32_e32 v68, 0xbfb8aa3b, v67
	v_exp_f32_e32 v68, v68
	s_nop 0
	v_add_f32_e32 v68, 1.0, v68
	v_rcp_f32_e32 v68, v68
	s_nop 0
	v_mul_f32_e32 v67, v67, v68
	v_mul_f32_e32 v71, v66, v67
	v_pk_mul_f32 v[66:67], v[72:73], v[148:149] op_sel_hi:[1,0]
	v_or_b32_e32 v72, 48, v142
	v_mul_f32_e32 v68, 0xbfb8aa3b, v67
	v_exp_f32_e32 v68, v68
	s_nop 0
	v_add_f32_e32 v68, 1.0, v68
	v_rcp_f32_e32 v68, v68
	s_nop 0
	v_mul_f32_e32 v67, v67, v68
	v_mul_f32_e32 v69, v66, v67
	v_cvt_pk_bf16_f32 v66, v82, v78
	v_cvt_pk_bf16_f32 v67, v76, v77
	v_cvt_pk_bf16_f32 v68, v74, v70
	v_cvt_pk_bf16_f32 v69, v71, v69
	v_mad_i64_i32 v[70:71], s[16:17], v72, s76, v[114:115]
	v_lshl_add_u64 v[70:71], v[70:71], 0, v[116:117]
	global_store_dwordx4 v[70:71], v[66:69], off sc1
	s_nop 1
	v_mov_b32_e32 v66, v58
	v_mov_b32_e32 v67, v62
	v_pk_mul_f32 v[66:67], v[66:67], v[146:147] op_sel:[0,1]
	v_mov_b32_e32 v62, v59
; __device__ __forceinline__ unsigned cvt_pk_bf16(float lo, float hi) { unsigned r; asm volatile("v_cvt_pk_bf16_f32 %0, %1, %2" : "=v"(r) : "v"(lo), "v"(hi)); return r; }
; __device__ __forceinline__ float sigmoid_f(float v) { return __builtin_amdgcn_rcpf(1.0f + __expf(-v)); }
;     __device__ __forceinline__ void operator()(const f32x4 (&acc)[2][2][4][2], const Unit& u, int wr, int wc, int fr, int fq) const {
;     ...
; #pragma unroll
;         for (int ai = 0; ai < 2; ++ai)
; #pragma unroll
;             for (int m = 0; m < 4; ++m) { const int row = row0 + ai * HALF + m * 16; const float r = rr[ai][m];
;                 float o[8];
; #pragma unroll
;                 for (int n = 0; n < 2; ++n)
; #pragma unroll
;                     for (int j = 0; j < 4; ++j) { const float g = acc[ai][0][m][n][j] * r, up = acc[ai][1][m][n][j] * r; o[4 * n + j] = g * sigmoid_f(g) * up; }
;                 u32x4 w; w.x = cvt_pk_bf16(o[0], o[1]); w.y = cvt_pk_bf16(o[2], o[3]); w.z = cvt_pk_bf16(o[4], o[5]); w.w = cvt_pk_bf16(o[6], o[7]);
;                 *(u32x4*)(O + (size_t)row * D_FF + col0) = w; }
	v_mul_f32_e32 v58, 0xbfb8aa3b, v67
	v_exp_f32_e32 v58, v58
	v_add_u32_e32 v68, 0x80, v142
	v_add_f32_e32 v58, 1.0, v58
	v_rcp_f32_e32 v58, v58
	s_nop 0
	v_mul_f32_e32 v58, v67, v58
	v_mul_f32_e32 v66, v66, v58
	v_pk_mul_f32 v[58:59], v[62:63], v[146:147] op_sel:[0,1]
	s_nop 0
	v_mul_f32_e32 v62, 0xbfb8aa3b, v59
	v_exp_f32_e32 v62, v62
	s_nop 0
	v_add_f32_e32 v62, 1.0, v62
	v_rcp_f32_e32 v62, v62
	s_nop 0
	v_mul_f32_e32 v59, v59, v62
	v_mul_f32_e32 v62, v58, v59
	v_mov_b32_e32 v58, v60
	v_mov_b32_e32 v59, v64
	v_pk_mul_f32 v[58:59], v[58:59], v[146:147] op_sel:[0,1]
	v_mov_b32_e32 v64, v61
	v_mul_f32_e32 v60, 0xbfb8aa3b, v59
	v_exp_f32_e32 v60, v60
	s_nop 0
	v_add_f32_e32 v60, 1.0, v60
	v_rcp_f32_e32 v60, v60
	s_nop 0
	v_mul_f32_e32 v59, v59, v60
	v_mul_f32_e32 v60, v58, v59
	v_pk_mul_f32 v[58:59], v[64:65], v[146:147] op_sel:[0,1]
	s_nop 0
	v_mul_f32_e32 v61, 0xbfb8aa3b, v59
	v_exp_f32_e32 v61, v61
	s_nop 0
	v_add_f32_e32 v61, 1.0, v61
	v_rcp_f32_e32 v61, v61
	s_nop 0
	v_mul_f32_e32 v59, v59, v61
	v_mul_f32_e32 v61, v58, v59
	v_mov_b32_e32 v58, v50
	v_mov_b32_e32 v59, v54
	v_pk_mul_f32 v[58:59], v[58:59], v[146:147] op_sel:[0,1]
	v_mov_b32_e32 v54, v51
	v_mul_f32_e32 v50, 0xbfb8aa3b, v59
	v_exp_f32_e32 v50, v50
	s_nop 0
	v_add_f32_e32 v50, 1.0, v50
	v_rcp_f32_e32 v50, v50
	s_nop 0
	v_mul_f32_e32 v50, v59, v50
	v_mul_f32_e32 v58, v58, v50
	v_pk_mul_f32 v[50:51], v[54:55], v[146:147] op_sel:[0,1]
	s_nop 0
	v_mul_f32_e32 v54, 0xbfb8aa3b, v51
	v_exp_f32_e32 v54, v54
	s_nop 0
	v_add_f32_e32 v54, 1.0, v54
	v_rcp_f32_e32 v54, v54
	s_nop 0
	v_mul_f32_e32 v51, v51, v54
	v_mul_f32_e32 v54, v50, v51
	v_mov_b32_e32 v50, v52
	v_mov_b32_e32 v51, v56
	v_pk_mul_f32 v[50:51], v[50:51], v[146:147] op_sel:[0,1]
	v_mov_b32_e32 v56, v53
	v_mul_f32_e32 v52, 0xbfb8aa3b, v51
	v_exp_f32_e32 v52, v52
	s_nop 0
	v_add_f32_e32 v52, 1.0, v52
	v_rcp_f32_e32 v52, v52
	s_nop 0
	v_mul_f32_e32 v51, v51, v52
	v_mul_f32_e32 v55, v50, v51
	v_pk_mul_f32 v[50:51], v[56:57], v[146:147] op_sel:[0,1]
	s_nop 0
	v_mul_f32_e32 v52, 0xbfb8aa3b, v51
	v_exp_f32_e32 v52, v52
	s_nop 0
	v_add_f32_e32 v52, 1.0, v52
	v_rcp_f32_e32 v52, v52
	s_nop 0
	v_mul_f32_e32 v51, v51, v52
	v_mul_f32_e32 v53, v50, v51
	v_cvt_pk_bf16_f32 v50, v66, v62
	v_cvt_pk_bf16_f32 v51, v60, v61
	v_cvt_pk_bf16_f32 v52, v58, v54
	v_cvt_pk_bf16_f32 v53, v55, v53
	v_mad_i64_i32 v[54:55], s[16:17], v68, s76, v[114:115]
	v_lshl_add_u64 v[54:55], v[54:55], 0, v[116:117]
	global_store_dwordx4 v[54:55], v[50:53], off sc1
	s_nop 1
	v_mov_b32_e32 v50, v42
	v_mov_b32_e32 v51, v46
	v_pk_mul_f32 v[50:51], v[50:51], v[146:147] op_sel_hi:[1,0]
	v_mov_b32_e32 v46, v43
	v_mul_f32_e32 v42, 0xbfb8aa3b, v51
	v_exp_f32_e32 v42, v42
	s_nop 0
	v_add_f32_e32 v42, 1.0, v42
	v_rcp_f32_e32 v42, v42
	s_nop 0
	v_mul_f32_e32 v42, v51, v42
	v_mul_f32_e32 v50, v50, v42
	v_pk_mul_f32 v[42:43], v[46:47], v[146:147] op_sel_hi:[1,0]
	s_nop 0
	v_mul_f32_e32 v46, 0xbfb8aa3b, v43
	v_exp_f32_e32 v46, v46
	s_nop 0
	v_add_f32_e32 v46, 1.0, v46
	v_rcp_f32_e32 v46, v46
	s_nop 0
	v_mul_f32_e32 v43, v43, v46
	v_mul_f32_e32 v46, v42, v43
	v_mov_b32_e32 v42, v44
	v_mov_b32_e32 v43, v48
	v_pk_mul_f32 v[42:43], v[42:43], v[146:147] op_sel_hi:[1,0]
	v_mov_b32_e32 v48, v45
	v_mul_f32_e32 v44, 0xbfb8aa3b, v43
	v_exp_f32_e32 v44, v44
	s_nop 0
	v_add_f32_e32 v44, 1.0, v44
	v_rcp_f32_e32 v44, v44
	s_nop 0
	v_mul_f32_e32 v43, v43, v44
	v_mul_f32_e32 v44, v42, v43
	v_pk_mul_f32 v[42:43], v[48:49], v[146:147] op_sel_hi:[1,0]
	s_nop 0
	v_mul_f32_e32 v45, 0xbfb8aa3b, v43
	v_exp_f32_e32 v45, v45
	s_nop 0
	v_add_f32_e32 v45, 1.0, v45
	v_rcp_f32_e32 v45, v45
	s_nop 0
	v_mul_f32_e32 v43, v43, v45
	v_mul_f32_e32 v45, v42, v43
	v_mov_b32_e32 v42, v34
	v_mov_b32_e32 v43, v38
	v_pk_mul_f32 v[42:43], v[42:43], v[146:147] op_sel_hi:[1,0]
	v_mov_b32_e32 v38, v35
	v_mul_f32_e32 v34, 0xbfb8aa3b, v43
	v_exp_f32_e32 v34, v34
	s_nop 0
	v_add_f32_e32 v34, 1.0, v34
	v_rcp_f32_e32 v34, v34
	s_nop 0
	v_mul_f32_e32 v34, v43, v34
	v_mul_f32_e32 v42, v42, v34
	v_pk_mul_f32 v[34:35], v[38:39], v[146:147] op_sel_hi:[1,0]
	s_nop 0
	v_mul_f32_e32 v38, 0xbfb8aa3b, v35
	v_exp_f32_e32 v38, v38
	s_nop 0
	v_add_f32_e32 v38, 1.0, v38
	v_rcp_f32_e32 v38, v38
	s_nop 0
	v_mul_f32_e32 v35, v35, v38
	v_mul_f32_e32 v38, v34, v35
	v_mov_b32_e32 v34, v36
	v_mov_b32_e32 v35, v40
	v_pk_mul_f32 v[34:35], v[34:35], v[146:147] op_sel_hi:[1,0]
	v_mov_b32_e32 v40, v37
	v_mul_f32_e32 v36, 0xbfb8aa3b, v35
	v_exp_f32_e32 v36, v36
	s_nop 0
	v_add_f32_e32 v36, 1.0, v36
	v_rcp_f32_e32 v36, v36
	s_nop 0
	v_mul_f32_e32 v35, v35, v36
	v_mul_f32_e32 v39, v34, v35
	v_pk_mul_f32 v[34:35], v[40:41], v[146:147] op_sel_hi:[1,0]
	v_add_u32_e32 v40, 0x90, v142
	v_mul_f32_e32 v36, 0xbfb8aa3b, v35
	v_exp_f32_e32 v36, v36
	s_nop 0
	v_add_f32_e32 v36, 1.0, v36
	v_rcp_f32_e32 v36, v36
	s_nop 0
	v_mul_f32_e32 v35, v35, v36
	v_mul_f32_e32 v37, v34, v35
	v_cvt_pk_bf16_f32 v34, v50, v46
	v_cvt_pk_bf16_f32 v35, v44, v45
	v_cvt_pk_bf16_f32 v36, v42, v38
	v_cvt_pk_bf16_f32 v37, v39, v37
	v_mad_i64_i32 v[38:39], s[16:17], v40, s76, v[114:115]
	v_lshl_add_u64 v[38:39], v[38:39], 0, v[116:117]
	global_store_dwordx4 v[38:39], v[34:37], off sc1
	s_nop 1
	v_mov_b32_e32 v34, v26
	v_mov_b32_e32 v35, v30
	v_pk_mul_f32 v[34:35], v[34:35], v[144:145] op_sel:[0,1]
; __device__ __forceinline__ unsigned cvt_pk_bf16(float lo, float hi) { unsigned r; asm volatile("v_cvt_pk_bf16_f32 %0, %1, %2" : "=v"(r) : "v"(lo), "v"(hi)); return r; }
; __device__ __forceinline__ float sigmoid_f(float v) { return __builtin_amdgcn_rcpf(1.0f + __expf(-v)); }
;     __device__ __forceinline__ void operator()(const f32x4 (&acc)[2][2][4][2], const Unit& u, int wr, int wc, int fr, int fq) const {
;     ...
; #pragma unroll
;         for (int ai = 0; ai < 2; ++ai)
; #pragma unroll
;             for (int m = 0; m < 4; ++m) { const int row = row0 + ai * HALF + m * 16; const float r = rr[ai][m];
;                 float o[8];
; #pragma unroll
;                 for (int n = 0; n < 2; ++n)
; #pragma unroll
;                     for (int j = 0; j < 4; ++j) { const float g = acc[ai][0][m][n][j] * r, up = acc[ai][1][m][n][j] * r; o[4 * n + j] = g * sigmoid_f(g) * up; }
;                 u32x4 w; w.x = cvt_pk_bf16(o[0], o[1]); w.y = cvt_pk_bf16(o[2], o[3]); w.z = cvt_pk_bf16(o[4], o[5]); w.w = cvt_pk_bf16(o[6], o[7]);
;                 *(u32x4*)(O + (size_t)row * D_FF + col0) = w; }
	v_mov_b32_e32 v30, v27
	v_mul_f32_e32 v26, 0xbfb8aa3b, v35
	v_exp_f32_e32 v26, v26
	s_nop 0
	v_add_f32_e32 v26, 1.0, v26
	v_rcp_f32_e32 v26, v26
	s_nop 0
	v_mul_f32_e32 v26, v35, v26
	v_mul_f32_e32 v34, v34, v26
	v_pk_mul_f32 v[26:27], v[30:31], v[144:145] op_sel:[0,1]
	s_nop 0
	v_mul_f32_e32 v30, 0xbfb8aa3b, v27
	v_exp_f32_e32 v30, v30
	s_nop 0
	v_add_f32_e32 v30, 1.0, v30
	v_rcp_f32_e32 v30, v30
	s_nop 0
	v_mul_f32_e32 v27, v27, v30
	v_mul_f32_e32 v30, v26, v27
	v_mov_b32_e32 v26, v28
	v_mov_b32_e32 v27, v32
	v_pk_mul_f32 v[26:27], v[26:27], v[144:145] op_sel:[0,1]
	v_mov_b32_e32 v32, v29
	v_mul_f32_e32 v28, 0xbfb8aa3b, v27
	v_exp_f32_e32 v28, v28
	s_nop 0
	v_add_f32_e32 v28, 1.0, v28
	v_rcp_f32_e32 v28, v28
	s_nop 0
	v_mul_f32_e32 v27, v27, v28
	v_mul_f32_e32 v28, v26, v27
	v_pk_mul_f32 v[26:27], v[32:33], v[144:145] op_sel:[0,1]
	s_nop 0
	v_mul_f32_e32 v29, 0xbfb8aa3b, v27
	v_exp_f32_e32 v29, v29
	s_nop 0
	v_add_f32_e32 v29, 1.0, v29
	v_rcp_f32_e32 v29, v29
	s_nop 0
	v_mul_f32_e32 v27, v27, v29
	v_mul_f32_e32 v29, v26, v27
	v_mov_b32_e32 v26, v18
	v_mov_b32_e32 v27, v22
	v_pk_mul_f32 v[26:27], v[26:27], v[144:145] op_sel:[0,1]
	v_mov_b32_e32 v22, v19
	v_mul_f32_e32 v18, 0xbfb8aa3b, v27
	v_exp_f32_e32 v18, v18
	s_nop 0
	v_add_f32_e32 v18, 1.0, v18
	v_rcp_f32_e32 v18, v18
	s_nop 0
	v_mul_f32_e32 v18, v27, v18
	v_mul_f32_e32 v26, v26, v18
	v_pk_mul_f32 v[18:19], v[22:23], v[144:145] op_sel:[0,1]
	s_nop 0
	v_mul_f32_e32 v22, 0xbfb8aa3b, v19
	v_exp_f32_e32 v22, v22
	s_nop 0
	v_add_f32_e32 v22, 1.0, v22
	v_rcp_f32_e32 v22, v22
	s_nop 0
	v_mul_f32_e32 v19, v19, v22
	v_mul_f32_e32 v22, v18, v19
	v_mov_b32_e32 v18, v20
	v_mov_b32_e32 v19, v24
	v_pk_mul_f32 v[18:19], v[18:19], v[144:145] op_sel:[0,1]
	v_mov_b32_e32 v24, v21
	v_mul_f32_e32 v20, 0xbfb8aa3b, v19
	v_exp_f32_e32 v20, v20
	s_nop 0
	v_add_f32_e32 v20, 1.0, v20
	v_rcp_f32_e32 v20, v20
	s_nop 0
	v_mul_f32_e32 v19, v19, v20
	v_mul_f32_e32 v23, v18, v19
	v_pk_mul_f32 v[18:19], v[24:25], v[144:145] op_sel:[0,1]
	v_add_u32_e32 v24, 0xa0, v142
	v_mul_f32_e32 v20, 0xbfb8aa3b, v19
	v_exp_f32_e32 v20, v20
	s_nop 0
	v_add_f32_e32 v20, 1.0, v20
	v_rcp_f32_e32 v20, v20
	s_nop 0
	v_mul_f32_e32 v19, v19, v20
	v_mul_f32_e32 v21, v18, v19
	v_cvt_pk_bf16_f32 v18, v34, v30
	v_cvt_pk_bf16_f32 v19, v28, v29
	v_cvt_pk_bf16_f32 v20, v26, v22
	v_cvt_pk_bf16_f32 v21, v23, v21
	v_mad_i64_i32 v[22:23], s[16:17], v24, s76, v[114:115]
	v_lshl_add_u64 v[22:23], v[22:23], 0, v[116:117]
	global_store_dwordx4 v[22:23], v[18:21], off sc1
	s_nop 1
	v_mov_b32_e32 v18, v10
	v_mov_b32_e32 v19, v14
	v_pk_mul_f32 v[18:19], v[18:19], v[144:145] op_sel_hi:[1,0]
	v_mov_b32_e32 v14, v11
	v_mul_f32_e32 v10, 0xbfb8aa3b, v19
	v_exp_f32_e32 v10, v10
	s_nop 0
	v_add_f32_e32 v10, 1.0, v10
	v_rcp_f32_e32 v10, v10
	s_nop 0
	v_mul_f32_e32 v10, v19, v10
	v_mul_f32_e32 v18, v18, v10
	v_pk_mul_f32 v[10:11], v[14:15], v[144:145] op_sel_hi:[1,0]
	s_nop 0
	v_mul_f32_e32 v14, 0xbfb8aa3b, v11
	v_exp_f32_e32 v14, v14
	s_nop 0
	v_add_f32_e32 v14, 1.0, v14
	v_rcp_f32_e32 v14, v14
	s_nop 0
	v_mul_f32_e32 v11, v11, v14
	v_mul_f32_e32 v14, v10, v11
	v_mov_b32_e32 v10, v12
	v_mov_b32_e32 v11, v16
	v_pk_mul_f32 v[10:11], v[10:11], v[144:145] op_sel_hi:[1,0]
	v_mov_b32_e32 v16, v13
	v_mul_f32_e32 v12, 0xbfb8aa3b, v11
	v_exp_f32_e32 v12, v12
	s_nop 0
	v_add_f32_e32 v12, 1.0, v12
	v_rcp_f32_e32 v12, v12
	s_nop 0
	v_mul_f32_e32 v11, v11, v12
	v_mul_f32_e32 v12, v10, v11
	v_pk_mul_f32 v[10:11], v[16:17], v[144:145] op_sel_hi:[1,0]
	s_nop 0
	v_mul_f32_e32 v13, 0xbfb8aa3b, v11
	v_exp_f32_e32 v13, v13
	s_nop 0
	v_add_f32_e32 v13, 1.0, v13
	v_rcp_f32_e32 v13, v13
	s_nop 0
	v_mul_f32_e32 v11, v11, v13
	v_mul_f32_e32 v13, v10, v11
	v_mov_b32_e32 v10, v2
	v_mov_b32_e32 v11, v6
	v_pk_mul_f32 v[10:11], v[10:11], v[144:145] op_sel_hi:[1,0]
	v_mov_b32_e32 v6, v3
	v_mul_f32_e32 v2, 0xbfb8aa3b, v11
	v_exp_f32_e32 v2, v2
	s_nop 0
	v_add_f32_e32 v2, 1.0, v2
	v_rcp_f32_e32 v2, v2
	s_nop 0
	v_mul_f32_e32 v2, v11, v2
	v_mul_f32_e32 v10, v10, v2
	v_pk_mul_f32 v[2:3], v[6:7], v[144:145] op_sel_hi:[1,0]
	s_nop 0
	v_mul_f32_e32 v6, 0xbfb8aa3b, v3
	v_exp_f32_e32 v6, v6
	s_nop 0
	v_add_f32_e32 v6, 1.0, v6
	v_rcp_f32_e32 v6, v6
	s_nop 0
	v_mul_f32_e32 v3, v3, v6
	v_mul_f32_e32 v6, v2, v3
	v_mov_b32_e32 v2, v4
	v_mov_b32_e32 v3, v8
	v_pk_mul_f32 v[2:3], v[2:3], v[144:145] op_sel_hi:[1,0]
	v_mov_b32_e32 v8, v5
	v_mul_f32_e32 v4, 0xbfb8aa3b, v3
	v_exp_f32_e32 v4, v4
	s_nop 0
	v_add_f32_e32 v4, 1.0, v4
	v_rcp_f32_e32 v4, v4
	s_nop 0
	v_mul_f32_e32 v3, v3, v4
	v_mul_f32_e32 v7, v2, v3
	v_pk_mul_f32 v[2:3], v[8:9], v[144:145] op_sel_hi:[1,0]
	v_add_u32_e32 v8, 0xb0, v142
	v_mul_f32_e32 v4, 0xbfb8aa3b, v3
	v_exp_f32_e32 v4, v4
	s_nop 0
	v_add_f32_e32 v4, 1.0, v4
	v_rcp_f32_e32 v4, v4
	s_nop 0
	v_mul_f32_e32 v3, v3, v4
	v_mul_f32_e32 v5, v2, v3
	v_cvt_pk_bf16_f32 v2, v18, v14
	v_cvt_pk_bf16_f32 v3, v12, v13
	v_cvt_pk_bf16_f32 v4, v10, v6
	v_cvt_pk_bf16_f32 v5, v7, v5
	v_mad_i64_i32 v[6:7], s[16:17], v8, s76, v[114:115]
	v_lshl_add_u64 v[6:7], v[6:7], 0, v[116:117]
	s_mov_b64 s[16:17], -1
	global_store_dwordx4 v[6:7], v[2:5], off sc1
	s_cbranch_vccnz .LBB0_655
	s_andn2_b64 vcc, exec, s[6:7]
	s_cbranch_vccnz .LBB0_654
	s_barrier
	s_branch .LBB0_654

; __device__ __forceinline__ unsigned cvt_pk_bf16(float lo, float hi) { unsigned r; asm volatile("v_cvt_pk_bf16_f32 %0, %1, %2" : "=v"(r) : "v"(lo), "v"(hi)); return r; }
; __device__ __forceinline__ float bf_lo(unsigned w) { return __uint_as_float(w << 16); }
; __device__ __forceinline__ float bf_hi(unsigned w) { return __uint_as_float(w & 0xffff0000u); }
;     __device__ __forceinline__ void operator()(const f32x4 (&acc)[2][2][4][2], const Unit& u, int wr, int wc, int fr, int fq) const {
;     ...
;         for (int ai = 0; ai < 2; ++ai) {
;             u32x4 xw[4][2];
; #pragma unroll
;             for (int m = 0; m < 4; ++m)
; #pragma unroll
;                 for (int bj = 0; bj < 2; ++bj) xw[m][bj] = *(const u32x4*)(XB + (size_t)(row0 + ai * HALF + m * 16) * D_MODEL + col0 + bj * HALF);
; #pragma unroll
;             for (int m = 0; m < 4; ++m) { const int row = row0 + ai * HALF + m * 16; float ss = 0.f;
; #pragma unroll
;                 for (int bj = 0; bj < 2; ++bj) { const size_t o = (size_t)row * D_MODEL + col0 + bj * HALF; const u32x4 t = xw[m][bj];
;                     f32x4 v0, v1; v0[0] = bf_lo(t.x); v0[1] = bf_hi(t.x); v0[2] = bf_lo(t.y); v0[3] = bf_hi(t.y); v1[0] = bf_lo(t.z); v1[1] = bf_hi(t.z); v1[2] = bf_lo(t.w); v1[3] = bf_hi(t.w);
;                     v0 = v0 + acc[ai][bj][m][0]; v1 = v1 + acc[ai][bj][m][1];
;                     if (aux) { u32x4 w; w.x = cvt_pk_bf16(v0[0], v0[1]); w.y = cvt_pk_bf16(v0[2], v0[3]); w.z = cvt_pk_bf16(v1[0], v1[1]); w.w = cvt_pk_bf16(v1[2], v1[3]);
;                         *(u32x4*)(XB + o) = w;
;                         ss += (v0[0] * v0[0] + v0[1] * v0[1]) + (v0[2] * v0[2] + v0[3] * v0[3]) + (v1[0] * v1[0] + v1[1] * v1[1]) + (v1[2] * v1[2] + v1[3] * v1[3]); }
;                     else { *(f32x4*)(Xout + o) = v0; *(f32x4*)(Xout + o + 4) = v1; } }
.LBB0_805:
	s_lshl_b32 s22, s17, 8
	v_add_u32_e32 v186, s22, v198
	v_lshl_or_b32 v182, s16, 8, v200
	v_ashrrev_i32_e32 v183, 31, v182
	v_ashrrev_i32_e32 v187, 31, v186
	v_lshl_add_u64 v[184:185], v[182:183], 1, s[56:57]
	v_lshlrev_b64 v[122:123], 12, v[186:187]
	v_or_b32_e32 v192, 16, v186
	v_lshl_add_u64 v[122:123], v[184:185], 0, v[122:123]
	v_ashrrev_i32_e32 v193, 31, v192
	global_load_dwordx4 v[218:221], v[122:123], off
	global_load_dwordx4 v[154:157], v[122:123], off offset:256
	v_lshlrev_b64 v[122:123], 12, v[192:193]
	v_or_b32_e32 v190, 32, v186
	v_lshl_add_u64 v[122:123], v[184:185], 0, v[122:123]
	v_ashrrev_i32_e32 v191, 31, v190
	global_load_dwordx4 v[150:153], v[122:123], off
	global_load_dwordx4 v[146:149], v[122:123], off offset:256
	v_lshlrev_b64 v[122:123], 12, v[190:191]
	v_or_b32_e32 v188, 48, v186
	v_lshl_add_u64 v[122:123], v[184:185], 0, v[122:123]
	v_ashrrev_i32_e32 v189, 31, v188
	global_load_dwordx4 v[142:145], v[122:123], off
	global_load_dwordx4 v[138:141], v[122:123], off offset:256
	v_lshlrev_b64 v[122:123], 12, v[188:189]
	v_lshl_add_u64 v[122:123], v[184:185], 0, v[122:123]
	global_load_dwordx4 v[134:137], v[122:123], off
	s_nop 0
	global_load_dwordx4 v[122:125], v[122:123], off offset:256
	v_cndmask_b32_e64 v194, 0, 1, s[68:69]
	v_cmp_ne_u32_e64 s[44:45], 1, v194
	s_andn2_b64 vcc, exec, s[68:69]
	v_lshlrev_b64 v[194:195], 11, v[186:187]
	s_mov_b64 s[24:25], -1
	s_waitcnt vmcnt(0)
	v_lshlrev_b32_e32 v196, 16, v218
	v_and_b32_e32 v197, 0xffff0000, v218
	v_lshlrev_b32_e32 v218, 16, v219
	v_and_b32_e32 v219, 0xffff0000, v219
	v_lshlrev_b32_e32 v222, 16, v220
	v_and_b32_e32 v223, 0xffff0000, v220
	v_lshlrev_b32_e32 v220, 16, v221
	v_and_b32_e32 v221, 0xffff0000, v221
	v_pk_add_f32 v[132:133], v[132:133], v[218:219]
	v_pk_add_f32 v[130:131], v[130:131], v[196:197]
	v_pk_add_f32 v[128:129], v[128:129], v[220:221]
	v_pk_add_f32 v[126:127], v[126:127], v[222:223]
	s_cbranch_vccnz .LBB0_807
	v_cvt_pk_bf16_f32 v218, v130, v131
	v_cvt_pk_bf16_f32 v219, v132, v133
	v_lshl_add_u64 v[196:197], v[194:195], 1, v[184:185]
	v_cvt_pk_bf16_f32 v220, v126, v127
	v_cvt_pk_bf16_f32 v221, v128, v129
	global_store_dwordx4 v[196:197], v[218:221], off sc1
	v_pk_mul_f32 v[196:197], v[132:133], v[132:133]
	s_mov_b64 s[24:25], 0
	v_pk_mul_f32 v[218:219], v[130:131], v[130:131]
	s_nop 0
	v_pk_mov_b32 v[220:221], v[218:219], v[196:197] op_sel:[1,0]
	v_mov_b32_e32 v219, v197
	v_pk_add_f32 v[196:197], v[220:221], v[218:219]
	v_pk_mul_f32 v[218:219], v[128:129], v[128:129]
	v_pk_mul_f32 v[220:221], v[126:127], v[126:127]
	v_mov_b32_e32 v222, v218
	v_mov_b32_e32 v223, v220
	v_mov_b32_e32 v220, v219
	v_pk_add_f32 v[218:219], v[222:223], v[220:221]
	v_add_f32_e32 v187, v196, v197
	v_add_f32_e32 v187, v219, v187
	v_add_f32_e32 v187, v218, v187
.LBB0_807:
	v_lshl_add_u64 v[196:197], v[194:195], 0, v[182:183]
	s_andn2_b64 vcc, exec, s[24:25]
	v_lshl_add_u64 v[194:195], v[196:197], 2, s[90:91]
	s_cbranch_vccnz .LBB0_809
	v_mov_b32_e32 v187, 0
	global_store_dwordx4 v[194:195], v[130:133], off sc1
	global_store_dwordx4 v[194:195], v[126:129], off offset:16 sc1

; __device__ __forceinline__ unsigned cvt_pk_bf16(float lo, float hi) { unsigned r; asm volatile("v_cvt_pk_bf16_f32 %0, %1, %2" : "=v"(r) : "v"(lo), "v"(hi)); return r; }
; __device__ __forceinline__ float bf_lo(unsigned w) { return __uint_as_float(w << 16); }
; __device__ __forceinline__ float bf_hi(unsigned w) { return __uint_as_float(w & 0xffff0000u); }
;     __device__ __forceinline__ void operator()(const f32x4 (&acc)[2][2][4][2], const Unit& u, int wr, int wc, int fr, int fq) const {
;     ...
;             for (int m = 0; m < 4; ++m) { const int row = row0 + ai * HALF + m * 16; float ss = 0.f;
; #pragma unroll
;                 for (int bj = 0; bj < 2; ++bj) { const size_t o = (size_t)row * D_MODEL + col0 + bj * HALF; const u32x4 t = xw[m][bj];
;                     f32x4 v0, v1; v0[0] = bf_lo(t.x); v0[1] = bf_hi(t.x); v0[2] = bf_lo(t.y); v0[3] = bf_hi(t.y); v1[0] = bf_lo(t.z); v1[1] = bf_hi(t.z); v1[2] = bf_lo(t.w); v1[3] = bf_hi(t.w);
;                     v0 = v0 + acc[ai][bj][m][0]; v1 = v1 + acc[ai][bj][m][1];
;                     if (aux) { u32x4 w; w.x = cvt_pk_bf16(v0[0], v0[1]); w.y = cvt_pk_bf16(v0[2], v0[3]); w.z = cvt_pk_bf16(v1[0], v1[1]); w.w = cvt_pk_bf16(v1[2], v1[3]);
;                         *(u32x4*)(XB + o) = w;
;                         ss += (v0[0] * v0[0] + v0[1] * v0[1]) + (v0[2] * v0[2] + v0[3] * v0[3]) + (v1[0] * v1[0] + v1[1] * v1[1]) + (v1[2] * v1[2] + v1[3] * v1[3]); }
;                     else { *(f32x4*)(Xout + o) = v0; *(f32x4*)(Xout + o + 4) = v1; } }
.LBB0_812:
	v_lshlrev_b64 v[130:131], 1, v[196:197]
	v_or_b32_e32 v130, 0x100, v130
	v_cvt_pk_bf16_f32 v126, v118, v119
	v_cvt_pk_bf16_f32 v127, v120, v121
	v_cvt_pk_bf16_f32 v128, v114, v115
	v_cvt_pk_bf16_f32 v129, v116, v117
	v_lshl_add_u64 v[130:131], s[56:57], 0, v[130:131]
	global_store_dwordx4 v[130:131], v[126:129], off sc1
	s_nop 1
	v_pk_mul_f32 v[126:127], v[120:121], v[120:121]
	v_pk_mul_f32 v[128:129], v[118:119], v[118:119]
	s_nop 0
	v_pk_mov_b32 v[130:131], v[128:129], v[126:127] op_sel:[1,0]
	v_mov_b32_e32 v129, v127
	v_pk_add_f32 v[126:127], v[130:131], v[128:129]
	v_pk_mul_f32 v[128:129], v[116:117], v[116:117]
	v_pk_mul_f32 v[130:131], v[114:115], v[114:115]
	v_mov_b32_e32 v132, v128
	v_mov_b32_e32 v133, v130
	v_mov_b32_e32 v130, v129
	v_pk_add_f32 v[128:129], v[132:133], v[130:131]
	v_add_f32_e32 v126, v126, v127
	v_add_f32_e32 v126, v129, v126
	v_add_f32_e32 v126, v128, v126
	v_add_f32_e32 v126, v126, v187
	s_cbranch_execnz .LBB0_811
.LBB0_813:
	v_mov_b32_e32 v126, v187
	global_store_dwordx4 v[194:195], v[118:121], off offset:512 sc1
	global_store_dwordx4 v[194:195], v[114:117], off offset:528 sc1
	s_and_b64 vcc, exec, s[44:45]
	s_cbranch_vccnz .LBB0_817

; __device__ __forceinline__ unsigned cvt_pk_bf16(float lo, float hi) { unsigned r; asm volatile("v_cvt_pk_bf16_f32 %0, %1, %2" : "=v"(r) : "v"(lo), "v"(hi)); return r; }
; __device__ __forceinline__ float bf_lo(unsigned w) { return __uint_as_float(w << 16); }
; __device__ __forceinline__ float bf_hi(unsigned w) { return __uint_as_float(w & 0xffff0000u); }
;     __device__ __forceinline__ void operator()(const f32x4 (&acc)[2][2][4][2], const Unit& u, int wr, int wc, int fr, int fq) const {
;     ...
;             for (int m = 0; m < 4; ++m) { const int row = row0 + ai * HALF + m * 16; float ss = 0.f;
; #pragma unroll
;                 for (int bj = 0; bj < 2; ++bj) { const size_t o = (size_t)row * D_MODEL + col0 + bj * HALF; const u32x4 t = xw[m][bj];
;                     f32x4 v0, v1; v0[0] = bf_lo(t.x); v0[1] = bf_hi(t.x); v0[2] = bf_lo(t.y); v0[3] = bf_hi(t.y); v1[0] = bf_lo(t.z); v1[1] = bf_hi(t.z); v1[2] = bf_lo(t.w); v1[3] = bf_hi(t.w);
;                     v0 = v0 + acc[ai][bj][m][0]; v1 = v1 + acc[ai][bj][m][1];
;                     if (aux) { u32x4 w; w.x = cvt_pk_bf16(v0[0], v0[1]); w.y = cvt_pk_bf16(v0[2], v0[3]); w.z = cvt_pk_bf16(v1[0], v1[1]); w.w = cvt_pk_bf16(v1[2], v1[3]);
;                         *(u32x4*)(XB + o) = w;
;                         ss += (v0[0] * v0[0] + v0[1] * v0[1]) + (v0[2] * v0[2] + v0[3] * v0[3]) + (v1[0] * v1[0] + v1[1] * v1[1]) + (v1[2] * v1[2] + v1[3] * v1[3]); }
;                     else { *(f32x4*)(Xout + o) = v0; *(f32x4*)(Xout + o + 4) = v1; } }
.LBB0_817:
	v_lshlrev_b32_e32 v116, 16, v150
	v_and_b32_e32 v117, 0xffff0000, v150
	v_lshlrev_b32_e32 v118, 16, v151
	v_and_b32_e32 v119, 0xffff0000, v151
	v_lshlrev_b32_e32 v120, 16, v152
	v_and_b32_e32 v121, 0xffff0000, v152
	v_lshlrev_b32_e32 v126, 16, v153
	v_and_b32_e32 v127, 0xffff0000, v153
	s_waitcnt lgkmcnt(0)
	v_lshlrev_b64 v[114:115], 11, v[192:193]
	v_pk_add_f32 v[112:113], v[112:113], v[118:119]
	v_pk_add_f32 v[110:111], v[110:111], v[116:117]
	v_pk_add_f32 v[108:109], v[108:109], v[126:127]
	v_pk_add_f32 v[106:107], v[106:107], v[120:121]
	s_and_b64 vcc, exec, s[44:45]
	s_mov_b64 s[24:25], -1
	s_cbranch_vccnz .LBB0_819
	v_cvt_pk_bf16_f32 v116, v110, v111
	v_cvt_pk_bf16_f32 v117, v112, v113
	v_cvt_pk_bf16_f32 v118, v106, v107
	v_cvt_pk_bf16_f32 v119, v108, v109
	v_lshl_add_u64 v[120:121], v[114:115], 1, v[184:185]
	global_store_dwordx4 v[120:121], v[116:119], off sc1
	s_mov_b64 s[24:25], 0
	s_nop 0
	v_pk_mul_f32 v[116:117], v[112:113], v[112:113]
	v_pk_mul_f32 v[118:119], v[110:111], v[110:111]
	s_nop 0
	v_pk_mov_b32 v[120:121], v[118:119], v[116:117] op_sel:[1,0]
	v_mov_b32_e32 v119, v117
	v_pk_add_f32 v[116:117], v[120:121], v[118:119]
	v_pk_mul_f32 v[118:119], v[108:109], v[108:109]
	v_pk_mul_f32 v[120:121], v[106:107], v[106:107]
	v_mov_b32_e32 v126, v118
	v_mov_b32_e32 v127, v120
	v_mov_b32_e32 v120, v119
	v_pk_add_f32 v[118:119], v[126:127], v[120:121]
	v_add_f32_e32 v116, v116, v117
	v_add_f32_e32 v116, v119, v116
	v_add_f32_e32 v118, v118, v116
.LBB0_819:
	v_lshl_add_u64 v[116:117], v[114:115], 0, v[182:183]
	s_andn2_b64 vcc, exec, s[24:25]
	v_lshl_add_u64 v[114:115], v[116:117], 2, s[90:91]
	s_cbranch_vccnz .LBB0_821
	v_mov_b32_e32 v118, 0
	global_store_dwordx4 v[114:115], v[110:113], off sc1
	global_store_dwordx4 v[114:115], v[106:109], off offset:16 sc1

; __device__ __forceinline__ unsigned cvt_pk_bf16(float lo, float hi) { unsigned r; asm volatile("v_cvt_pk_bf16_f32 %0, %1, %2" : "=v"(r) : "v"(lo), "v"(hi)); return r; }
; __device__ __forceinline__ float bf_lo(unsigned w) { return __uint_as_float(w << 16); }
; __device__ __forceinline__ float bf_hi(unsigned w) { return __uint_as_float(w & 0xffff0000u); }
;     __device__ __forceinline__ void operator()(const f32x4 (&acc)[2][2][4][2], const Unit& u, int wr, int wc, int fr, int fq) const {
;     ...
;             for (int m = 0; m < 4; ++m) { const int row = row0 + ai * HALF + m * 16; float ss = 0.f;
; #pragma unroll
;                 for (int bj = 0; bj < 2; ++bj) { const size_t o = (size_t)row * D_MODEL + col0 + bj * HALF; const u32x4 t = xw[m][bj];
;                     f32x4 v0, v1; v0[0] = bf_lo(t.x); v0[1] = bf_hi(t.x); v0[2] = bf_lo(t.y); v0[3] = bf_hi(t.y); v1[0] = bf_lo(t.z); v1[1] = bf_hi(t.z); v1[2] = bf_lo(t.w); v1[3] = bf_hi(t.w);
;                     v0 = v0 + acc[ai][bj][m][0]; v1 = v1 + acc[ai][bj][m][1];
;                     if (aux) { u32x4 w; w.x = cvt_pk_bf16(v0[0], v0[1]); w.y = cvt_pk_bf16(v0[2], v0[3]); w.z = cvt_pk_bf16(v1[0], v1[1]); w.w = cvt_pk_bf16(v1[2], v1[3]);
;                         *(u32x4*)(XB + o) = w;
;                         ss += (v0[0] * v0[0] + v0[1] * v0[1]) + (v0[2] * v0[2] + v0[3] * v0[3]) + (v1[0] * v1[0] + v1[1] * v1[1]) + (v1[2] * v1[2] + v1[3] * v1[3]); }
;                     else { *(f32x4*)(Xout + o) = v0; *(f32x4*)(Xout + o + 4) = v1; } }
.LBB0_824:
	v_lshlrev_b64 v[110:111], 1, v[116:117]
	v_or_b32_e32 v110, 0x100, v110
	v_cvt_pk_bf16_f32 v106, v102, v103
	v_cvt_pk_bf16_f32 v107, v104, v105
	v_cvt_pk_bf16_f32 v108, v98, v99
	v_cvt_pk_bf16_f32 v109, v100, v101
	v_lshl_add_u64 v[110:111], s[56:57], 0, v[110:111]
	global_store_dwordx4 v[110:111], v[106:109], off sc1
	s_nop 1
	v_pk_mul_f32 v[106:107], v[104:105], v[104:105]
	v_pk_mul_f32 v[108:109], v[102:103], v[102:103]
	s_nop 0
	v_pk_mov_b32 v[110:111], v[108:109], v[106:107] op_sel:[1,0]
	v_mov_b32_e32 v109, v107
	v_pk_add_f32 v[106:107], v[110:111], v[108:109]
	v_pk_mul_f32 v[108:109], v[100:101], v[100:101]
	v_pk_mul_f32 v[110:111], v[98:99], v[98:99]
	v_mov_b32_e32 v112, v108
	v_mov_b32_e32 v113, v110
	v_mov_b32_e32 v110, v109
	v_pk_add_f32 v[108:109], v[112:113], v[110:111]
	v_add_f32_e32 v106, v106, v107
	v_add_f32_e32 v106, v109, v106
	v_add_f32_e32 v106, v108, v106
	v_add_f32_e32 v106, v106, v118
	s_cbranch_execnz .LBB0_823
.LBB0_825:
	v_mov_b32_e32 v106, v118
	global_store_dwordx4 v[114:115], v[102:105], off offset:512 sc1
	global_store_dwordx4 v[114:115], v[98:101], off offset:528 sc1
	s_and_b64 vcc, exec, s[44:45]
	s_cbranch_vccnz .LBB0_829

; __device__ __forceinline__ unsigned cvt_pk_bf16(float lo, float hi) { unsigned r; asm volatile("v_cvt_pk_bf16_f32 %0, %1, %2" : "=v"(r) : "v"(lo), "v"(hi)); return r; }
; __device__ __forceinline__ float bf_lo(unsigned w) { return __uint_as_float(w << 16); }
; __device__ __forceinline__ float bf_hi(unsigned w) { return __uint_as_float(w & 0xffff0000u); }
;     __device__ __forceinline__ void operator()(const f32x4 (&acc)[2][2][4][2], const Unit& u, int wr, int wc, int fr, int fq) const {
;     ...
;             for (int m = 0; m < 4; ++m) { const int row = row0 + ai * HALF + m * 16; float ss = 0.f;
; #pragma unroll
;                 for (int bj = 0; bj < 2; ++bj) { const size_t o = (size_t)row * D_MODEL + col0 + bj * HALF; const u32x4 t = xw[m][bj];
;                     f32x4 v0, v1; v0[0] = bf_lo(t.x); v0[1] = bf_hi(t.x); v0[2] = bf_lo(t.y); v0[3] = bf_hi(t.y); v1[0] = bf_lo(t.z); v1[1] = bf_hi(t.z); v1[2] = bf_lo(t.w); v1[3] = bf_hi(t.w);
;                     v0 = v0 + acc[ai][bj][m][0]; v1 = v1 + acc[ai][bj][m][1];
;                     if (aux) { u32x4 w; w.x = cvt_pk_bf16(v0[0], v0[1]); w.y = cvt_pk_bf16(v0[2], v0[3]); w.z = cvt_pk_bf16(v1[0], v1[1]); w.w = cvt_pk_bf16(v1[2], v1[3]);
;                         *(u32x4*)(XB + o) = w;
;                         ss += (v0[0] * v0[0] + v0[1] * v0[1]) + (v0[2] * v0[2] + v0[3] * v0[3]) + (v1[0] * v1[0] + v1[1] * v1[1]) + (v1[2] * v1[2] + v1[3] * v1[3]); }
;                     else { *(f32x4*)(Xout + o) = v0; *(f32x4*)(Xout + o + 4) = v1; } }
.LBB0_829:
	v_lshlrev_b32_e32 v100, 16, v142
	v_and_b32_e32 v101, 0xffff0000, v142
	v_lshlrev_b32_e32 v102, 16, v143
	v_and_b32_e32 v103, 0xffff0000, v143
	v_lshlrev_b32_e32 v104, 16, v144
	v_and_b32_e32 v105, 0xffff0000, v144
	v_lshlrev_b32_e32 v106, 16, v145
	v_and_b32_e32 v107, 0xffff0000, v145
	s_waitcnt lgkmcnt(0)
	v_lshlrev_b64 v[98:99], 11, v[190:191]
	v_pk_add_f32 v[96:97], v[96:97], v[102:103]
	v_pk_add_f32 v[94:95], v[94:95], v[100:101]
	v_pk_add_f32 v[92:93], v[92:93], v[106:107]
	v_pk_add_f32 v[90:91], v[90:91], v[104:105]
	s_and_b64 vcc, exec, s[44:45]
	s_mov_b64 s[24:25], -1
	s_cbranch_vccnz .LBB0_831
	v_cvt_pk_bf16_f32 v100, v94, v95
	v_cvt_pk_bf16_f32 v101, v96, v97
	v_cvt_pk_bf16_f32 v102, v90, v91
	v_cvt_pk_bf16_f32 v103, v92, v93
	v_lshl_add_u64 v[104:105], v[98:99], 1, v[184:185]
	global_store_dwordx4 v[104:105], v[100:103], off sc1
	s_mov_b64 s[24:25], 0
	s_nop 0
	v_pk_mul_f32 v[100:101], v[96:97], v[96:97]
	v_pk_mul_f32 v[102:103], v[94:95], v[94:95]
	s_nop 0
	v_pk_mov_b32 v[104:105], v[102:103], v[100:101] op_sel:[1,0]
	v_mov_b32_e32 v103, v101
	v_pk_add_f32 v[100:101], v[104:105], v[102:103]
	v_pk_mul_f32 v[102:103], v[92:93], v[92:93]
	v_pk_mul_f32 v[104:105], v[90:91], v[90:91]
	v_mov_b32_e32 v106, v102
	v_mov_b32_e32 v107, v104
	v_mov_b32_e32 v104, v103
	v_pk_add_f32 v[102:103], v[106:107], v[104:105]
	v_add_f32_e32 v100, v100, v101
	v_add_f32_e32 v100, v103, v100
	v_add_f32_e32 v102, v102, v100
.LBB0_831:
	v_lshl_add_u64 v[100:101], v[98:99], 0, v[182:183]
	s_andn2_b64 vcc, exec, s[24:25]
	v_lshl_add_u64 v[98:99], v[100:101], 2, s[90:91]
	s_cbranch_vccnz .LBB0_833
	v_mov_b32_e32 v102, 0
	global_store_dwordx4 v[98:99], v[94:97], off sc1
	global_store_dwordx4 v[98:99], v[90:93], off offset:16 sc1

; __device__ __forceinline__ unsigned cvt_pk_bf16(float lo, float hi) { unsigned r; asm volatile("v_cvt_pk_bf16_f32 %0, %1, %2" : "=v"(r) : "v"(lo), "v"(hi)); return r; }
; __device__ __forceinline__ float bf_lo(unsigned w) { return __uint_as_float(w << 16); }
; __device__ __forceinline__ float bf_hi(unsigned w) { return __uint_as_float(w & 0xffff0000u); }
;     __device__ __forceinline__ void operator()(const f32x4 (&acc)[2][2][4][2], const Unit& u, int wr, int wc, int fr, int fq) const {
;     ...
;             for (int m = 0; m < 4; ++m) { const int row = row0 + ai * HALF + m * 16; float ss = 0.f;
; #pragma unroll
;                 for (int bj = 0; bj < 2; ++bj) { const size_t o = (size_t)row * D_MODEL + col0 + bj * HALF; const u32x4 t = xw[m][bj];
;                     f32x4 v0, v1; v0[0] = bf_lo(t.x); v0[1] = bf_hi(t.x); v0[2] = bf_lo(t.y); v0[3] = bf_hi(t.y); v1[0] = bf_lo(t.z); v1[1] = bf_hi(t.z); v1[2] = bf_lo(t.w); v1[3] = bf_hi(t.w);
;                     v0 = v0 + acc[ai][bj][m][0]; v1 = v1 + acc[ai][bj][m][1];
;                     if (aux) { u32x4 w; w.x = cvt_pk_bf16(v0[0], v0[1]); w.y = cvt_pk_bf16(v0[2], v0[3]); w.z = cvt_pk_bf16(v1[0], v1[1]); w.w = cvt_pk_bf16(v1[2], v1[3]);
;                         *(u32x4*)(XB + o) = w;
;                         ss += (v0[0] * v0[0] + v0[1] * v0[1]) + (v0[2] * v0[2] + v0[3] * v0[3]) + (v1[0] * v1[0] + v1[1] * v1[1]) + (v1[2] * v1[2] + v1[3] * v1[3]); }
;                     else { *(f32x4*)(Xout + o) = v0; *(f32x4*)(Xout + o + 4) = v1; } }
.LBB0_836:
	v_lshlrev_b64 v[94:95], 1, v[100:101]
	v_or_b32_e32 v94, 0x100, v94
	v_cvt_pk_bf16_f32 v90, v86, v87
	v_cvt_pk_bf16_f32 v91, v88, v89
	v_cvt_pk_bf16_f32 v92, v82, v83
	v_cvt_pk_bf16_f32 v93, v84, v85
	v_lshl_add_u64 v[94:95], s[56:57], 0, v[94:95]
	global_store_dwordx4 v[94:95], v[90:93], off sc1
	s_nop 1
	v_pk_mul_f32 v[90:91], v[88:89], v[88:89]
	v_pk_mul_f32 v[92:93], v[86:87], v[86:87]
	s_nop 0
	v_pk_mov_b32 v[94:95], v[92:93], v[90:91] op_sel:[1,0]
	v_mov_b32_e32 v93, v91
	v_pk_add_f32 v[90:91], v[94:95], v[92:93]
	v_pk_mul_f32 v[92:93], v[84:85], v[84:85]
	v_pk_mul_f32 v[94:95], v[82:83], v[82:83]
	v_mov_b32_e32 v96, v92
	v_mov_b32_e32 v97, v94
	v_mov_b32_e32 v94, v93
	v_pk_add_f32 v[92:93], v[96:97], v[94:95]
	v_add_f32_e32 v90, v90, v91
	v_add_f32_e32 v90, v93, v90
	v_add_f32_e32 v90, v92, v90
	v_add_f32_e32 v90, v90, v102
	s_cbranch_execnz .LBB0_835
.LBB0_837:
	v_mov_b32_e32 v90, v102
	global_store_dwordx4 v[98:99], v[86:89], off offset:512 sc1
	global_store_dwordx4 v[98:99], v[82:85], off offset:528 sc1
	s_and_b64 vcc, exec, s[44:45]
	s_cbranch_vccnz .LBB0_841

; __device__ __forceinline__ unsigned cvt_pk_bf16(float lo, float hi) { unsigned r; asm volatile("v_cvt_pk_bf16_f32 %0, %1, %2" : "=v"(r) : "v"(lo), "v"(hi)); return r; }
; __device__ __forceinline__ float bf_lo(unsigned w) { return __uint_as_float(w << 16); }
; __device__ __forceinline__ float bf_hi(unsigned w) { return __uint_as_float(w & 0xffff0000u); }
;     __device__ __forceinline__ void operator()(const f32x4 (&acc)[2][2][4][2], const Unit& u, int wr, int wc, int fr, int fq) const {
;     ...
;             for (int m = 0; m < 4; ++m) { const int row = row0 + ai * HALF + m * 16; float ss = 0.f;
; #pragma unroll
;                 for (int bj = 0; bj < 2; ++bj) { const size_t o = (size_t)row * D_MODEL + col0 + bj * HALF; const u32x4 t = xw[m][bj];
;                     f32x4 v0, v1; v0[0] = bf_lo(t.x); v0[1] = bf_hi(t.x); v0[2] = bf_lo(t.y); v0[3] = bf_hi(t.y); v1[0] = bf_lo(t.z); v1[1] = bf_hi(t.z); v1[2] = bf_lo(t.w); v1[3] = bf_hi(t.w);
;                     v0 = v0 + acc[ai][bj][m][0]; v1 = v1 + acc[ai][bj][m][1];
;                     if (aux) { u32x4 w; w.x = cvt_pk_bf16(v0[0], v0[1]); w.y = cvt_pk_bf16(v0[2], v0[3]); w.z = cvt_pk_bf16(v1[0], v1[1]); w.w = cvt_pk_bf16(v1[2], v1[3]);
;                         *(u32x4*)(XB + o) = w;
;                         ss += (v0[0] * v0[0] + v0[1] * v0[1]) + (v0[2] * v0[2] + v0[3] * v0[3]) + (v1[0] * v1[0] + v1[1] * v1[1]) + (v1[2] * v1[2] + v1[3] * v1[3]); }
;                     else { *(f32x4*)(Xout + o) = v0; *(f32x4*)(Xout + o + 4) = v1; } }
.LBB0_841:
	v_lshlrev_b32_e32 v84, 16, v134
	v_and_b32_e32 v85, 0xffff0000, v134
	v_lshlrev_b32_e32 v86, 16, v135
	v_and_b32_e32 v87, 0xffff0000, v135
	v_lshlrev_b32_e32 v88, 16, v136
	v_and_b32_e32 v89, 0xffff0000, v136
	v_lshlrev_b32_e32 v90, 16, v137
	v_and_b32_e32 v91, 0xffff0000, v137
	s_waitcnt lgkmcnt(0)
	v_lshlrev_b64 v[82:83], 11, v[188:189]
	v_pk_add_f32 v[80:81], v[80:81], v[86:87]
	v_pk_add_f32 v[78:79], v[78:79], v[84:85]
	v_pk_add_f32 v[76:77], v[76:77], v[90:91]
	v_pk_add_f32 v[74:75], v[74:75], v[88:89]
	s_and_b64 vcc, exec, s[44:45]
	s_mov_b64 s[24:25], -1
	s_cbranch_vccnz .LBB0_843
	v_cvt_pk_bf16_f32 v84, v78, v79
	v_cvt_pk_bf16_f32 v85, v80, v81
	v_cvt_pk_bf16_f32 v86, v74, v75
	v_cvt_pk_bf16_f32 v87, v76, v77
	v_lshl_add_u64 v[88:89], v[82:83], 1, v[184:185]
	global_store_dwordx4 v[88:89], v[84:87], off sc1
	s_mov_b64 s[24:25], 0
	s_nop 0
	v_pk_mul_f32 v[84:85], v[80:81], v[80:81]
	v_pk_mul_f32 v[86:87], v[78:79], v[78:79]
	s_nop 0
	v_pk_mov_b32 v[88:89], v[86:87], v[84:85] op_sel:[1,0]
	v_mov_b32_e32 v87, v85
	v_pk_add_f32 v[84:85], v[88:89], v[86:87]
	v_pk_mul_f32 v[86:87], v[76:77], v[76:77]
	v_pk_mul_f32 v[88:89], v[74:75], v[74:75]
	v_mov_b32_e32 v90, v86
	v_mov_b32_e32 v91, v88
	v_mov_b32_e32 v88, v87
	v_pk_add_f32 v[86:87], v[90:91], v[88:89]
	v_add_f32_e32 v84, v84, v85
	v_add_f32_e32 v84, v87, v84
	v_add_f32_e32 v86, v86, v84
.LBB0_843:
	v_lshl_add_u64 v[84:85], v[82:83], 0, v[182:183]
	s_andn2_b64 vcc, exec, s[24:25]
	v_lshl_add_u64 v[82:83], v[84:85], 2, s[90:91]
	s_cbranch_vccnz .LBB0_845
	v_mov_b32_e32 v86, 0
	global_store_dwordx4 v[82:83], v[78:81], off sc1
	global_store_dwordx4 v[82:83], v[74:77], off offset:16 sc1

; __device__ __forceinline__ unsigned cvt_pk_bf16(float lo, float hi) { unsigned r; asm volatile("v_cvt_pk_bf16_f32 %0, %1, %2" : "=v"(r) : "v"(lo), "v"(hi)); return r; }
; __device__ __forceinline__ float bf_lo(unsigned w) { return __uint_as_float(w << 16); }
; __device__ __forceinline__ float bf_hi(unsigned w) { return __uint_as_float(w & 0xffff0000u); }
;     __device__ __forceinline__ void operator()(const f32x4 (&acc)[2][2][4][2], const Unit& u, int wr, int wc, int fr, int fq) const {
;     ...
;             for (int m = 0; m < 4; ++m) { const int row = row0 + ai * HALF + m * 16; float ss = 0.f;
; #pragma unroll
;                 for (int bj = 0; bj < 2; ++bj) { const size_t o = (size_t)row * D_MODEL + col0 + bj * HALF; const u32x4 t = xw[m][bj];
;                     f32x4 v0, v1; v0[0] = bf_lo(t.x); v0[1] = bf_hi(t.x); v0[2] = bf_lo(t.y); v0[3] = bf_hi(t.y); v1[0] = bf_lo(t.z); v1[1] = bf_hi(t.z); v1[2] = bf_lo(t.w); v1[3] = bf_hi(t.w);
;                     v0 = v0 + acc[ai][bj][m][0]; v1 = v1 + acc[ai][bj][m][1];
;                     if (aux) { u32x4 w; w.x = cvt_pk_bf16(v0[0], v0[1]); w.y = cvt_pk_bf16(v0[2], v0[3]); w.z = cvt_pk_bf16(v1[0], v1[1]); w.w = cvt_pk_bf16(v1[2], v1[3]);
;                         *(u32x4*)(XB + o) = w;
;                         ss += (v0[0] * v0[0] + v0[1] * v0[1]) + (v0[2] * v0[2] + v0[3] * v0[3]) + (v1[0] * v1[0] + v1[1] * v1[1]) + (v1[2] * v1[2] + v1[3] * v1[3]); }
;                     else { *(f32x4*)(Xout + o) = v0; *(f32x4*)(Xout + o + 4) = v1; } }
.LBB0_848:
	v_lshlrev_b64 v[78:79], 1, v[84:85]
	v_or_b32_e32 v78, 0x100, v78
	v_cvt_pk_bf16_f32 v74, v70, v71
	v_cvt_pk_bf16_f32 v75, v72, v73
	v_cvt_pk_bf16_f32 v76, v66, v67
	v_cvt_pk_bf16_f32 v77, v68, v69
	v_lshl_add_u64 v[78:79], s[56:57], 0, v[78:79]
	global_store_dwordx4 v[78:79], v[74:77], off sc1
	s_nop 1
	v_pk_mul_f32 v[74:75], v[72:73], v[72:73]
	v_pk_mul_f32 v[76:77], v[70:71], v[70:71]
	s_nop 0
	v_pk_mov_b32 v[78:79], v[76:77], v[74:75] op_sel:[1,0]
	v_mov_b32_e32 v77, v75
	v_pk_add_f32 v[74:75], v[78:79], v[76:77]
	v_pk_mul_f32 v[76:77], v[68:69], v[68:69]
	v_pk_mul_f32 v[78:79], v[66:67], v[66:67]
	v_mov_b32_e32 v80, v76
	v_mov_b32_e32 v81, v78
	v_mov_b32_e32 v78, v77
	v_pk_add_f32 v[76:77], v[80:81], v[78:79]
	v_add_f32_e32 v74, v74, v75
	v_add_f32_e32 v74, v77, v74
	v_add_f32_e32 v74, v76, v74
	v_add_f32_e32 v74, v74, v86
	s_cbranch_execnz .LBB0_847
.LBB0_849:
	v_mov_b32_e32 v74, v86
	global_store_dwordx4 v[82:83], v[70:73], off offset:512 sc1
	global_store_dwordx4 v[82:83], v[66:69], off offset:528 sc1
	s_and_b64 vcc, exec, s[44:45]
	s_cbranch_vccnz .LBB0_853

; __device__ __forceinline__ unsigned cvt_pk_bf16(float lo, float hi) { unsigned r; asm volatile("v_cvt_pk_bf16_f32 %0, %1, %2" : "=v"(r) : "v"(lo), "v"(hi)); return r; }
; __device__ __forceinline__ float bf_lo(unsigned w) { return __uint_as_float(w << 16); }
; __device__ __forceinline__ float bf_hi(unsigned w) { return __uint_as_float(w & 0xffff0000u); }
;     __device__ __forceinline__ void operator()(const f32x4 (&acc)[2][2][4][2], const Unit& u, int wr, int wc, int fr, int fq) const {
;     ...
;             for (int m = 0; m < 4; ++m)
; #pragma unroll
;                 for (int bj = 0; bj < 2; ++bj) xw[m][bj] = *(const u32x4*)(XB + (size_t)(row0 + ai * HALF + m * 16) * D_MODEL + col0 + bj * HALF);
; #pragma unroll
;             for (int m = 0; m < 4; ++m) { const int row = row0 + ai * HALF + m * 16; float ss = 0.f;
; #pragma unroll
;                 for (int bj = 0; bj < 2; ++bj) { const size_t o = (size_t)row * D_MODEL + col0 + bj * HALF; const u32x4 t = xw[m][bj];
;                     f32x4 v0, v1; v0[0] = bf_lo(t.x); v0[1] = bf_hi(t.x); v0[2] = bf_lo(t.y); v0[3] = bf_hi(t.y); v1[0] = bf_lo(t.z); v1[1] = bf_hi(t.z); v1[2] = bf_lo(t.w); v1[3] = bf_hi(t.w);
;                     v0 = v0 + acc[ai][bj][m][0]; v1 = v1 + acc[ai][bj][m][1];
;                     if (aux) { u32x4 w; w.x = cvt_pk_bf16(v0[0], v0[1]); w.y = cvt_pk_bf16(v0[2], v0[3]); w.z = cvt_pk_bf16(v1[0], v1[1]); w.w = cvt_pk_bf16(v1[2], v1[3]);
;                         *(u32x4*)(XB + o) = w;
;                         ss += (v0[0] * v0[0] + v0[1] * v0[1]) + (v0[2] * v0[2] + v0[3] * v0[3]) + (v1[0] * v1[0] + v1[1] * v1[1]) + (v1[2] * v1[2] + v1[3] * v1[3]); }
;                     else { *(f32x4*)(Xout + o) = v0; *(f32x4*)(Xout + o + 4) = v1; } }
.LBB0_853:
	v_add_u32_e32 v100, 0x80, v186
	v_ashrrev_i32_e32 v101, 31, v100
	s_waitcnt lgkmcnt(0)
	v_lshlrev_b64 v[66:67], 12, v[100:101]
	v_add_u32_e32 v98, 0x90, v186
	v_lshl_add_u64 v[66:67], v[184:185], 0, v[66:67]
	v_ashrrev_i32_e32 v99, 31, v98
	global_load_dwordx4 v[102:105], v[66:67], off
	global_load_dwordx4 v[90:93], v[66:67], off offset:256
	v_lshlrev_b64 v[66:67], 12, v[98:99]
	v_add_u32_e32 v96, 0xa0, v186
	v_lshl_add_u64 v[66:67], v[184:185], 0, v[66:67]
	v_ashrrev_i32_e32 v97, 31, v96
	global_load_dwordx4 v[86:89], v[66:67], off
	global_load_dwordx4 v[82:85], v[66:67], off offset:256
	v_lshlrev_b64 v[66:67], 12, v[96:97]
	v_add_u32_e32 v94, 0xb0, v186
	v_lshl_add_u64 v[66:67], v[184:185], 0, v[66:67]
	v_ashrrev_i32_e32 v95, 31, v94
	global_load_dwordx4 v[78:81], v[66:67], off
	global_load_dwordx4 v[74:77], v[66:67], off offset:256
	v_lshlrev_b64 v[66:67], 12, v[94:95]
	v_lshl_add_u64 v[66:67], v[184:185], 0, v[66:67]
	global_load_dwordx4 v[70:73], v[66:67], off
	s_nop 0
	global_load_dwordx4 v[66:69], v[66:67], off offset:256
	s_and_b64 vcc, exec, s[44:45]
	v_lshlrev_b64 v[100:101], 11, v[100:101]
	s_mov_b64 s[24:25], -1
	s_waitcnt vmcnt(7)
	v_lshlrev_b32_e32 v106, 16, v102
	v_and_b32_e32 v107, 0xffff0000, v102
	v_lshlrev_b32_e32 v102, 16, v103
	v_and_b32_e32 v103, 0xffff0000, v103
	v_lshlrev_b32_e32 v108, 16, v104
	v_and_b32_e32 v109, 0xffff0000, v104
	v_lshlrev_b32_e32 v104, 16, v105
	v_and_b32_e32 v105, 0xffff0000, v105
	v_pk_add_f32 v[64:65], v[64:65], v[102:103]
	v_pk_add_f32 v[62:63], v[62:63], v[106:107]
	v_pk_add_f32 v[60:61], v[60:61], v[104:105]
	v_pk_add_f32 v[58:59], v[58:59], v[108:109]
	s_cbranch_vccnz .LBB0_855
	v_cvt_pk_bf16_f32 v102, v62, v63
	v_cvt_pk_bf16_f32 v103, v64, v65
	v_cvt_pk_bf16_f32 v104, v58, v59
	v_cvt_pk_bf16_f32 v105, v60, v61
	v_lshl_add_u64 v[106:107], v[100:101], 1, v[184:185]
	global_store_dwordx4 v[106:107], v[102:105], off sc1
	s_mov_b64 s[24:25], 0
	s_nop 0
	v_pk_mul_f32 v[102:103], v[64:65], v[64:65]
	v_pk_mul_f32 v[104:105], v[62:63], v[62:63]
	s_nop 0
	v_pk_mov_b32 v[106:107], v[104:105], v[102:103] op_sel:[1,0]
	v_mov_b32_e32 v105, v103
	v_pk_add_f32 v[102:103], v[106:107], v[104:105]
	v_pk_mul_f32 v[104:105], v[60:61], v[60:61]
	v_pk_mul_f32 v[106:107], v[58:59], v[58:59]
	v_mov_b32_e32 v108, v104
	v_mov_b32_e32 v109, v106
	v_mov_b32_e32 v106, v105
	v_pk_add_f32 v[104:105], v[108:109], v[106:107]
	v_add_f32_e32 v102, v102, v103
	v_add_f32_e32 v102, v105, v102
	v_add_f32_e32 v104, v104, v102
.LBB0_855:
	v_lshl_add_u64 v[102:103], v[100:101], 0, v[182:183]
	s_andn2_b64 vcc, exec, s[24:25]
	v_lshl_add_u64 v[100:101], v[102:103], 2, s[90:91]
	s_cbranch_vccnz .LBB0_857
	v_mov_b32_e32 v104, 0
	global_store_dwordx4 v[100:101], v[62:65], off sc1
	global_store_dwordx4 v[100:101], v[58:61], off offset:16 sc1

; __device__ __forceinline__ unsigned cvt_pk_bf16(float lo, float hi) { unsigned r; asm volatile("v_cvt_pk_bf16_f32 %0, %1, %2" : "=v"(r) : "v"(lo), "v"(hi)); return r; }
; __device__ __forceinline__ float bf_lo(unsigned w) { return __uint_as_float(w << 16); }
; __device__ __forceinline__ float bf_hi(unsigned w) { return __uint_as_float(w & 0xffff0000u); }
;     __device__ __forceinline__ void operator()(const f32x4 (&acc)[2][2][4][2], const Unit& u, int wr, int wc, int fr, int fq) const {
;     ...
;             for (int m = 0; m < 4; ++m) { const int row = row0 + ai * HALF + m * 16; float ss = 0.f;
; #pragma unroll
;                 for (int bj = 0; bj < 2; ++bj) { const size_t o = (size_t)row * D_MODEL + col0 + bj * HALF; const u32x4 t = xw[m][bj];
;                     f32x4 v0, v1; v0[0] = bf_lo(t.x); v0[1] = bf_hi(t.x); v0[2] = bf_lo(t.y); v0[3] = bf_hi(t.y); v1[0] = bf_lo(t.z); v1[1] = bf_hi(t.z); v1[2] = bf_lo(t.w); v1[3] = bf_hi(t.w);
;                     v0 = v0 + acc[ai][bj][m][0]; v1 = v1 + acc[ai][bj][m][1];
;                     if (aux) { u32x4 w; w.x = cvt_pk_bf16(v0[0], v0[1]); w.y = cvt_pk_bf16(v0[2], v0[3]); w.z = cvt_pk_bf16(v1[0], v1[1]); w.w = cvt_pk_bf16(v1[2], v1[3]);
;                         *(u32x4*)(XB + o) = w;
;                         ss += (v0[0] * v0[0] + v0[1] * v0[1]) + (v0[2] * v0[2] + v0[3] * v0[3]) + (v1[0] * v1[0] + v1[1] * v1[1]) + (v1[2] * v1[2] + v1[3] * v1[3]); }
;                     else { *(f32x4*)(Xout + o) = v0; *(f32x4*)(Xout + o + 4) = v1; } }
.LBB0_860:
	v_lshlrev_b64 v[62:63], 1, v[102:103]
	v_or_b32_e32 v62, 0x100, v62
	v_cvt_pk_bf16_f32 v58, v54, v55
	v_cvt_pk_bf16_f32 v59, v56, v57
	v_cvt_pk_bf16_f32 v60, v50, v51
	v_cvt_pk_bf16_f32 v61, v52, v53
	v_lshl_add_u64 v[62:63], s[56:57], 0, v[62:63]
	global_store_dwordx4 v[62:63], v[58:61], off sc1
	s_nop 1
	v_pk_mul_f32 v[58:59], v[56:57], v[56:57]
	v_pk_mul_f32 v[60:61], v[54:55], v[54:55]
	s_nop 0
	v_pk_mov_b32 v[62:63], v[60:61], v[58:59] op_sel:[1,0]
	v_mov_b32_e32 v61, v59
	v_pk_add_f32 v[58:59], v[62:63], v[60:61]
	v_pk_mul_f32 v[60:61], v[52:53], v[52:53]
	v_pk_mul_f32 v[62:63], v[50:51], v[50:51]
	v_mov_b32_e32 v64, v60
	v_mov_b32_e32 v65, v62
	v_mov_b32_e32 v62, v61
	v_pk_add_f32 v[60:61], v[64:65], v[62:63]
	v_add_f32_e32 v58, v58, v59
	v_add_f32_e32 v58, v61, v58
	v_add_f32_e32 v58, v60, v58
	v_add_f32_e32 v58, v58, v104
	s_cbranch_execnz .LBB0_859
.LBB0_861:
	v_mov_b32_e32 v58, v104
	global_store_dwordx4 v[100:101], v[54:57], off offset:512 sc1
	global_store_dwordx4 v[100:101], v[50:53], off offset:528 sc1
	s_and_b64 vcc, exec, s[44:45]
	s_cbranch_vccnz .LBB0_865

; __device__ __forceinline__ unsigned cvt_pk_bf16(float lo, float hi) { unsigned r; asm volatile("v_cvt_pk_bf16_f32 %0, %1, %2" : "=v"(r) : "v"(lo), "v"(hi)); return r; }
; __device__ __forceinline__ float bf_lo(unsigned w) { return __uint_as_float(w << 16); }
; __device__ __forceinline__ float bf_hi(unsigned w) { return __uint_as_float(w & 0xffff0000u); }
;     __device__ __forceinline__ void operator()(const f32x4 (&acc)[2][2][4][2], const Unit& u, int wr, int wc, int fr, int fq) const {
;     ...
;             for (int m = 0; m < 4; ++m) { const int row = row0 + ai * HALF + m * 16; float ss = 0.f;
; #pragma unroll
;                 for (int bj = 0; bj < 2; ++bj) { const size_t o = (size_t)row * D_MODEL + col0 + bj * HALF; const u32x4 t = xw[m][bj];
;                     f32x4 v0, v1; v0[0] = bf_lo(t.x); v0[1] = bf_hi(t.x); v0[2] = bf_lo(t.y); v0[3] = bf_hi(t.y); v1[0] = bf_lo(t.z); v1[1] = bf_hi(t.z); v1[2] = bf_lo(t.w); v1[3] = bf_hi(t.w);
;                     v0 = v0 + acc[ai][bj][m][0]; v1 = v1 + acc[ai][bj][m][1];
;                     if (aux) { u32x4 w; w.x = cvt_pk_bf16(v0[0], v0[1]); w.y = cvt_pk_bf16(v0[2], v0[3]); w.z = cvt_pk_bf16(v1[0], v1[1]); w.w = cvt_pk_bf16(v1[2], v1[3]);
;                         *(u32x4*)(XB + o) = w;
;                         ss += (v0[0] * v0[0] + v0[1] * v0[1]) + (v0[2] * v0[2] + v0[3] * v0[3]) + (v1[0] * v1[0] + v1[1] * v1[1]) + (v1[2] * v1[2] + v1[3] * v1[3]); }
;                     else { *(f32x4*)(Xout + o) = v0; *(f32x4*)(Xout + o + 4) = v1; } }
.LBB0_865:
	s_waitcnt vmcnt(5)
	v_lshlrev_b32_e32 v52, 16, v86
	v_and_b32_e32 v53, 0xffff0000, v86
	v_lshlrev_b32_e32 v54, 16, v87
	v_and_b32_e32 v55, 0xffff0000, v87
	v_lshlrev_b32_e32 v56, 16, v88
	v_and_b32_e32 v57, 0xffff0000, v88
	v_lshlrev_b32_e32 v58, 16, v89
	v_and_b32_e32 v59, 0xffff0000, v89
	s_waitcnt lgkmcnt(0)
	v_lshlrev_b64 v[50:51], 11, v[98:99]
	v_pk_add_f32 v[48:49], v[48:49], v[54:55]
	v_pk_add_f32 v[46:47], v[46:47], v[52:53]
	v_pk_add_f32 v[44:45], v[44:45], v[58:59]
	v_pk_add_f32 v[42:43], v[42:43], v[56:57]
	s_and_b64 vcc, exec, s[44:45]
	s_mov_b64 s[24:25], -1
	s_cbranch_vccnz .LBB0_867
	v_cvt_pk_bf16_f32 v52, v46, v47
	v_cvt_pk_bf16_f32 v53, v48, v49
	v_cvt_pk_bf16_f32 v54, v42, v43
	v_cvt_pk_bf16_f32 v55, v44, v45
	v_lshl_add_u64 v[56:57], v[50:51], 1, v[184:185]
	global_store_dwordx4 v[56:57], v[52:55], off sc1
	s_mov_b64 s[24:25], 0
	s_nop 0
	v_pk_mul_f32 v[52:53], v[48:49], v[48:49]
	v_pk_mul_f32 v[54:55], v[46:47], v[46:47]
	s_nop 0
	v_pk_mov_b32 v[56:57], v[54:55], v[52:53] op_sel:[1,0]
	v_mov_b32_e32 v55, v53
	v_pk_add_f32 v[52:53], v[56:57], v[54:55]
	v_pk_mul_f32 v[54:55], v[44:45], v[44:45]
	v_pk_mul_f32 v[56:57], v[42:43], v[42:43]
	v_mov_b32_e32 v58, v54
	v_mov_b32_e32 v59, v56
	v_mov_b32_e32 v56, v55
	v_pk_add_f32 v[54:55], v[58:59], v[56:57]
	v_add_f32_e32 v52, v52, v53
	v_add_f32_e32 v52, v55, v52
	v_add_f32_e32 v54, v54, v52
.LBB0_867:
	v_lshl_add_u64 v[52:53], v[50:51], 0, v[182:183]
	s_andn2_b64 vcc, exec, s[24:25]
	v_lshl_add_u64 v[50:51], v[52:53], 2, s[90:91]
	s_cbranch_vccnz .LBB0_869
	v_mov_b32_e32 v54, 0
	global_store_dwordx4 v[50:51], v[46:49], off sc1
	global_store_dwordx4 v[50:51], v[42:45], off offset:16 sc1

; __device__ __forceinline__ unsigned cvt_pk_bf16(float lo, float hi) { unsigned r; asm volatile("v_cvt_pk_bf16_f32 %0, %1, %2" : "=v"(r) : "v"(lo), "v"(hi)); return r; }
; __device__ __forceinline__ float bf_lo(unsigned w) { return __uint_as_float(w << 16); }
; __device__ __forceinline__ float bf_hi(unsigned w) { return __uint_as_float(w & 0xffff0000u); }
;     __device__ __forceinline__ void operator()(const f32x4 (&acc)[2][2][4][2], const Unit& u, int wr, int wc, int fr, int fq) const {
;     ...
;             for (int m = 0; m < 4; ++m) { const int row = row0 + ai * HALF + m * 16; float ss = 0.f;
; #pragma unroll
;                 for (int bj = 0; bj < 2; ++bj) { const size_t o = (size_t)row * D_MODEL + col0 + bj * HALF; const u32x4 t = xw[m][bj];
;                     f32x4 v0, v1; v0[0] = bf_lo(t.x); v0[1] = bf_hi(t.x); v0[2] = bf_lo(t.y); v0[3] = bf_hi(t.y); v1[0] = bf_lo(t.z); v1[1] = bf_hi(t.z); v1[2] = bf_lo(t.w); v1[3] = bf_hi(t.w);
;                     v0 = v0 + acc[ai][bj][m][0]; v1 = v1 + acc[ai][bj][m][1];
;                     if (aux) { u32x4 w; w.x = cvt_pk_bf16(v0[0], v0[1]); w.y = cvt_pk_bf16(v0[2], v0[3]); w.z = cvt_pk_bf16(v1[0], v1[1]); w.w = cvt_pk_bf16(v1[2], v1[3]);
;                         *(u32x4*)(XB + o) = w;
;                         ss += (v0[0] * v0[0] + v0[1] * v0[1]) + (v0[2] * v0[2] + v0[3] * v0[3]) + (v1[0] * v1[0] + v1[1] * v1[1]) + (v1[2] * v1[2] + v1[3] * v1[3]); }
;                     else { *(f32x4*)(Xout + o) = v0; *(f32x4*)(Xout + o + 4) = v1; } }
.LBB0_872:
	v_lshlrev_b64 v[46:47], 1, v[52:53]
	v_or_b32_e32 v46, 0x100, v46
	v_cvt_pk_bf16_f32 v42, v38, v39
	v_cvt_pk_bf16_f32 v43, v40, v41
	v_cvt_pk_bf16_f32 v44, v34, v35
	v_cvt_pk_bf16_f32 v45, v36, v37
	v_lshl_add_u64 v[46:47], s[56:57], 0, v[46:47]
	global_store_dwordx4 v[46:47], v[42:45], off sc1
	s_nop 1
	v_pk_mul_f32 v[42:43], v[40:41], v[40:41]
	v_pk_mul_f32 v[44:45], v[38:39], v[38:39]
	s_nop 0
	v_pk_mov_b32 v[46:47], v[44:45], v[42:43] op_sel:[1,0]
	v_mov_b32_e32 v45, v43
	v_pk_add_f32 v[42:43], v[46:47], v[44:45]
	v_pk_mul_f32 v[44:45], v[36:37], v[36:37]
	v_pk_mul_f32 v[46:47], v[34:35], v[34:35]
	v_mov_b32_e32 v48, v44
	v_mov_b32_e32 v49, v46
	v_mov_b32_e32 v46, v45
	v_pk_add_f32 v[44:45], v[48:49], v[46:47]
	v_add_f32_e32 v42, v42, v43
	v_add_f32_e32 v42, v45, v42
	v_add_f32_e32 v42, v44, v42
	v_add_f32_e32 v42, v42, v54
	s_cbranch_execnz .LBB0_871
.LBB0_873:
	v_mov_b32_e32 v42, v54
	global_store_dwordx4 v[50:51], v[38:41], off offset:512 sc1
	global_store_dwordx4 v[50:51], v[34:37], off offset:528 sc1
	s_and_b64 vcc, exec, s[44:45]
	s_cbranch_vccnz .LBB0_877

; __device__ __forceinline__ unsigned cvt_pk_bf16(float lo, float hi) { unsigned r; asm volatile("v_cvt_pk_bf16_f32 %0, %1, %2" : "=v"(r) : "v"(lo), "v"(hi)); return r; }
; __device__ __forceinline__ float bf_lo(unsigned w) { return __uint_as_float(w << 16); }
; __device__ __forceinline__ float bf_hi(unsigned w) { return __uint_as_float(w & 0xffff0000u); }
;     __device__ __forceinline__ void operator()(const f32x4 (&acc)[2][2][4][2], const Unit& u, int wr, int wc, int fr, int fq) const {
;     ...
;             for (int m = 0; m < 4; ++m) { const int row = row0 + ai * HALF + m * 16; float ss = 0.f;
; #pragma unroll
;                 for (int bj = 0; bj < 2; ++bj) { const size_t o = (size_t)row * D_MODEL + col0 + bj * HALF; const u32x4 t = xw[m][bj];
;                     f32x4 v0, v1; v0[0] = bf_lo(t.x); v0[1] = bf_hi(t.x); v0[2] = bf_lo(t.y); v0[3] = bf_hi(t.y); v1[0] = bf_lo(t.z); v1[1] = bf_hi(t.z); v1[2] = bf_lo(t.w); v1[3] = bf_hi(t.w);
;                     v0 = v0 + acc[ai][bj][m][0]; v1 = v1 + acc[ai][bj][m][1];
;                     if (aux) { u32x4 w; w.x = cvt_pk_bf16(v0[0], v0[1]); w.y = cvt_pk_bf16(v0[2], v0[3]); w.z = cvt_pk_bf16(v1[0], v1[1]); w.w = cvt_pk_bf16(v1[2], v1[3]);
;                         *(u32x4*)(XB + o) = w;
;                         ss += (v0[0] * v0[0] + v0[1] * v0[1]) + (v0[2] * v0[2] + v0[3] * v0[3]) + (v1[0] * v1[0] + v1[1] * v1[1]) + (v1[2] * v1[2] + v1[3] * v1[3]); }
;                     else { *(f32x4*)(Xout + o) = v0; *(f32x4*)(Xout + o + 4) = v1; } }
.LBB0_877:
	s_waitcnt vmcnt(3)
	v_lshlrev_b32_e32 v36, 16, v78
	v_and_b32_e32 v37, 0xffff0000, v78
	v_lshlrev_b32_e32 v38, 16, v79
	v_and_b32_e32 v39, 0xffff0000, v79
	v_lshlrev_b32_e32 v40, 16, v80
	v_and_b32_e32 v41, 0xffff0000, v80
	v_lshlrev_b32_e32 v42, 16, v81
	v_and_b32_e32 v43, 0xffff0000, v81
	s_waitcnt lgkmcnt(0)
	v_lshlrev_b64 v[34:35], 11, v[96:97]
	v_pk_add_f32 v[32:33], v[32:33], v[38:39]
	v_pk_add_f32 v[30:31], v[30:31], v[36:37]
	v_pk_add_f32 v[28:29], v[28:29], v[42:43]
	v_pk_add_f32 v[26:27], v[26:27], v[40:41]
	s_and_b64 vcc, exec, s[44:45]
	s_mov_b64 s[24:25], -1
	s_cbranch_vccnz .LBB0_879
	v_cvt_pk_bf16_f32 v36, v30, v31
	v_cvt_pk_bf16_f32 v37, v32, v33
	v_cvt_pk_bf16_f32 v38, v26, v27
	v_cvt_pk_bf16_f32 v39, v28, v29
	v_lshl_add_u64 v[40:41], v[34:35], 1, v[184:185]
	global_store_dwordx4 v[40:41], v[36:39], off sc1
	s_mov_b64 s[24:25], 0
	s_nop 0
	v_pk_mul_f32 v[36:37], v[32:33], v[32:33]
	v_pk_mul_f32 v[38:39], v[30:31], v[30:31]
	s_nop 0
	v_pk_mov_b32 v[40:41], v[38:39], v[36:37] op_sel:[1,0]
	v_mov_b32_e32 v39, v37
	v_pk_add_f32 v[36:37], v[40:41], v[38:39]
	v_pk_mul_f32 v[38:39], v[28:29], v[28:29]
	v_pk_mul_f32 v[40:41], v[26:27], v[26:27]
	v_mov_b32_e32 v42, v38
	v_mov_b32_e32 v43, v40
	v_mov_b32_e32 v40, v39
	v_pk_add_f32 v[38:39], v[42:43], v[40:41]
	v_add_f32_e32 v36, v36, v37
	v_add_f32_e32 v36, v39, v36
	v_add_f32_e32 v38, v38, v36
.LBB0_879:
	v_lshl_add_u64 v[36:37], v[34:35], 0, v[182:183]
	s_andn2_b64 vcc, exec, s[24:25]
	v_lshl_add_u64 v[34:35], v[36:37], 2, s[90:91]
	s_cbranch_vccnz .LBB0_881
	v_mov_b32_e32 v38, 0
	global_store_dwordx4 v[34:35], v[30:33], off sc1
	global_store_dwordx4 v[34:35], v[26:29], off offset:16 sc1

; __device__ __forceinline__ unsigned cvt_pk_bf16(float lo, float hi) { unsigned r; asm volatile("v_cvt_pk_bf16_f32 %0, %1, %2" : "=v"(r) : "v"(lo), "v"(hi)); return r; }
; __device__ __forceinline__ float bf_lo(unsigned w) { return __uint_as_float(w << 16); }
; __device__ __forceinline__ float bf_hi(unsigned w) { return __uint_as_float(w & 0xffff0000u); }
;     __device__ __forceinline__ void operator()(const f32x4 (&acc)[2][2][4][2], const Unit& u, int wr, int wc, int fr, int fq) const {
;     ...
;             for (int m = 0; m < 4; ++m) { const int row = row0 + ai * HALF + m * 16; float ss = 0.f;
; #pragma unroll
;                 for (int bj = 0; bj < 2; ++bj) { const size_t o = (size_t)row * D_MODEL + col0 + bj * HALF; const u32x4 t = xw[m][bj];
;                     f32x4 v0, v1; v0[0] = bf_lo(t.x); v0[1] = bf_hi(t.x); v0[2] = bf_lo(t.y); v0[3] = bf_hi(t.y); v1[0] = bf_lo(t.z); v1[1] = bf_hi(t.z); v1[2] = bf_lo(t.w); v1[3] = bf_hi(t.w);
;                     v0 = v0 + acc[ai][bj][m][0]; v1 = v1 + acc[ai][bj][m][1];
;                     if (aux) { u32x4 w; w.x = cvt_pk_bf16(v0[0], v0[1]); w.y = cvt_pk_bf16(v0[2], v0[3]); w.z = cvt_pk_bf16(v1[0], v1[1]); w.w = cvt_pk_bf16(v1[2], v1[3]);
;                         *(u32x4*)(XB + o) = w;
;                         ss += (v0[0] * v0[0] + v0[1] * v0[1]) + (v0[2] * v0[2] + v0[3] * v0[3]) + (v1[0] * v1[0] + v1[1] * v1[1]) + (v1[2] * v1[2] + v1[3] * v1[3]); }
;                     else { *(f32x4*)(Xout + o) = v0; *(f32x4*)(Xout + o + 4) = v1; } }
.LBB0_884:
	v_lshlrev_b64 v[30:31], 1, v[36:37]
	v_or_b32_e32 v30, 0x100, v30
	v_cvt_pk_bf16_f32 v26, v22, v23
	v_cvt_pk_bf16_f32 v27, v24, v25
	v_cvt_pk_bf16_f32 v28, v18, v19
	v_cvt_pk_bf16_f32 v29, v20, v21
	v_lshl_add_u64 v[30:31], s[56:57], 0, v[30:31]
	global_store_dwordx4 v[30:31], v[26:29], off sc1
	s_nop 1
	v_pk_mul_f32 v[26:27], v[24:25], v[24:25]
	v_pk_mul_f32 v[28:29], v[22:23], v[22:23]
	s_nop 0
	v_pk_mov_b32 v[30:31], v[28:29], v[26:27] op_sel:[1,0]
	v_mov_b32_e32 v29, v27
	v_pk_add_f32 v[26:27], v[30:31], v[28:29]
	v_pk_mul_f32 v[28:29], v[20:21], v[20:21]
	v_pk_mul_f32 v[30:31], v[18:19], v[18:19]
	v_mov_b32_e32 v32, v28
	v_mov_b32_e32 v33, v30
	v_mov_b32_e32 v30, v29
	v_pk_add_f32 v[28:29], v[32:33], v[30:31]
	v_add_f32_e32 v26, v26, v27
	v_add_f32_e32 v26, v29, v26
	v_add_f32_e32 v26, v28, v26
	v_add_f32_e32 v26, v26, v38
	s_cbranch_execnz .LBB0_883
.LBB0_885:
	v_mov_b32_e32 v26, v38
	global_store_dwordx4 v[34:35], v[22:25], off offset:512 sc1
	global_store_dwordx4 v[34:35], v[18:21], off offset:528 sc1
	s_and_b64 vcc, exec, s[44:45]
	s_cbranch_vccnz .LBB0_889

; __device__ __forceinline__ unsigned cvt_pk_bf16(float lo, float hi) { unsigned r; asm volatile("v_cvt_pk_bf16_f32 %0, %1, %2" : "=v"(r) : "v"(lo), "v"(hi)); return r; }
; __device__ __forceinline__ float bf_lo(unsigned w) { return __uint_as_float(w << 16); }
; __device__ __forceinline__ float bf_hi(unsigned w) { return __uint_as_float(w & 0xffff0000u); }
;     __device__ __forceinline__ void operator()(const f32x4 (&acc)[2][2][4][2], const Unit& u, int wr, int wc, int fr, int fq) const {
;     ...
;             for (int m = 0; m < 4; ++m) { const int row = row0 + ai * HALF + m * 16; float ss = 0.f;
; #pragma unroll
;                 for (int bj = 0; bj < 2; ++bj) { const size_t o = (size_t)row * D_MODEL + col0 + bj * HALF; const u32x4 t = xw[m][bj];
;                     f32x4 v0, v1; v0[0] = bf_lo(t.x); v0[1] = bf_hi(t.x); v0[2] = bf_lo(t.y); v0[3] = bf_hi(t.y); v1[0] = bf_lo(t.z); v1[1] = bf_hi(t.z); v1[2] = bf_lo(t.w); v1[3] = bf_hi(t.w);
;                     v0 = v0 + acc[ai][bj][m][0]; v1 = v1 + acc[ai][bj][m][1];
;                     if (aux) { u32x4 w; w.x = cvt_pk_bf16(v0[0], v0[1]); w.y = cvt_pk_bf16(v0[2], v0[3]); w.z = cvt_pk_bf16(v1[0], v1[1]); w.w = cvt_pk_bf16(v1[2], v1[3]);
;                         *(u32x4*)(XB + o) = w;
;                         ss += (v0[0] * v0[0] + v0[1] * v0[1]) + (v0[2] * v0[2] + v0[3] * v0[3]) + (v1[0] * v1[0] + v1[1] * v1[1]) + (v1[2] * v1[2] + v1[3] * v1[3]); }
;                     else { *(f32x4*)(Xout + o) = v0; *(f32x4*)(Xout + o + 4) = v1; } }
.LBB0_889:
	s_waitcnt vmcnt(1)
	v_lshlrev_b32_e32 v20, 16, v70
	v_and_b32_e32 v21, 0xffff0000, v70
	v_lshlrev_b32_e32 v22, 16, v71
	v_and_b32_e32 v23, 0xffff0000, v71
	v_lshlrev_b32_e32 v24, 16, v72
	v_and_b32_e32 v25, 0xffff0000, v72
	v_lshlrev_b32_e32 v26, 16, v73
	v_and_b32_e32 v27, 0xffff0000, v73
	s_waitcnt lgkmcnt(0)
	v_lshlrev_b64 v[18:19], 11, v[94:95]
	v_pk_add_f32 v[16:17], v[16:17], v[22:23]
	v_pk_add_f32 v[14:15], v[14:15], v[20:21]
	v_pk_add_f32 v[12:13], v[12:13], v[26:27]
	v_pk_add_f32 v[10:11], v[10:11], v[24:25]
	s_and_b64 vcc, exec, s[44:45]
	s_mov_b64 s[24:25], -1
	s_cbranch_vccnz .LBB0_891
	v_cvt_pk_bf16_f32 v20, v14, v15
	v_cvt_pk_bf16_f32 v21, v16, v17
	v_cvt_pk_bf16_f32 v22, v10, v11
	v_cvt_pk_bf16_f32 v23, v12, v13
	v_lshl_add_u64 v[24:25], v[18:19], 1, v[184:185]
	global_store_dwordx4 v[24:25], v[20:23], off sc1
	s_mov_b64 s[24:25], 0
	s_nop 0
	v_pk_mul_f32 v[20:21], v[16:17], v[16:17]
	v_pk_mul_f32 v[22:23], v[14:15], v[14:15]
	s_nop 0
	v_pk_mov_b32 v[24:25], v[22:23], v[20:21] op_sel:[1,0]
	v_mov_b32_e32 v23, v21
	v_pk_add_f32 v[20:21], v[24:25], v[22:23]
	v_pk_mul_f32 v[22:23], v[12:13], v[12:13]
	v_pk_mul_f32 v[24:25], v[10:11], v[10:11]
	v_mov_b32_e32 v26, v22
	v_mov_b32_e32 v27, v24
	v_mov_b32_e32 v24, v23
	v_pk_add_f32 v[22:23], v[26:27], v[24:25]
	v_add_f32_e32 v20, v20, v21
	v_add_f32_e32 v20, v23, v20
	v_add_f32_e32 v22, v22, v20
.LBB0_891:
	v_lshl_add_u64 v[20:21], v[18:19], 0, v[182:183]
	s_andn2_b64 vcc, exec, s[24:25]
	v_lshl_add_u64 v[18:19], v[20:21], 2, s[90:91]
	s_cbranch_vccnz .LBB0_893
	v_mov_b32_e32 v22, 0
	global_store_dwordx4 v[18:19], v[14:17], off sc1
	global_store_dwordx4 v[18:19], v[10:13], off offset:16 sc1

; __device__ __forceinline__ unsigned cvt_pk_bf16(float lo, float hi) { unsigned r; asm volatile("v_cvt_pk_bf16_f32 %0, %1, %2" : "=v"(r) : "v"(lo), "v"(hi)); return r; }
; __device__ __forceinline__ float bf_lo(unsigned w) { return __uint_as_float(w << 16); }
; __device__ __forceinline__ float bf_hi(unsigned w) { return __uint_as_float(w & 0xffff0000u); }
;     __device__ __forceinline__ void operator()(const f32x4 (&acc)[2][2][4][2], const Unit& u, int wr, int wc, int fr, int fq) const {
;     ...
;                 for (int bj = 0; bj < 2; ++bj) { const size_t o = (size_t)row * D_MODEL + col0 + bj * HALF; const u32x4 t = xw[m][bj];
;                     f32x4 v0, v1; v0[0] = bf_lo(t.x); v0[1] = bf_hi(t.x); v0[2] = bf_lo(t.y); v0[3] = bf_hi(t.y); v1[0] = bf_lo(t.z); v1[1] = bf_hi(t.z); v1[2] = bf_lo(t.w); v1[3] = bf_hi(t.w);
;                     v0 = v0 + acc[ai][bj][m][0]; v1 = v1 + acc[ai][bj][m][1];
;                     if (aux) { u32x4 w; w.x = cvt_pk_bf16(v0[0], v0[1]); w.y = cvt_pk_bf16(v0[2], v0[3]); w.z = cvt_pk_bf16(v1[0], v1[1]); w.w = cvt_pk_bf16(v1[2], v1[3]);
;                         *(u32x4*)(XB + o) = w;
;                         ss += (v0[0] * v0[0] + v0[1] * v0[1]) + (v0[2] * v0[2] + v0[3] * v0[3]) + (v1[0] * v1[0] + v1[1] * v1[1]) + (v1[2] * v1[2] + v1[3] * v1[3]); }
;                     else { *(f32x4*)(Xout + o) = v0; *(f32x4*)(Xout + o + 4) = v1; } }
;                 if (aux) { ss += __shfl_xor(ss, 16); ss += __shfl_xor(ss, 32); if (fq == 0) red[(ai * HALF + wr * 64 + m * 16 + fr) * 4 + wc] = ss; } } }
.LBB0_897:
	v_lshlrev_b64 v[14:15], 1, v[20:21]
	v_or_b32_e32 v14, 0x100, v14
	v_cvt_pk_bf16_f32 v10, v6, v7
	v_cvt_pk_bf16_f32 v11, v8, v9
	v_cvt_pk_bf16_f32 v12, v2, v3
	v_cvt_pk_bf16_f32 v13, v4, v5
	v_lshl_add_u64 v[14:15], s[56:57], 0, v[14:15]
	global_store_dwordx4 v[14:15], v[10:13], off sc1
	s_nop 1
	v_pk_mul_f32 v[10:11], v[8:9], v[8:9]
	v_pk_mul_f32 v[12:13], v[6:7], v[6:7]
	s_nop 0
	v_pk_mov_b32 v[14:15], v[12:13], v[10:11] op_sel:[1,0]
	v_mov_b32_e32 v13, v11
	v_pk_add_f32 v[10:11], v[14:15], v[12:13]
	v_pk_mul_f32 v[12:13], v[4:5], v[4:5]
	v_pk_mul_f32 v[14:15], v[2:3], v[2:3]
	v_mov_b32_e32 v16, v12
	v_mov_b32_e32 v17, v14
	v_mov_b32_e32 v14, v13
	v_pk_add_f32 v[12:13], v[16:17], v[14:15]
	v_add_f32_e32 v10, v10, v11
	v_add_f32_e32 v10, v13, v10
	v_add_f32_e32 v10, v12, v10
	v_add_f32_e32 v10, v10, v22
	s_cbranch_execnz .LBB0_895
.LBB0_898:
	v_mov_b32_e32 v10, v22
	global_store_dwordx4 v[18:19], v[6:9], off offset:512 sc1
	global_store_dwordx4 v[18:19], v[2:5], off offset:528 sc1
	s_and_b64 vcc, exec, s[44:45]
	s_cbranch_vccnz .LBB0_896
